# stack12: stack11 + GEMM K-loops: one counted vmcnt(10) guard per reading phase instead of two vmcnt(6) per iteration (every DMA pair gets 5+ phases of latency cover)
# baseline (speedup 1.0000x reference)
.LBB0_287:
	v_readlane_b32 s16, v250, 58
	s_and_b32 s63, s3, 3
	s_add_i32 m0, s59, 0x18000
	v_lshl_add_u64 v[6:7], v[6:7], 0, s[24:25]
	s_lshl_b32 s86, s16, 6
	s_lshl_b32 s3, s57, 13
	s_lshl_b32 s10, s63, 12
	s_waitcnt vmcnt(4)
	s_barrier
	global_load_lds_dwordx4 v[6:7], off
	v_lshl_add_u64 v[4:5], v[4:5], 0, s[24:25]
	s_add_i32 m0, s59, 0x1a000
	s_add_i32 s64, s59, 0x8000
	s_add_i32 s65, s59, 0xa000
	global_load_lds_dwordx4 v[4:5], off
	v_lshl_add_u64 v[2:3], v[2:3], 0, s[24:25]
	s_mov_b32 m0, s64
	s_add_u32 s8, s38, 0x40080
	global_load_lds_dwordx4 v[2:3], off
	v_lshl_add_u64 v[0:1], v[0:1], 0, s[24:25]
	s_mov_b32 m0, s65
	s_addc_u32 s9, s39, 0
	global_load_lds_dwordx4 v[0:1], off
	s_add_i32 m0, s59, 0x1c000
	v_lshl_add_u64 v[0:1], s[8:9], 0, v[144:145]
	global_load_lds_dwordx4 v[0:1], off
	v_lshl_add_u64 v[0:1], s[8:9], 0, v[146:147]
	s_add_i32 m0, s59, 0x1e000
	s_ashr_i32 s66, s21, 31
	global_load_lds_dwordx4 v[0:1], off
	s_add_u32 s8, s96, 0x8200000
	s_addc_u32 s9, s97, 0
	s_add_u32 s67, s96, 0xe380000
	v_and_b32_e32 v238, 15, v8
	s_addc_u32 s68, s97, 0
	v_bfe_u32 v239, v8, 4, 2
	v_lshlrev_b32_e32 v0, 6, v238
	v_lshlrev_b32_e32 v1, 2, v8
	s_add_u32 s69, s96, 0x12480000
	v_lshl_or_b32 v0, v239, 4, v0
	v_and_b32_e32 v1, 32, v1
	s_addc_u32 s70, s97, 0
	v_bitop3_b32 v240, v0, s10, v1 bitop3:0xde
	s_add_u32 s10, s96, 0x14500000
	v_bitop3_b32 v2, v0, s3, v1 bitop3:0xde
	s_addc_u32 s11, s97, 0
	s_lshl_b32 s3, s16, 26
	s_waitcnt lgkmcnt(0)
	s_add_u32 s3, s26, s3
	s_addc_u32 s13, s27, 0
	s_add_u32 s12, s3, 0x8200000
	s_addc_u32 s13, s13, 0
	v_lshlrev_b32_e32 v0, 14, v9
	s_add_u32 s14, s96, 0x14708000
	v_and_b32_e32 v0, 0xffff8000, v0
	s_addc_u32 s15, s97, 0
	s_lshl_b32 s3, s16, 20
	v_lshl_add_u32 v0, v10, 11, v0
	v_and_b32_e32 v1, 1, v9
	v_readlane_b32 s17, v250, 59
	s_add_u32 s3, s26, s3
	v_lshl_or_b32 v0, v1, 6, v0
	s_addc_u32 s17, s27, 0
	v_lshl_add_u32 v148, v11, 1, v0
	v_lshlrev_b32_e32 v0, 14, v12
	s_add_u32 s16, s3, 0x187e0000
	v_and_b32_e32 v0, 0xffff8000, v0
	s_waitcnt vmcnt(0)
	s_addc_u32 s17, s17, 0
	v_lshl_add_u32 v0, v13, 11, v0
	v_and_b32_e32 v1, 1, v12
	s_add_u32 s71, s96, 0x4100000
	v_lshl_or_b32 v0, v1, 6, v0
	s_addc_u32 s72, s97, 0
	v_mov_b32_e32 v149, v177
	v_lshl_add_u32 v150, v14, 1, v0
	v_mov_b32_e32 v151, v177
	s_mov_b32 s73, 0
	v_add_u32_e32 v241, 0, v2
	s_lshl_b64 s[18:19], s[86:87], 2
	s_mov_b64 s[36:37], s[22:23]
	s_mov_b64 s[52:53], s[38:39]
	s_barrier
	s_branch .LBB0_289

.LBB0_296:
	s_add_u32 s38, s22, 0xfffc0080
	s_addc_u32 s39, s23, -1
	s_add_i32 s44, 0, 0x10000
	v_add_u32_e32 v140, s44, v240
	s_waitcnt lgkmcnt(0)
	ds_read_b128 v[128:131], v140
	ds_read_b128 v[132:135], v140 offset:1024
	ds_read_b128 v[136:139], v140 offset:2048
	ds_read_b128 v[140:143], v140 offset:3072
	s_cmp_eq_u32 s35, 12
	s_cselect_b32 s43, s37, s39
	s_cselect_b32 s42, s36, s38
	s_cselect_b32 s39, s53, s31
	s_cselect_b32 s38, s52, s3
	v_lshl_add_u64 v[198:199], s[22:23], 0, v[148:149]
	s_add_i32 m0, s59, 0xc000
	ds_read_b128 v[152:155], v241
	ds_read_b128 v[156:159], v241 offset:1024
	ds_read_b128 v[160:163], v241 offset:2048
	ds_read_b128 v[164:167], v241 offset:3072
	ds_read_b128 v[168:171], v241 offset:4096
	ds_read_b128 v[172:175], v241 offset:5120
	ds_read_b128 v[190:193], v241 offset:6144
	ds_read_b128 v[194:197], v241 offset:7168
	global_load_lds_dwordx4 v[198:199], off
	v_lshl_add_u64 v[198:199], s[22:23], 0, v[150:151]
	s_add_i32 m0, s59, 0xe000
	s_nop 0
	global_load_lds_dwordx4 v[198:199], off
	s_waitcnt lgkmcnt(8)
	s_waitcnt vmcnt(10)
	s_barrier
	s_waitcnt lgkmcnt(0)
	s_setprio 1
	s_waitcnt lgkmcnt(0)
	v_mfma_f32_16x16x32_bf16 v[124:127], v[128:131], v[152:155], v[124:127]
	v_mfma_f32_16x16x32_bf16 v[120:123], v[136:139], v[152:155], v[120:123]
	v_mfma_f32_16x16x32_bf16 v[108:111], v[128:131], v[160:163], v[108:111]
	v_mfma_f32_16x16x32_bf16 v[104:107], v[136:139], v[160:163], v[104:107]
	v_mfma_f32_16x16x32_bf16 v[92:95], v[128:131], v[168:171], v[92:95]
	v_mfma_f32_16x16x32_bf16 v[88:91], v[136:139], v[168:171], v[88:91]
	v_mfma_f32_16x16x32_bf16 v[76:79], v[128:131], v[190:193], v[76:79]
	v_mfma_f32_16x16x32_bf16 v[72:75], v[136:139], v[190:193], v[72:75]
	v_mfma_f32_16x16x32_bf16 v[124:127], v[132:135], v[156:159], v[124:127]
	v_mfma_f32_16x16x32_bf16 v[120:123], v[140:143], v[156:159], v[120:123]
	v_mfma_f32_16x16x32_bf16 v[108:111], v[132:135], v[164:167], v[108:111]
	v_mfma_f32_16x16x32_bf16 v[104:107], v[140:143], v[164:167], v[104:107]
	v_mfma_f32_16x16x32_bf16 v[92:95], v[132:135], v[172:175], v[92:95]
	v_mfma_f32_16x16x32_bf16 v[88:91], v[140:143], v[172:175], v[88:91]
	v_mfma_f32_16x16x32_bf16 v[76:79], v[132:135], v[194:197], v[76:79]
	v_mfma_f32_16x16x32_bf16 v[72:75], v[140:143], v[194:197], v[72:75]
	s_setprio 0
	s_barrier
	s_add_i32 s46, 0, 0x14000
	s_add_i32 s44, s44, s58
	v_add_u32_e32 v176, s46, v240
	v_lshl_add_u64 v[214:215], s[38:39], 0, v[144:145]
	s_mov_b32 m0, s44
	ds_read_b128 v[198:201], v176
	ds_read_b128 v[202:205], v176 offset:1024
	ds_read_b128 v[206:209], v176 offset:2048
	ds_read_b128 v[210:213], v176 offset:3072
	global_load_lds_dwordx4 v[214:215], off
	v_lshl_add_u64 v[216:217], s[38:39], 0, v[146:147]
	s_add_i32 m0, s44, 0x2000
	s_nop 0
	global_load_lds_dwordx4 v[216:217], off
	s_waitcnt vmcnt(10)
	s_barrier
	s_waitcnt lgkmcnt(0)
	s_setprio 1
	s_waitcnt lgkmcnt(0)
	v_mfma_f32_16x16x32_bf16 v[116:119], v[198:201], v[152:155], v[116:119]
	v_mfma_f32_16x16x32_bf16 v[112:115], v[206:209], v[152:155], v[112:115]
	v_mfma_f32_16x16x32_bf16 v[100:103], v[198:201], v[160:163], v[100:103]
	v_mfma_f32_16x16x32_bf16 v[96:99], v[206:209], v[160:163], v[96:99]
	v_mfma_f32_16x16x32_bf16 v[84:87], v[198:201], v[168:171], v[84:87]
	v_mfma_f32_16x16x32_bf16 v[80:83], v[206:209], v[168:171], v[80:83]
	v_mfma_f32_16x16x32_bf16 v[68:71], v[198:201], v[190:193], v[68:71]
	v_mfma_f32_16x16x32_bf16 v[64:67], v[206:209], v[190:193], v[64:67]
	v_mfma_f32_16x16x32_bf16 v[116:119], v[202:205], v[156:159], v[116:119]
	v_mfma_f32_16x16x32_bf16 v[112:115], v[210:213], v[156:159], v[112:115]
	v_mfma_f32_16x16x32_bf16 v[100:103], v[202:205], v[164:167], v[100:103]
	v_mfma_f32_16x16x32_bf16 v[96:99], v[210:213], v[164:167], v[96:99]
	v_mfma_f32_16x16x32_bf16 v[84:87], v[202:205], v[172:175], v[84:87]
	v_mfma_f32_16x16x32_bf16 v[80:83], v[210:213], v[172:175], v[80:83]
	v_mfma_f32_16x16x32_bf16 v[68:71], v[202:205], v[194:197], v[68:71]
	v_mfma_f32_16x16x32_bf16 v[64:67], v[210:213], v[194:197], v[64:67]
	s_setprio 0
	s_mov_b32 m0, s59
	v_lshl_add_u64 v[218:219], s[42:43], 0, v[144:145]
	s_barrier
	ds_read_b128 v[152:155], v241 offset:16384
	ds_read_b128 v[156:159], v241 offset:17408
	ds_read_b128 v[160:163], v241 offset:18432
	ds_read_b128 v[164:167], v241 offset:19456
	ds_read_b128 v[168:171], v241 offset:20480
	ds_read_b128 v[172:175], v241 offset:21504
	ds_read_b128 v[190:193], v241 offset:22528
	ds_read_b128 v[194:197], v241 offset:23552
	global_load_lds_dwordx4 v[218:219], off
	v_lshl_add_u64 v[220:221], s[42:43], 0, v[146:147]
	s_mov_b32 m0, s60
	s_nop 0
	global_load_lds_dwordx4 v[220:221], off
	s_barrier
	s_waitcnt lgkmcnt(0)
	s_setprio 1
	s_waitcnt lgkmcnt(0)
	v_mfma_f32_16x16x32_bf16 v[60:63], v[128:131], v[152:155], v[60:63]
	v_mfma_f32_16x16x32_bf16 v[56:59], v[136:139], v[152:155], v[56:59]
	v_mfma_f32_16x16x32_bf16 v[44:47], v[128:131], v[160:163], v[44:47]
	v_mfma_f32_16x16x32_bf16 v[40:43], v[136:139], v[160:163], v[40:43]
	v_mfma_f32_16x16x32_bf16 v[28:31], v[128:131], v[168:171], v[28:31]
	v_mfma_f32_16x16x32_bf16 v[24:27], v[136:139], v[168:171], v[24:27]
	v_mfma_f32_16x16x32_bf16 v[12:15], v[128:131], v[190:193], v[12:15]
	v_mfma_f32_16x16x32_bf16 v[8:11], v[136:139], v[190:193], v[8:11]
	v_mfma_f32_16x16x32_bf16 v[60:63], v[132:135], v[156:159], v[60:63]
	v_mfma_f32_16x16x32_bf16 v[56:59], v[140:143], v[156:159], v[56:59]
	v_mfma_f32_16x16x32_bf16 v[44:47], v[132:135], v[164:167], v[44:47]
	v_mfma_f32_16x16x32_bf16 v[40:43], v[140:143], v[164:167], v[40:43]
	v_mfma_f32_16x16x32_bf16 v[28:31], v[132:135], v[172:175], v[28:31]
	v_mfma_f32_16x16x32_bf16 v[24:27], v[140:143], v[172:175], v[24:27]
	v_mfma_f32_16x16x32_bf16 v[12:15], v[132:135], v[194:197], v[12:15]
	v_mfma_f32_16x16x32_bf16 v[8:11], v[140:143], v[194:197], v[8:11]
	s_setprio 0
	s_barrier
	s_add_u32 s44, s38, 0x40000
	s_addc_u32 s45, s39, 0
	s_add_i32 s46, s46, s58
	v_lshl_add_u64 v[128:129], s[44:45], 0, v[144:145]
	s_mov_b32 m0, s46
	s_nop 0
	global_load_lds_dwordx4 v[128:129], off
	v_lshl_add_u64 v[128:129], s[44:45], 0, v[146:147]
	s_add_i32 m0, s46, 0x2000
	s_nop 0
	global_load_lds_dwordx4 v[128:129], off
	s_waitcnt vmcnt(10)
	s_barrier
	s_setprio 1
	v_mfma_f32_16x16x32_bf16 v[52:55], v[198:201], v[152:155], v[52:55]
	v_mfma_f32_16x16x32_bf16 v[48:51], v[206:209], v[152:155], v[48:51]
	v_mfma_f32_16x16x32_bf16 v[36:39], v[198:201], v[160:163], v[36:39]
	v_mfma_f32_16x16x32_bf16 v[32:35], v[206:209], v[160:163], v[32:35]
	v_mfma_f32_16x16x32_bf16 v[20:23], v[198:201], v[168:171], v[20:23]
	v_mfma_f32_16x16x32_bf16 v[16:19], v[206:209], v[168:171], v[16:19]
	v_mfma_f32_16x16x32_bf16 v[4:7], v[198:201], v[190:193], v[4:7]
	v_mfma_f32_16x16x32_bf16 v[0:3], v[206:209], v[190:193], v[0:3]
	v_mfma_f32_16x16x32_bf16 v[52:55], v[202:205], v[156:159], v[52:55]
	v_mfma_f32_16x16x32_bf16 v[48:51], v[210:213], v[156:159], v[48:51]
	v_mfma_f32_16x16x32_bf16 v[36:39], v[202:205], v[164:167], v[36:39]
	v_mfma_f32_16x16x32_bf16 v[32:35], v[210:213], v[164:167], v[32:35]
	v_mfma_f32_16x16x32_bf16 v[20:23], v[202:205], v[172:175], v[20:23]
	v_mfma_f32_16x16x32_bf16 v[16:19], v[210:213], v[172:175], v[16:19]
	v_mfma_f32_16x16x32_bf16 v[4:7], v[202:205], v[194:197], v[4:7]
	v_mfma_f32_16x16x32_bf16 v[0:3], v[210:213], v[194:197], v[0:3]
	s_setprio 0
	s_add_i32 s44, 0, 0x18000
	v_add_u32_e32 v140, s44, v240
	s_barrier
	ds_read_b128 v[128:131], v140
	ds_read_b128 v[132:135], v140 offset:1024
	ds_read_b128 v[136:139], v140 offset:2048
	ds_read_b128 v[140:143], v140 offset:3072
	s_add_u32 s42, s42, 0x40000
	s_addc_u32 s43, s43, 0
	s_mov_b32 m0, s61
	v_lshl_add_u64 v[198:199], s[42:43], 0, v[144:145]
	ds_read_b128 v[152:155], v241 offset:32768
	ds_read_b128 v[156:159], v241 offset:33792
	ds_read_b128 v[160:163], v241 offset:34816
	ds_read_b128 v[164:167], v241 offset:35840
	ds_read_b128 v[168:171], v241 offset:36864
	ds_read_b128 v[172:175], v241 offset:37888
	ds_read_b128 v[190:193], v241 offset:38912
	ds_read_b128 v[194:197], v241 offset:39936
	global_load_lds_dwordx4 v[198:199], off
	v_lshl_add_u64 v[198:199], s[42:43], 0, v[146:147]
	s_mov_b32 m0, s62
	s_nop 0
	global_load_lds_dwordx4 v[198:199], off
	s_waitcnt lgkmcnt(8)
	s_waitcnt vmcnt(10)
	s_barrier
	s_waitcnt lgkmcnt(0)
	s_setprio 1
	s_waitcnt lgkmcnt(0)
	v_mfma_f32_16x16x32_bf16 v[124:127], v[128:131], v[152:155], v[124:127]
	v_mfma_f32_16x16x32_bf16 v[120:123], v[136:139], v[152:155], v[120:123]
	v_mfma_f32_16x16x32_bf16 v[108:111], v[128:131], v[160:163], v[108:111]
	v_mfma_f32_16x16x32_bf16 v[104:107], v[136:139], v[160:163], v[104:107]
	v_mfma_f32_16x16x32_bf16 v[92:95], v[128:131], v[168:171], v[92:95]
	v_mfma_f32_16x16x32_bf16 v[88:91], v[136:139], v[168:171], v[88:91]
	v_mfma_f32_16x16x32_bf16 v[76:79], v[128:131], v[190:193], v[76:79]
	v_mfma_f32_16x16x32_bf16 v[72:75], v[136:139], v[190:193], v[72:75]
	v_mfma_f32_16x16x32_bf16 v[124:127], v[132:135], v[156:159], v[124:127]
	v_mfma_f32_16x16x32_bf16 v[120:123], v[140:143], v[156:159], v[120:123]
	v_mfma_f32_16x16x32_bf16 v[108:111], v[132:135], v[164:167], v[108:111]
	v_mfma_f32_16x16x32_bf16 v[104:107], v[140:143], v[164:167], v[104:107]
	v_mfma_f32_16x16x32_bf16 v[92:95], v[132:135], v[172:175], v[92:95]
	v_mfma_f32_16x16x32_bf16 v[88:91], v[140:143], v[172:175], v[88:91]
	v_mfma_f32_16x16x32_bf16 v[76:79], v[132:135], v[194:197], v[76:79]
	v_mfma_f32_16x16x32_bf16 v[72:75], v[140:143], v[194:197], v[72:75]
	s_setprio 0
	s_barrier
	s_add_i32 s42, 0, 0x1c000
	s_add_i32 s43, s44, s58
	v_add_u32_e32 v176, s42, v240
	v_lshl_add_u64 v[214:215], v[214:215], 0, s[24:25]
	s_mov_b32 m0, s43
	ds_read_b128 v[198:201], v176
	ds_read_b128 v[202:205], v176 offset:1024
	ds_read_b128 v[206:209], v176 offset:2048
	ds_read_b128 v[210:213], v176 offset:3072
	global_load_lds_dwordx4 v[214:215], off
	v_lshl_add_u64 v[214:215], v[216:217], 0, s[24:25]
	s_add_i32 m0, s43, 0x2000
	s_nop 0
	global_load_lds_dwordx4 v[214:215], off
	s_waitcnt vmcnt(10)
	s_barrier
	s_waitcnt lgkmcnt(0)
	s_setprio 1
	s_waitcnt lgkmcnt(0)
	v_mfma_f32_16x16x32_bf16 v[116:119], v[198:201], v[152:155], v[116:119]
	v_mfma_f32_16x16x32_bf16 v[112:115], v[206:209], v[152:155], v[112:115]
	v_mfma_f32_16x16x32_bf16 v[100:103], v[198:201], v[160:163], v[100:103]
	v_mfma_f32_16x16x32_bf16 v[96:99], v[206:209], v[160:163], v[96:99]
	v_mfma_f32_16x16x32_bf16 v[84:87], v[198:201], v[168:171], v[84:87]
	v_mfma_f32_16x16x32_bf16 v[80:83], v[206:209], v[168:171], v[80:83]
	v_mfma_f32_16x16x32_bf16 v[68:71], v[198:201], v[190:193], v[68:71]
	v_mfma_f32_16x16x32_bf16 v[64:67], v[206:209], v[190:193], v[64:67]
	v_mfma_f32_16x16x32_bf16 v[116:119], v[202:205], v[156:159], v[116:119]
	v_mfma_f32_16x16x32_bf16 v[112:115], v[210:213], v[156:159], v[112:115]
	v_mfma_f32_16x16x32_bf16 v[100:103], v[202:205], v[164:167], v[100:103]
	v_mfma_f32_16x16x32_bf16 v[96:99], v[210:213], v[164:167], v[96:99]
	v_mfma_f32_16x16x32_bf16 v[84:87], v[202:205], v[172:175], v[84:87]
	v_mfma_f32_16x16x32_bf16 v[80:83], v[210:213], v[172:175], v[80:83]
	v_mfma_f32_16x16x32_bf16 v[68:71], v[202:205], v[194:197], v[68:71]
	v_mfma_f32_16x16x32_bf16 v[64:67], v[210:213], v[194:197], v[64:67]
	s_setprio 0
	s_mov_b32 m0, s64
	v_lshl_add_u64 v[214:215], v[218:219], 0, s[24:25]
	s_barrier
	ds_read_b128 v[152:155], v241 offset:49152
	ds_read_b128 v[156:159], v241 offset:50176
	ds_read_b128 v[160:163], v241 offset:51200
	ds_read_b128 v[164:167], v241 offset:52224
	ds_read_b128 v[168:171], v241 offset:53248
	ds_read_b128 v[172:175], v241 offset:54272
	ds_read_b128 v[190:193], v241 offset:55296
	ds_read_b128 v[194:197], v241 offset:56320
	global_load_lds_dwordx4 v[214:215], off
	v_lshl_add_u64 v[214:215], v[220:221], 0, s[24:25]
	s_mov_b32 m0, s65
	s_nop 0
	global_load_lds_dwordx4 v[214:215], off
	s_barrier
	s_waitcnt lgkmcnt(0)
	s_setprio 1
	s_waitcnt lgkmcnt(0)
	v_mfma_f32_16x16x32_bf16 v[60:63], v[128:131], v[152:155], v[60:63]
	v_mfma_f32_16x16x32_bf16 v[56:59], v[136:139], v[152:155], v[56:59]
	v_mfma_f32_16x16x32_bf16 v[44:47], v[128:131], v[160:163], v[44:47]
	v_mfma_f32_16x16x32_bf16 v[40:43], v[136:139], v[160:163], v[40:43]
	v_mfma_f32_16x16x32_bf16 v[28:31], v[128:131], v[168:171], v[28:31]
	v_mfma_f32_16x16x32_bf16 v[24:27], v[136:139], v[168:171], v[24:27]
	v_mfma_f32_16x16x32_bf16 v[12:15], v[128:131], v[190:193], v[12:15]
	v_mfma_f32_16x16x32_bf16 v[8:11], v[136:139], v[190:193], v[8:11]
	v_mfma_f32_16x16x32_bf16 v[60:63], v[132:135], v[156:159], v[60:63]
	v_mfma_f32_16x16x32_bf16 v[56:59], v[140:143], v[156:159], v[56:59]
	v_mfma_f32_16x16x32_bf16 v[44:47], v[132:135], v[164:167], v[44:47]
	v_mfma_f32_16x16x32_bf16 v[40:43], v[140:143], v[164:167], v[40:43]
	v_mfma_f32_16x16x32_bf16 v[28:31], v[132:135], v[172:175], v[28:31]
	v_mfma_f32_16x16x32_bf16 v[24:27], v[140:143], v[172:175], v[24:27]
	v_mfma_f32_16x16x32_bf16 v[12:15], v[132:135], v[194:197], v[12:15]
	v_mfma_f32_16x16x32_bf16 v[8:11], v[140:143], v[194:197], v[8:11]
	s_setprio 0
	s_barrier
	s_add_u32 s38, s38, 0x40080
	s_addc_u32 s39, s39, 0
	s_add_i32 s42, s42, s58
	v_lshl_add_u64 v[128:129], s[38:39], 0, v[144:145]
	s_mov_b32 m0, s42
	s_nop 0
	global_load_lds_dwordx4 v[128:129], off
	v_lshl_add_u64 v[128:129], s[38:39], 0, v[146:147]
	s_add_i32 m0, s42, 0x2000
	s_nop 0
	global_load_lds_dwordx4 v[128:129], off
	s_waitcnt vmcnt(10)
	s_barrier
	s_setprio 1
	v_mfma_f32_16x16x32_bf16 v[52:55], v[198:201], v[152:155], v[52:55]
	v_mfma_f32_16x16x32_bf16 v[48:51], v[206:209], v[152:155], v[48:51]
	v_mfma_f32_16x16x32_bf16 v[36:39], v[198:201], v[160:163], v[36:39]
	v_mfma_f32_16x16x32_bf16 v[32:35], v[206:209], v[160:163], v[32:35]
	v_mfma_f32_16x16x32_bf16 v[20:23], v[198:201], v[168:171], v[20:23]
	v_mfma_f32_16x16x32_bf16 v[16:19], v[206:209], v[168:171], v[16:19]
	v_mfma_f32_16x16x32_bf16 v[4:7], v[198:201], v[190:193], v[4:7]
	v_mfma_f32_16x16x32_bf16 v[0:3], v[206:209], v[190:193], v[0:3]
	v_mfma_f32_16x16x32_bf16 v[52:55], v[202:205], v[156:159], v[52:55]
	v_mfma_f32_16x16x32_bf16 v[48:51], v[210:213], v[156:159], v[48:51]
	v_mfma_f32_16x16x32_bf16 v[36:39], v[202:205], v[164:167], v[36:39]
	v_mfma_f32_16x16x32_bf16 v[32:35], v[210:213], v[164:167], v[32:35]
	v_mfma_f32_16x16x32_bf16 v[20:23], v[202:205], v[172:175], v[20:23]
	v_mfma_f32_16x16x32_bf16 v[16:19], v[210:213], v[172:175], v[16:19]
	v_mfma_f32_16x16x32_bf16 v[4:7], v[202:205], v[194:197], v[4:7]
	v_mfma_f32_16x16x32_bf16 v[0:3], v[210:213], v[194:197], v[0:3]
	s_setprio 0
	s_add_i32 s35, s35, 2
	s_add_u32 s22, s22, 0x100
	s_addc_u32 s23, s23, 0
	s_add_u32 s3, s3, 0x100
	s_addc_u32 s31, s31, 0
	s_cmp_gt_u32 s35, 13
	s_barrier
	s_cbranch_scc0 .LBB0_296
	v_mov_b32_e32 v153, v238
	s_mov_b32 s3, s57
	v_mov_b32_e32 v157, v239
	s_mov_b32 s31, s63
	s_lshl_b32 s22, s2, 8
	s_lshl_b32 s3, s3, 6
	s_add_i32 s3, s3, s22
	v_add_u32_e32 v196, s3, v153
	v_readlane_b32 s22, v249, 12
	v_ashrrev_i32_e32 v197, 31, v196
	v_readlane_b32 s23, v249, 13
	v_lshlrev_b32_e32 v200, 2, v157
	v_add_u32_e32 v192, 16, v196
	v_lshl_add_u64 v[128:129], v[196:197], 2, s[22:23]
	global_load_dword v130, v[128:129], off
	global_load_dword v131, v[128:129], off offset:64
	global_load_dword v132, v[128:129], off offset:128
	global_load_dword v133, v[128:129], off offset:192
	global_load_dword v134, v[128:129], off offset:512
	global_load_dword v135, v[128:129], off offset:576
	global_load_dword v136, v[128:129], off offset:640
	s_nop 0
	global_load_dword v128, v[128:129], off offset:704
	v_add_u32_e32 v174, 32, v196
	v_add_u32_e32 v170, 48, v196
	v_add_u32_e32 v166, 0x80, v196
	v_add_u32_e32 v162, 0x90, v196
	v_add_u32_e32 v158, 0xa0, v196
	v_add_u32_e32 v154, 0xb0, v196
	v_ashrrev_i32_e32 v193, 31, v192
	v_ashrrev_i32_e32 v175, 31, v174
	v_ashrrev_i32_e32 v171, 31, v170
	v_ashrrev_i32_e32 v167, 31, v166
	v_ashrrev_i32_e32 v163, 31, v162
	v_ashrrev_i32_e32 v159, 31, v158
	v_ashrrev_i32_e32 v155, 31, v154
	v_lshl_add_u32 v198, s31, 5, v200
	s_cmp_gt_i32 s74, 1
	s_mov_b64 s[22:23], -1
	s_waitcnt vmcnt(0)
	v_fmamk_f32 v129, v130, 0x3a800000, v228
	v_fmamk_f32 v130, v131, 0x3a800000, v228
	v_fmamk_f32 v131, v132, 0x3a800000, v228
	v_fmamk_f32 v132, v133, 0x3a800000, v228
	v_fmamk_f32 v133, v134, 0x3a800000, v228
	v_fmamk_f32 v134, v135, 0x3a800000, v228
	v_fmamk_f32 v135, v136, 0x3a800000, v228
	v_fmamk_f32 v128, v128, 0x3a800000, v228
	v_rsq_f32_e32 v194, v129
	v_rsq_f32_e32 v190, v130
	v_rsq_f32_e32 v172, v131
	v_rsq_f32_e32 v168, v132
	v_rsq_f32_e32 v164, v133
	v_rsq_f32_e32 v160, v134
	v_rsq_f32_e32 v156, v135
	v_rsq_f32_e32 v152, v128
	s_cbranch_scc0 .LBB0_587
	s_cmpk_gt_i32 s2, 0x7f
	s_cselect_b64 s[42:43], -1, 0
	s_cmpk_lt_i32 s2, 0x80
	s_cselect_b64 s[22:23], -1, 0
	s_cmp_lt_u32 s74, 4
	s_cselect_b64 s[38:39], -1, 0
	s_mov_b64 s[2:3], -1
	s_and_b64 vcc, exec, s[38:39]
	s_cbranch_vccnz .LBB0_386
	s_and_b32 s35, s74, 0x7ffffffe
	s_cmp_lt_i32 s35, 16
	s_cbranch_scc1 .LBB0_301
	s_cmp_lg_u32 s35, 16
	s_cselect_b64 s[44:45], -1, 0
	s_cbranch_execz .LBB0_302
	s_branch .LBB0_303

.LBB0_924:
	v_readlane_b32 s8, v249, 62
	v_and_b32_e32 v142, 15, v14
	v_readlane_b32 s9, v249, 63
	s_waitcnt lgkmcnt(0)
	s_add_u32 s4, s4, s8
	v_bfe_u32 v143, v14, 4, 2
	v_lshlrev_b32_e32 v15, 6, v142
	v_lshlrev_b32_e32 v14, 2, v14
	s_sext_i32_i8 s48, s6
	s_addc_u32 s5, s5, s9
	s_and_b32 s44, s7, 3
	v_lshl_or_b32 v15, v143, 4, v15
	s_lshl_b32 s6, s29, 13
	v_and_b32_e32 v14, 32, v14
	s_add_i32 m0, s3, 0x18000
	v_lshl_add_u64 v[6:7], v[6:7], 0, s[24:25]
	v_bitop3_b32 v16, v15, s6, v14 bitop3:0xde
	s_lshl_b32 s6, s44, 12
	s_waitcnt vmcnt(4)
	s_barrier
	global_load_lds_dwordx4 v[6:7], off
	v_lshl_add_u64 v[4:5], v[4:5], 0, s[24:25]
	s_add_i32 m0, s3, 0x1a000
	s_add_i32 s45, s3, 0x8000
	s_add_i32 s46, s3, 0xa000
	v_bitop3_b32 v144, v15, s6, v14 bitop3:0xde
	global_load_lds_dwordx4 v[4:5], off
	v_lshl_add_u64 v[2:3], v[2:3], 0, s[24:25]
	s_mov_b32 m0, s45
	s_add_u32 s6, s16, 0x20080
	global_load_lds_dwordx4 v[2:3], off
	v_lshl_add_u64 v[0:1], v[0:1], 0, s[24:25]
	s_mov_b32 m0, s46
	s_addc_u32 s7, s17, 0
	global_load_lds_dwordx4 v[0:1], off
	s_add_i32 m0, s3, 0x1c000
	v_lshl_add_u64 v[0:1], s[6:7], 0, v[176:177]
	global_load_lds_dwordx4 v[0:1], off
	v_lshl_add_u64 v[0:1], s[6:7], 0, v[128:129]
	s_add_i32 m0, s3, 0x1e000
	v_mov_b32_e32 v131, v177
	global_load_lds_dwordx4 v[0:1], off
	v_lshlrev_b32_e32 v0, 13, v8
	v_and_b32_e32 v0, 0xffffc000, v0
	v_lshl_add_u32 v0, v9, 10, v0
	v_and_b32_e32 v1, 1, v8
	v_lshl_or_b32 v0, v1, 6, v0
	v_lshl_add_u32 v130, v10, 1, v0
	v_lshlrev_b32_e32 v0, 13, v11
	v_and_b32_e32 v0, 0xffffc000, v0
	s_waitcnt vmcnt(0)
	v_lshl_add_u32 v0, v12, 10, v0
	v_and_b32_e32 v1, 1, v11
	v_lshl_or_b32 v0, v1, 6, v0
	v_lshl_add_u32 v132, v13, 1, v0
	v_mov_b32_e32 v133, v177
	s_mov_b32 s47, 0
	v_add_u32_e32 v145, 0, v16
	s_mov_b64 s[10:11], s[14:15]
	s_mov_b64 s[12:13], s[16:17]
	s_barrier

.LBB0_932:
	s_add_u32 s16, s14, 0xfffe0080
	s_addc_u32 s17, s15, -1
	s_add_i32 s50, 0, 0x10000
	v_add_u32_e32 v150, s50, v144
	ds_read_b128 v[134:137], v150
	ds_read_b128 v[138:141], v150 offset:1024
	ds_read_b128 v[146:149], v150 offset:2048
	ds_read_b128 v[150:153], v150 offset:3072
	s_cmp_eq_u32 s49, 4
	s_cselect_b32 s19, s11, s17
	s_cselect_b32 s18, s10, s16
	s_cselect_b32 s17, s13, s9
	s_cselect_b32 s16, s12, s7
	v_lshl_add_u64 v[174:175], s[14:15], 0, v[130:131]
	s_add_i32 m0, s3, 0xc000
	ds_read_b128 v[154:157], v145
	ds_read_b128 v[158:161], v145 offset:1024
	ds_read_b128 v[162:165], v145 offset:2048
	ds_read_b128 v[166:169], v145 offset:3072
	ds_read_b128 v[170:173], v145 offset:4096
	ds_read_b128 v[190:193], v145 offset:5120
	ds_read_b128 v[194:197], v145 offset:6144
	ds_read_b128 v[198:201], v145 offset:7168
	global_load_lds_dwordx4 v[174:175], off
	v_lshl_add_u64 v[174:175], s[14:15], 0, v[132:133]
	s_add_i32 m0, s3, 0xe000
	s_nop 0
	global_load_lds_dwordx4 v[174:175], off
	s_waitcnt lgkmcnt(8)
	s_waitcnt vmcnt(10)
	s_barrier
	s_waitcnt lgkmcnt(0)
	s_setprio 1
	s_waitcnt lgkmcnt(0)
	v_mfma_f32_16x16x32_bf16 v[124:127], v[134:137], v[154:157], v[124:127]
	v_mfma_f32_16x16x32_bf16 v[120:123], v[146:149], v[154:157], v[120:123]
	v_mfma_f32_16x16x32_bf16 v[108:111], v[134:137], v[162:165], v[108:111]
	v_mfma_f32_16x16x32_bf16 v[104:107], v[146:149], v[162:165], v[104:107]
	v_mfma_f32_16x16x32_bf16 v[92:95], v[134:137], v[170:173], v[92:95]
	v_mfma_f32_16x16x32_bf16 v[88:91], v[146:149], v[170:173], v[88:91]
	v_mfma_f32_16x16x32_bf16 v[76:79], v[134:137], v[194:197], v[76:79]
	v_mfma_f32_16x16x32_bf16 v[72:75], v[146:149], v[194:197], v[72:75]
	v_mfma_f32_16x16x32_bf16 v[124:127], v[138:141], v[158:161], v[124:127]
	v_mfma_f32_16x16x32_bf16 v[120:123], v[150:153], v[158:161], v[120:123]
	v_mfma_f32_16x16x32_bf16 v[108:111], v[138:141], v[166:169], v[108:111]
	v_mfma_f32_16x16x32_bf16 v[104:107], v[150:153], v[166:169], v[104:107]
	v_mfma_f32_16x16x32_bf16 v[92:95], v[138:141], v[190:193], v[92:95]
	v_mfma_f32_16x16x32_bf16 v[88:91], v[150:153], v[190:193], v[88:91]
	v_mfma_f32_16x16x32_bf16 v[76:79], v[138:141], v[198:201], v[76:79]
	v_mfma_f32_16x16x32_bf16 v[72:75], v[150:153], v[198:201], v[72:75]
	s_setprio 0
	s_barrier
	s_add_i32 s52, 0, 0x14000
	v_add_u32_e32 v174, s52, v144
	s_add_i32 s50, s50, s38
	ds_read_b128 v[202:205], v174
	ds_read_b128 v[206:209], v174 offset:1024
	ds_read_b128 v[210:213], v174 offset:2048
	ds_read_b128 v[214:217], v174 offset:3072
	v_lshl_add_u64 v[174:175], s[16:17], 0, v[176:177]
	s_mov_b32 m0, s50
	v_lshl_add_u64 v[218:219], s[16:17], 0, v[128:129]
	global_load_lds_dwordx4 v[174:175], off
	s_add_i32 m0, s50, 0x2000
	s_nop 0
	global_load_lds_dwordx4 v[218:219], off
	s_waitcnt vmcnt(10)
	s_barrier
	s_waitcnt lgkmcnt(0)
	s_setprio 1
	s_waitcnt lgkmcnt(0)
	v_mfma_f32_16x16x32_bf16 v[116:119], v[202:205], v[154:157], v[116:119]
	v_mfma_f32_16x16x32_bf16 v[112:115], v[210:213], v[154:157], v[112:115]
	v_mfma_f32_16x16x32_bf16 v[100:103], v[202:205], v[162:165], v[100:103]
	v_mfma_f32_16x16x32_bf16 v[96:99], v[210:213], v[162:165], v[96:99]
	v_mfma_f32_16x16x32_bf16 v[84:87], v[202:205], v[170:173], v[84:87]
	v_mfma_f32_16x16x32_bf16 v[80:83], v[210:213], v[170:173], v[80:83]
	v_mfma_f32_16x16x32_bf16 v[68:71], v[202:205], v[194:197], v[68:71]
	v_mfma_f32_16x16x32_bf16 v[64:67], v[210:213], v[194:197], v[64:67]
	v_mfma_f32_16x16x32_bf16 v[116:119], v[206:209], v[158:161], v[116:119]
	v_mfma_f32_16x16x32_bf16 v[112:115], v[214:217], v[158:161], v[112:115]
	v_mfma_f32_16x16x32_bf16 v[100:103], v[206:209], v[166:169], v[100:103]
	v_mfma_f32_16x16x32_bf16 v[96:99], v[214:217], v[166:169], v[96:99]
	v_mfma_f32_16x16x32_bf16 v[84:87], v[206:209], v[190:193], v[84:87]
	v_mfma_f32_16x16x32_bf16 v[80:83], v[214:217], v[190:193], v[80:83]
	v_mfma_f32_16x16x32_bf16 v[68:71], v[206:209], v[198:201], v[68:71]
	v_mfma_f32_16x16x32_bf16 v[64:67], v[214:217], v[198:201], v[64:67]
	s_setprio 0
	s_mov_b32 m0, s3
	v_lshl_add_u64 v[220:221], s[18:19], 0, v[176:177]
	s_barrier
	ds_read_b128 v[154:157], v145 offset:16384
	ds_read_b128 v[158:161], v145 offset:17408
	ds_read_b128 v[162:165], v145 offset:18432
	ds_read_b128 v[166:169], v145 offset:19456
	ds_read_b128 v[170:173], v145 offset:20480
	ds_read_b128 v[190:193], v145 offset:21504
	ds_read_b128 v[194:197], v145 offset:22528
	ds_read_b128 v[198:201], v145 offset:23552
	global_load_lds_dwordx4 v[220:221], off
	v_lshl_add_u64 v[222:223], s[18:19], 0, v[128:129]
	s_mov_b32 m0, s39
	s_nop 0
	global_load_lds_dwordx4 v[222:223], off
	s_barrier
	s_waitcnt lgkmcnt(0)
	s_setprio 1
	s_waitcnt lgkmcnt(0)
	v_mfma_f32_16x16x32_bf16 v[60:63], v[134:137], v[154:157], v[60:63]
	v_mfma_f32_16x16x32_bf16 v[56:59], v[146:149], v[154:157], v[56:59]
	v_mfma_f32_16x16x32_bf16 v[44:47], v[134:137], v[162:165], v[44:47]
	v_mfma_f32_16x16x32_bf16 v[40:43], v[146:149], v[162:165], v[40:43]
	v_mfma_f32_16x16x32_bf16 v[28:31], v[134:137], v[170:173], v[28:31]
	v_mfma_f32_16x16x32_bf16 v[24:27], v[146:149], v[170:173], v[24:27]
	v_mfma_f32_16x16x32_bf16 v[12:15], v[134:137], v[194:197], v[12:15]
	v_mfma_f32_16x16x32_bf16 v[8:11], v[146:149], v[194:197], v[8:11]
	v_mfma_f32_16x16x32_bf16 v[60:63], v[138:141], v[158:161], v[60:63]
	v_mfma_f32_16x16x32_bf16 v[56:59], v[150:153], v[158:161], v[56:59]
	v_mfma_f32_16x16x32_bf16 v[44:47], v[138:141], v[166:169], v[44:47]
	v_mfma_f32_16x16x32_bf16 v[40:43], v[150:153], v[166:169], v[40:43]
	v_mfma_f32_16x16x32_bf16 v[28:31], v[138:141], v[190:193], v[28:31]
	v_mfma_f32_16x16x32_bf16 v[24:27], v[150:153], v[190:193], v[24:27]
	v_mfma_f32_16x16x32_bf16 v[12:15], v[138:141], v[198:201], v[12:15]
	v_mfma_f32_16x16x32_bf16 v[8:11], v[150:153], v[198:201], v[8:11]
	s_setprio 0
	s_barrier
	s_add_u32 s50, s16, 0x20000
	s_addc_u32 s51, s17, 0
	s_add_i32 s52, s52, s38
	v_lshl_add_u64 v[134:135], s[50:51], 0, v[176:177]
	s_mov_b32 m0, s52
	s_nop 0
	global_load_lds_dwordx4 v[134:135], off
	v_lshl_add_u64 v[134:135], s[50:51], 0, v[128:129]
	s_add_i32 m0, s52, 0x2000
	s_nop 0
	global_load_lds_dwordx4 v[134:135], off
	s_waitcnt vmcnt(10)
	s_barrier
	s_setprio 1
	v_mfma_f32_16x16x32_bf16 v[52:55], v[202:205], v[154:157], v[52:55]
	v_mfma_f32_16x16x32_bf16 v[48:51], v[210:213], v[154:157], v[48:51]
	v_mfma_f32_16x16x32_bf16 v[36:39], v[202:205], v[162:165], v[36:39]
	v_mfma_f32_16x16x32_bf16 v[32:35], v[210:213], v[162:165], v[32:35]
	v_mfma_f32_16x16x32_bf16 v[20:23], v[202:205], v[170:173], v[20:23]
	v_mfma_f32_16x16x32_bf16 v[16:19], v[210:213], v[170:173], v[16:19]
	v_mfma_f32_16x16x32_bf16 v[4:7], v[202:205], v[194:197], v[4:7]
	v_mfma_f32_16x16x32_bf16 v[0:3], v[210:213], v[194:197], v[0:3]
	v_mfma_f32_16x16x32_bf16 v[52:55], v[206:209], v[158:161], v[52:55]
	v_mfma_f32_16x16x32_bf16 v[48:51], v[214:217], v[158:161], v[48:51]
	v_mfma_f32_16x16x32_bf16 v[36:39], v[206:209], v[166:169], v[36:39]
	v_mfma_f32_16x16x32_bf16 v[32:35], v[214:217], v[166:169], v[32:35]
	v_mfma_f32_16x16x32_bf16 v[20:23], v[206:209], v[190:193], v[20:23]
	v_mfma_f32_16x16x32_bf16 v[16:19], v[214:217], v[190:193], v[16:19]
	v_mfma_f32_16x16x32_bf16 v[4:7], v[206:209], v[198:201], v[4:7]
	v_mfma_f32_16x16x32_bf16 v[0:3], v[214:217], v[198:201], v[0:3]
	s_setprio 0
	s_add_i32 s50, 0, 0x18000
	v_add_u32_e32 v150, s50, v144
	s_barrier
	ds_read_b128 v[134:137], v150
	ds_read_b128 v[138:141], v150 offset:1024
	ds_read_b128 v[146:149], v150 offset:2048
	ds_read_b128 v[150:153], v150 offset:3072
	s_add_u32 s18, s18, 0x20000
	s_addc_u32 s19, s19, 0
	s_mov_b32 m0, s42
	v_lshl_add_u64 v[202:203], s[18:19], 0, v[176:177]
	ds_read_b128 v[154:157], v145 offset:32768
	ds_read_b128 v[158:161], v145 offset:33792
	ds_read_b128 v[162:165], v145 offset:34816
	ds_read_b128 v[166:169], v145 offset:35840
	ds_read_b128 v[170:173], v145 offset:36864
	ds_read_b128 v[190:193], v145 offset:37888
	ds_read_b128 v[194:197], v145 offset:38912
	ds_read_b128 v[198:201], v145 offset:39936
	global_load_lds_dwordx4 v[202:203], off
	v_lshl_add_u64 v[202:203], s[18:19], 0, v[128:129]
	s_mov_b32 m0, s43
	s_nop 0
	global_load_lds_dwordx4 v[202:203], off
	s_waitcnt lgkmcnt(8)
	s_waitcnt vmcnt(10)
	s_barrier
	s_waitcnt lgkmcnt(0)
	s_setprio 1
	s_waitcnt lgkmcnt(0)
	v_mfma_f32_16x16x32_bf16 v[124:127], v[134:137], v[154:157], v[124:127]
	v_mfma_f32_16x16x32_bf16 v[120:123], v[146:149], v[154:157], v[120:123]
	v_mfma_f32_16x16x32_bf16 v[108:111], v[134:137], v[162:165], v[108:111]
	v_mfma_f32_16x16x32_bf16 v[104:107], v[146:149], v[162:165], v[104:107]
	v_mfma_f32_16x16x32_bf16 v[92:95], v[134:137], v[170:173], v[92:95]
	v_mfma_f32_16x16x32_bf16 v[88:91], v[146:149], v[170:173], v[88:91]
	v_mfma_f32_16x16x32_bf16 v[76:79], v[134:137], v[194:197], v[76:79]
	v_mfma_f32_16x16x32_bf16 v[72:75], v[146:149], v[194:197], v[72:75]
	v_mfma_f32_16x16x32_bf16 v[124:127], v[138:141], v[158:161], v[124:127]
	v_mfma_f32_16x16x32_bf16 v[120:123], v[150:153], v[158:161], v[120:123]
	v_mfma_f32_16x16x32_bf16 v[108:111], v[138:141], v[166:169], v[108:111]
	v_mfma_f32_16x16x32_bf16 v[104:107], v[150:153], v[166:169], v[104:107]
	v_mfma_f32_16x16x32_bf16 v[92:95], v[138:141], v[190:193], v[92:95]
	v_mfma_f32_16x16x32_bf16 v[88:91], v[150:153], v[190:193], v[88:91]
	v_mfma_f32_16x16x32_bf16 v[76:79], v[138:141], v[198:201], v[76:79]
	v_mfma_f32_16x16x32_bf16 v[72:75], v[150:153], v[198:201], v[72:75]
	s_setprio 0
	s_barrier
	s_add_i32 s18, 0, 0x1c000
	s_add_i32 s19, s50, s38
	v_add_u32_e32 v214, s18, v144
	v_lshl_add_u64 v[174:175], v[174:175], 0, s[24:25]
	s_mov_b32 m0, s19
	ds_read_b128 v[202:205], v214
	ds_read_b128 v[206:209], v214 offset:1024
	ds_read_b128 v[210:213], v214 offset:2048
	ds_read_b128 v[214:217], v214 offset:3072
	global_load_lds_dwordx4 v[174:175], off
	v_lshl_add_u64 v[174:175], v[218:219], 0, s[24:25]
	s_add_i32 m0, s19, 0x2000
	s_nop 0
	global_load_lds_dwordx4 v[174:175], off
	s_waitcnt vmcnt(10)
	s_barrier
	s_waitcnt lgkmcnt(0)
	s_setprio 1
	s_waitcnt lgkmcnt(0)
	v_mfma_f32_16x16x32_bf16 v[116:119], v[202:205], v[154:157], v[116:119]
	v_mfma_f32_16x16x32_bf16 v[112:115], v[210:213], v[154:157], v[112:115]
	v_mfma_f32_16x16x32_bf16 v[100:103], v[202:205], v[162:165], v[100:103]
	v_mfma_f32_16x16x32_bf16 v[96:99], v[210:213], v[162:165], v[96:99]
	v_mfma_f32_16x16x32_bf16 v[84:87], v[202:205], v[170:173], v[84:87]
	v_mfma_f32_16x16x32_bf16 v[80:83], v[210:213], v[170:173], v[80:83]
	v_mfma_f32_16x16x32_bf16 v[68:71], v[202:205], v[194:197], v[68:71]
	v_mfma_f32_16x16x32_bf16 v[64:67], v[210:213], v[194:197], v[64:67]
	v_mfma_f32_16x16x32_bf16 v[116:119], v[206:209], v[158:161], v[116:119]
	v_mfma_f32_16x16x32_bf16 v[112:115], v[214:217], v[158:161], v[112:115]
	v_mfma_f32_16x16x32_bf16 v[100:103], v[206:209], v[166:169], v[100:103]
	v_mfma_f32_16x16x32_bf16 v[96:99], v[214:217], v[166:169], v[96:99]
	v_mfma_f32_16x16x32_bf16 v[84:87], v[206:209], v[190:193], v[84:87]
	v_mfma_f32_16x16x32_bf16 v[80:83], v[214:217], v[190:193], v[80:83]
	v_mfma_f32_16x16x32_bf16 v[68:71], v[206:209], v[198:201], v[68:71]
	v_mfma_f32_16x16x32_bf16 v[64:67], v[214:217], v[198:201], v[64:67]
	s_setprio 0
	s_mov_b32 m0, s45
	v_lshl_add_u64 v[174:175], v[220:221], 0, s[24:25]
	s_barrier
	ds_read_b128 v[154:157], v145 offset:49152
	ds_read_b128 v[158:161], v145 offset:50176
	ds_read_b128 v[162:165], v145 offset:51200
	ds_read_b128 v[166:169], v145 offset:52224
	ds_read_b128 v[170:173], v145 offset:53248
	ds_read_b128 v[190:193], v145 offset:54272
	ds_read_b128 v[194:197], v145 offset:55296
	ds_read_b128 v[198:201], v145 offset:56320
	global_load_lds_dwordx4 v[174:175], off
	v_lshl_add_u64 v[174:175], v[222:223], 0, s[24:25]
	s_mov_b32 m0, s46
	s_nop 0
	global_load_lds_dwordx4 v[174:175], off
	s_barrier
	s_waitcnt lgkmcnt(0)
	s_setprio 1
	s_waitcnt lgkmcnt(0)
	v_mfma_f32_16x16x32_bf16 v[60:63], v[134:137], v[154:157], v[60:63]
	v_mfma_f32_16x16x32_bf16 v[56:59], v[146:149], v[154:157], v[56:59]
	v_mfma_f32_16x16x32_bf16 v[44:47], v[134:137], v[162:165], v[44:47]
	v_mfma_f32_16x16x32_bf16 v[40:43], v[146:149], v[162:165], v[40:43]
	v_mfma_f32_16x16x32_bf16 v[28:31], v[134:137], v[170:173], v[28:31]
	v_mfma_f32_16x16x32_bf16 v[24:27], v[146:149], v[170:173], v[24:27]
	v_mfma_f32_16x16x32_bf16 v[12:15], v[134:137], v[194:197], v[12:15]
	v_mfma_f32_16x16x32_bf16 v[8:11], v[146:149], v[194:197], v[8:11]
	v_mfma_f32_16x16x32_bf16 v[60:63], v[138:141], v[158:161], v[60:63]
	v_mfma_f32_16x16x32_bf16 v[56:59], v[150:153], v[158:161], v[56:59]
	v_mfma_f32_16x16x32_bf16 v[44:47], v[138:141], v[166:169], v[44:47]
	v_mfma_f32_16x16x32_bf16 v[40:43], v[150:153], v[166:169], v[40:43]
	v_mfma_f32_16x16x32_bf16 v[28:31], v[138:141], v[190:193], v[28:31]
	v_mfma_f32_16x16x32_bf16 v[24:27], v[150:153], v[190:193], v[24:27]
	v_mfma_f32_16x16x32_bf16 v[12:15], v[138:141], v[198:201], v[12:15]
	v_mfma_f32_16x16x32_bf16 v[8:11], v[150:153], v[198:201], v[8:11]
	s_setprio 0
	s_barrier
	s_add_u32 s16, s16, 0x20080
	s_addc_u32 s17, s17, 0
	s_add_i32 s18, s18, s38
	v_lshl_add_u64 v[134:135], s[16:17], 0, v[176:177]
	s_mov_b32 m0, s18
	s_nop 0
	global_load_lds_dwordx4 v[134:135], off
	v_lshl_add_u64 v[134:135], s[16:17], 0, v[128:129]
	s_add_i32 m0, s18, 0x2000
	s_nop 0
	global_load_lds_dwordx4 v[134:135], off
	s_waitcnt vmcnt(10)
	s_barrier
	s_setprio 1
	v_mfma_f32_16x16x32_bf16 v[52:55], v[202:205], v[154:157], v[52:55]
	v_mfma_f32_16x16x32_bf16 v[48:51], v[210:213], v[154:157], v[48:51]
	v_mfma_f32_16x16x32_bf16 v[36:39], v[202:205], v[162:165], v[36:39]
	v_mfma_f32_16x16x32_bf16 v[32:35], v[210:213], v[162:165], v[32:35]
	v_mfma_f32_16x16x32_bf16 v[20:23], v[202:205], v[170:173], v[20:23]
	v_mfma_f32_16x16x32_bf16 v[16:19], v[210:213], v[170:173], v[16:19]
	v_mfma_f32_16x16x32_bf16 v[4:7], v[202:205], v[194:197], v[4:7]
	v_mfma_f32_16x16x32_bf16 v[0:3], v[210:213], v[194:197], v[0:3]
	v_mfma_f32_16x16x32_bf16 v[52:55], v[206:209], v[158:161], v[52:55]
	v_mfma_f32_16x16x32_bf16 v[48:51], v[214:217], v[158:161], v[48:51]
	v_mfma_f32_16x16x32_bf16 v[36:39], v[206:209], v[166:169], v[36:39]
	v_mfma_f32_16x16x32_bf16 v[32:35], v[214:217], v[166:169], v[32:35]
	v_mfma_f32_16x16x32_bf16 v[20:23], v[206:209], v[190:193], v[20:23]
	v_mfma_f32_16x16x32_bf16 v[16:19], v[214:217], v[190:193], v[16:19]
	v_mfma_f32_16x16x32_bf16 v[4:7], v[206:209], v[198:201], v[4:7]
	v_mfma_f32_16x16x32_bf16 v[0:3], v[214:217], v[198:201], v[0:3]
	s_setprio 0
	s_add_i32 s49, s49, 2
	s_add_u32 s14, s14, 0x100
	s_addc_u32 s15, s15, 0
	s_add_u32 s7, s7, 0x100
	s_addc_u32 s9, s9, 0
	s_cmp_gt_u32 s49, 5
	s_barrier
	s_cbranch_scc0 .LBB0_932
	s_lshl_b32 s7, s29, 6
	s_lshl_b32 s9, s2, 8
	s_add_i32 s7, s7, s9
	v_add_u32_e32 v140, s7, v142
	s_lshl_b32 s7, s44, 5
	s_lshl_b32 s9, s48, 8
	s_add_i32 s7, s7, s9
	v_lshl_add_u32 v141, v143, 2, s7
	s_mov_b32 s48, s6
	s_mov_b64 s[16:17], s[12:13]
	s_mov_b32 s2, s8
	s_mov_b64 s[14:15], s[10:11]
	v_lshlrev_b32_e32 v134, 2, v141
	global_load_dwordx4 v[240:243], v134, s[4:5]
	global_load_dwordx4 v[244:247], v134, s[4:5] offset:64
	global_load_dwordx4 v[252:255], v134, s[4:5] offset:512
	global_load_dwordx4 v[136:139], v134, s[4:5] offset:576
	v_lshlrev_b32_e32 v238, 10, v140
	v_lshl_add_u32 v238, v141, 1, v238
	v_lshlrev_b32_e32 v239, 11, v140
	v_lshl_add_u32 v239, v141, 1, v239
	v_add_u32_e32 v239, 0x4100400, v239
	global_load_dwordx2 v[190:191], v238, s[78:79]
	global_load_dwordx2 v[192:193], v238, s[78:79] offset:32
	global_load_dwordx2 v[194:195], v238, s[78:79] offset:256
	global_load_dwordx2 v[196:197], v238, s[78:79] offset:288
	v_add_u32_e32 v238, 0x4000, v238
	global_load_dwordx2 v[198:199], v238, s[78:79]
	global_load_dwordx2 v[200:201], v238, s[78:79] offset:32
	global_load_dwordx2 v[202:203], v238, s[78:79] offset:256
	global_load_dwordx2 v[204:205], v238, s[78:79] offset:288
	v_add_u32_e32 v238, 0x4000, v238
	global_load_dwordx2 v[206:207], v238, s[78:79]
	global_load_dwordx2 v[208:209], v238, s[78:79] offset:32
	global_load_dwordx2 v[210:211], v238, s[78:79] offset:256
	global_load_dwordx2 v[212:213], v238, s[78:79] offset:288
	v_add_u32_e32 v238, 0x4000, v238
	global_load_dwordx2 v[214:215], v238, s[78:79]
	global_load_dwordx2 v[216:217], v238, s[78:79] offset:32
	global_load_dwordx2 v[218:219], v238, s[78:79] offset:256
	global_load_dwordx2 v[220:221], v238, s[78:79] offset:288
	v_add_u32_e32 v238, 0x14000, v238
	global_load_dwordx2 v[222:223], v238, s[78:79]
	global_load_dwordx2 v[146:147], v238, s[78:79] offset:32
	global_load_dwordx2 v[148:149], v238, s[78:79] offset:256
	global_load_dwordx2 v[150:151], v238, s[78:79] offset:288
	v_add_u32_e32 v238, 0x4000, v238
	global_load_dwordx2 v[152:153], v238, s[78:79]
	global_load_dwordx2 v[154:155], v238, s[78:79] offset:32
	global_load_dwordx2 v[156:157], v238, s[78:79] offset:256
	global_load_dwordx2 v[158:159], v238, s[78:79] offset:288
	v_add_u32_e32 v238, 0x4000, v238
	global_load_dwordx2 v[160:161], v238, s[78:79]
	global_load_dwordx2 v[162:163], v238, s[78:79] offset:32
	global_load_dwordx2 v[164:165], v238, s[78:79] offset:256
	global_load_dwordx2 v[166:167], v238, s[78:79] offset:288
	v_add_u32_e32 v238, 0x4000, v238
	global_load_dwordx2 v[168:169], v238, s[78:79]
	global_load_dwordx2 v[170:171], v238, s[78:79] offset:32
	global_load_dwordx2 v[172:173], v238, s[78:79] offset:256
	global_load_dwordx2 v[174:175], v238, s[78:79] offset:288
	s_waitcnt vmcnt(31)
	v_pk_add_f32 v[124:125], v[124:125], v[240:241]
	v_pk_add_f32 v[126:127], v[126:127], v[242:243]
	v_mul_f32_e32 v124, 0xbfb8aa3b, v124
	v_mul_f32_e32 v125, 0xbfb8aa3b, v125
	v_mul_f32_e32 v126, 0xbfb8aa3b, v126
	v_mul_f32_e32 v127, 0xbfb8aa3b, v127
	v_exp_f32_e32 v124, v124
	v_exp_f32_e32 v125, v125
	v_exp_f32_e32 v126, v126
	v_exp_f32_e32 v127, v127
	v_lshlrev_b32_e32 v134, 16, v190
	v_and_b32_e32 v135, 0xffff0000, v190
	v_lshlrev_b32_e32 v140, 16, v191
	v_and_b32_e32 v141, 0xffff0000, v191
	v_add_f32_e32 v124, 1.0, v124
	v_add_f32_e32 v125, 1.0, v125
	v_add_f32_e32 v126, 1.0, v126
	v_add_f32_e32 v127, 1.0, v127
	v_rcp_f32_e32 v124, v124
	v_rcp_f32_e32 v125, v125
	v_rcp_f32_e32 v126, v126
	v_rcp_f32_e32 v127, v127
	s_nop 0
	v_pk_mul_f32 v[124:125], v[124:125], v[134:135]
	v_pk_mul_f32 v[126:127], v[126:127], v[140:141]
	v_cvt_pk_bf16_f32 v134, v124, v125
	v_cvt_pk_bf16_f32 v135, v126, v127
	global_store_dwordx2 v239, v[134:135], s[96:97]
	s_waitcnt vmcnt(31)
	v_pk_add_f32 v[120:121], v[120:121], v[244:245]
	v_pk_add_f32 v[122:123], v[122:123], v[246:247]
	v_mul_f32_e32 v120, 0xbfb8aa3b, v120
	v_mul_f32_e32 v121, 0xbfb8aa3b, v121
	v_mul_f32_e32 v122, 0xbfb8aa3b, v122
	v_mul_f32_e32 v123, 0xbfb8aa3b, v123
	v_exp_f32_e32 v120, v120
	v_exp_f32_e32 v121, v121
	v_exp_f32_e32 v122, v122
	v_exp_f32_e32 v123, v123
	v_lshlrev_b32_e32 v134, 16, v192
	v_and_b32_e32 v135, 0xffff0000, v192
	v_lshlrev_b32_e32 v140, 16, v193
	v_and_b32_e32 v141, 0xffff0000, v193
	v_add_f32_e32 v120, 1.0, v120
	v_add_f32_e32 v121, 1.0, v121
	v_add_f32_e32 v122, 1.0, v122
	v_add_f32_e32 v123, 1.0, v123
	v_rcp_f32_e32 v120, v120
	v_rcp_f32_e32 v121, v121
	v_rcp_f32_e32 v122, v122
	v_rcp_f32_e32 v123, v123
	s_nop 0
	v_pk_mul_f32 v[120:121], v[120:121], v[134:135]
	v_pk_mul_f32 v[122:123], v[122:123], v[140:141]
	v_cvt_pk_bf16_f32 v134, v120, v121
	v_cvt_pk_bf16_f32 v135, v122, v123
	global_store_dwordx2 v239, v[134:135], s[96:97] offset:32
	s_waitcnt vmcnt(31)
	v_pk_add_f32 v[116:117], v[116:117], v[252:253]
	v_pk_add_f32 v[118:119], v[118:119], v[254:255]
	v_mul_f32_e32 v116, 0xbfb8aa3b, v116
	v_mul_f32_e32 v117, 0xbfb8aa3b, v117
	v_mul_f32_e32 v118, 0xbfb8aa3b, v118
	v_mul_f32_e32 v119, 0xbfb8aa3b, v119
	v_exp_f32_e32 v116, v116
	v_exp_f32_e32 v117, v117
	v_exp_f32_e32 v118, v118
	v_exp_f32_e32 v119, v119
	v_lshlrev_b32_e32 v134, 16, v194
	v_and_b32_e32 v135, 0xffff0000, v194
	v_lshlrev_b32_e32 v140, 16, v195
	v_and_b32_e32 v141, 0xffff0000, v195
	v_add_f32_e32 v116, 1.0, v116
	v_add_f32_e32 v117, 1.0, v117
	v_add_f32_e32 v118, 1.0, v118
	v_add_f32_e32 v119, 1.0, v119
	v_rcp_f32_e32 v116, v116
	v_rcp_f32_e32 v117, v117
	v_rcp_f32_e32 v118, v118
	v_rcp_f32_e32 v119, v119
	s_nop 0
	v_pk_mul_f32 v[116:117], v[116:117], v[134:135]
	v_pk_mul_f32 v[118:119], v[118:119], v[140:141]
	v_cvt_pk_bf16_f32 v134, v116, v117
	v_cvt_pk_bf16_f32 v135, v118, v119
	global_store_dwordx2 v239, v[134:135], s[96:97] offset:256
	s_waitcnt vmcnt(31)
	v_pk_add_f32 v[112:113], v[112:113], v[136:137]
	v_pk_add_f32 v[114:115], v[114:115], v[138:139]
	v_mul_f32_e32 v112, 0xbfb8aa3b, v112
	v_mul_f32_e32 v113, 0xbfb8aa3b, v113
	v_mul_f32_e32 v114, 0xbfb8aa3b, v114
	v_mul_f32_e32 v115, 0xbfb8aa3b, v115
	v_exp_f32_e32 v112, v112
	v_exp_f32_e32 v113, v113
	v_exp_f32_e32 v114, v114
	v_exp_f32_e32 v115, v115
	v_lshlrev_b32_e32 v134, 16, v196
	v_and_b32_e32 v135, 0xffff0000, v196
	v_lshlrev_b32_e32 v140, 16, v197
	v_and_b32_e32 v141, 0xffff0000, v197
	v_add_f32_e32 v112, 1.0, v112
	v_add_f32_e32 v113, 1.0, v113
	v_add_f32_e32 v114, 1.0, v114
	v_add_f32_e32 v115, 1.0, v115
	v_rcp_f32_e32 v112, v112
	v_rcp_f32_e32 v113, v113
	v_rcp_f32_e32 v114, v114
	v_rcp_f32_e32 v115, v115
	s_nop 0
	v_pk_mul_f32 v[112:113], v[112:113], v[134:135]
	v_pk_mul_f32 v[114:115], v[114:115], v[140:141]
	v_cvt_pk_bf16_f32 v134, v112, v113
	v_cvt_pk_bf16_f32 v135, v114, v115
	global_store_dwordx2 v239, v[134:135], s[96:97] offset:288
	v_add_u32_e32 v239, 0x8000, v239
	s_waitcnt vmcnt(31)
	v_pk_add_f32 v[108:109], v[108:109], v[240:241]
	v_pk_add_f32 v[110:111], v[110:111], v[242:243]
	v_mul_f32_e32 v108, 0xbfb8aa3b, v108
	v_mul_f32_e32 v109, 0xbfb8aa3b, v109
	v_mul_f32_e32 v110, 0xbfb8aa3b, v110
	v_mul_f32_e32 v111, 0xbfb8aa3b, v111
	v_exp_f32_e32 v108, v108
	v_exp_f32_e32 v109, v109
	v_exp_f32_e32 v110, v110
	v_exp_f32_e32 v111, v111
	v_lshlrev_b32_e32 v134, 16, v198
	v_and_b32_e32 v135, 0xffff0000, v198
	v_lshlrev_b32_e32 v140, 16, v199
	v_and_b32_e32 v141, 0xffff0000, v199
	v_add_f32_e32 v108, 1.0, v108
	v_add_f32_e32 v109, 1.0, v109
	v_add_f32_e32 v110, 1.0, v110
	v_add_f32_e32 v111, 1.0, v111
	v_rcp_f32_e32 v108, v108
	v_rcp_f32_e32 v109, v109
	v_rcp_f32_e32 v110, v110
	v_rcp_f32_e32 v111, v111
	s_nop 0
	v_pk_mul_f32 v[108:109], v[108:109], v[134:135]
	v_pk_mul_f32 v[110:111], v[110:111], v[140:141]
	v_cvt_pk_bf16_f32 v134, v108, v109
	v_cvt_pk_bf16_f32 v135, v110, v111
	global_store_dwordx2 v239, v[134:135], s[96:97]
	s_waitcnt vmcnt(31)
	v_pk_add_f32 v[104:105], v[104:105], v[244:245]
	v_pk_add_f32 v[106:107], v[106:107], v[246:247]
	v_mul_f32_e32 v104, 0xbfb8aa3b, v104
	v_mul_f32_e32 v105, 0xbfb8aa3b, v105
	v_mul_f32_e32 v106, 0xbfb8aa3b, v106
	v_mul_f32_e32 v107, 0xbfb8aa3b, v107
	v_exp_f32_e32 v104, v104
	v_exp_f32_e32 v105, v105
	v_exp_f32_e32 v106, v106
	v_exp_f32_e32 v107, v107
	v_lshlrev_b32_e32 v134, 16, v200
	v_and_b32_e32 v135, 0xffff0000, v200
	v_lshlrev_b32_e32 v140, 16, v201
	v_and_b32_e32 v141, 0xffff0000, v201
	v_add_f32_e32 v104, 1.0, v104
	v_add_f32_e32 v105, 1.0, v105
	v_add_f32_e32 v106, 1.0, v106
	v_add_f32_e32 v107, 1.0, v107
	v_rcp_f32_e32 v104, v104
	v_rcp_f32_e32 v105, v105
	v_rcp_f32_e32 v106, v106
	v_rcp_f32_e32 v107, v107
	s_nop 0
	v_pk_mul_f32 v[104:105], v[104:105], v[134:135]
	v_pk_mul_f32 v[106:107], v[106:107], v[140:141]
	v_cvt_pk_bf16_f32 v134, v104, v105
	v_cvt_pk_bf16_f32 v135, v106, v107
	global_store_dwordx2 v239, v[134:135], s[96:97] offset:32
	s_waitcnt vmcnt(31)
	v_pk_add_f32 v[100:101], v[100:101], v[252:253]
	v_pk_add_f32 v[102:103], v[102:103], v[254:255]
	v_mul_f32_e32 v100, 0xbfb8aa3b, v100
	v_mul_f32_e32 v101, 0xbfb8aa3b, v101
	v_mul_f32_e32 v102, 0xbfb8aa3b, v102
	v_mul_f32_e32 v103, 0xbfb8aa3b, v103
	v_exp_f32_e32 v100, v100
	v_exp_f32_e32 v101, v101
	v_exp_f32_e32 v102, v102
	v_exp_f32_e32 v103, v103
	v_lshlrev_b32_e32 v134, 16, v202
	v_and_b32_e32 v135, 0xffff0000, v202
	v_lshlrev_b32_e32 v140, 16, v203
	v_and_b32_e32 v141, 0xffff0000, v203
	v_add_f32_e32 v100, 1.0, v100
	v_add_f32_e32 v101, 1.0, v101
	v_add_f32_e32 v102, 1.0, v102
	v_add_f32_e32 v103, 1.0, v103
	v_rcp_f32_e32 v100, v100
	v_rcp_f32_e32 v101, v101
	v_rcp_f32_e32 v102, v102
	v_rcp_f32_e32 v103, v103
	s_nop 0
	v_pk_mul_f32 v[100:101], v[100:101], v[134:135]
	v_pk_mul_f32 v[102:103], v[102:103], v[140:141]
	v_cvt_pk_bf16_f32 v134, v100, v101
	v_cvt_pk_bf16_f32 v135, v102, v103
	global_store_dwordx2 v239, v[134:135], s[96:97] offset:256
	s_waitcnt vmcnt(31)
	v_pk_add_f32 v[96:97], v[96:97], v[136:137]
	v_pk_add_f32 v[98:99], v[98:99], v[138:139]
	v_mul_f32_e32 v96, 0xbfb8aa3b, v96
	v_mul_f32_e32 v97, 0xbfb8aa3b, v97
	v_mul_f32_e32 v98, 0xbfb8aa3b, v98
	v_mul_f32_e32 v99, 0xbfb8aa3b, v99
	v_exp_f32_e32 v96, v96
	v_exp_f32_e32 v97, v97
	v_exp_f32_e32 v98, v98
	v_exp_f32_e32 v99, v99
	v_lshlrev_b32_e32 v134, 16, v204
	v_and_b32_e32 v135, 0xffff0000, v204
	v_lshlrev_b32_e32 v140, 16, v205
	v_and_b32_e32 v141, 0xffff0000, v205
	v_add_f32_e32 v96, 1.0, v96
	v_add_f32_e32 v97, 1.0, v97
	v_add_f32_e32 v98, 1.0, v98
	v_add_f32_e32 v99, 1.0, v99
	v_rcp_f32_e32 v96, v96
	v_rcp_f32_e32 v97, v97
	v_rcp_f32_e32 v98, v98
	v_rcp_f32_e32 v99, v99
	s_nop 0
	v_pk_mul_f32 v[96:97], v[96:97], v[134:135]
	v_pk_mul_f32 v[98:99], v[98:99], v[140:141]
	v_cvt_pk_bf16_f32 v134, v96, v97
	v_cvt_pk_bf16_f32 v135, v98, v99
	global_store_dwordx2 v239, v[134:135], s[96:97] offset:288
	v_add_u32_e32 v239, 0x8000, v239
	s_waitcnt vmcnt(31)
	v_pk_add_f32 v[92:93], v[92:93], v[240:241]
	v_pk_add_f32 v[94:95], v[94:95], v[242:243]
	v_mul_f32_e32 v92, 0xbfb8aa3b, v92
	v_mul_f32_e32 v93, 0xbfb8aa3b, v93
	v_mul_f32_e32 v94, 0xbfb8aa3b, v94
	v_mul_f32_e32 v95, 0xbfb8aa3b, v95
	v_exp_f32_e32 v92, v92
	v_exp_f32_e32 v93, v93
	v_exp_f32_e32 v94, v94
	v_exp_f32_e32 v95, v95
	v_lshlrev_b32_e32 v134, 16, v206
	v_and_b32_e32 v135, 0xffff0000, v206
	v_lshlrev_b32_e32 v140, 16, v207
	v_and_b32_e32 v141, 0xffff0000, v207
	v_add_f32_e32 v92, 1.0, v92
	v_add_f32_e32 v93, 1.0, v93
	v_add_f32_e32 v94, 1.0, v94
	v_add_f32_e32 v95, 1.0, v95
	v_rcp_f32_e32 v92, v92
	v_rcp_f32_e32 v93, v93
	v_rcp_f32_e32 v94, v94
	v_rcp_f32_e32 v95, v95
	s_nop 0
	v_pk_mul_f32 v[92:93], v[92:93], v[134:135]
	v_pk_mul_f32 v[94:95], v[94:95], v[140:141]
	v_cvt_pk_bf16_f32 v134, v92, v93
	v_cvt_pk_bf16_f32 v135, v94, v95
	global_store_dwordx2 v239, v[134:135], s[96:97]
	s_waitcnt vmcnt(31)
	v_pk_add_f32 v[88:89], v[88:89], v[244:245]
	v_pk_add_f32 v[90:91], v[90:91], v[246:247]
	v_mul_f32_e32 v88, 0xbfb8aa3b, v88
	v_mul_f32_e32 v89, 0xbfb8aa3b, v89
	v_mul_f32_e32 v90, 0xbfb8aa3b, v90
	v_mul_f32_e32 v91, 0xbfb8aa3b, v91
	v_exp_f32_e32 v88, v88
	v_exp_f32_e32 v89, v89
	v_exp_f32_e32 v90, v90
	v_exp_f32_e32 v91, v91
	v_lshlrev_b32_e32 v134, 16, v208
	v_and_b32_e32 v135, 0xffff0000, v208
	v_lshlrev_b32_e32 v140, 16, v209
	v_and_b32_e32 v141, 0xffff0000, v209
	v_add_f32_e32 v88, 1.0, v88
	v_add_f32_e32 v89, 1.0, v89
	v_add_f32_e32 v90, 1.0, v90
	v_add_f32_e32 v91, 1.0, v91
	v_rcp_f32_e32 v88, v88
	v_rcp_f32_e32 v89, v89
	v_rcp_f32_e32 v90, v90
	v_rcp_f32_e32 v91, v91
	s_nop 0
	v_pk_mul_f32 v[88:89], v[88:89], v[134:135]
	v_pk_mul_f32 v[90:91], v[90:91], v[140:141]
	v_cvt_pk_bf16_f32 v134, v88, v89
	v_cvt_pk_bf16_f32 v135, v90, v91
	global_store_dwordx2 v239, v[134:135], s[96:97] offset:32
	s_waitcnt vmcnt(31)
	v_pk_add_f32 v[84:85], v[84:85], v[252:253]
	v_pk_add_f32 v[86:87], v[86:87], v[254:255]
	v_mul_f32_e32 v84, 0xbfb8aa3b, v84
	v_mul_f32_e32 v85, 0xbfb8aa3b, v85
	v_mul_f32_e32 v86, 0xbfb8aa3b, v86
	v_mul_f32_e32 v87, 0xbfb8aa3b, v87
	v_exp_f32_e32 v84, v84
	v_exp_f32_e32 v85, v85
	v_exp_f32_e32 v86, v86
	v_exp_f32_e32 v87, v87
	v_lshlrev_b32_e32 v134, 16, v210
	v_and_b32_e32 v135, 0xffff0000, v210
	v_lshlrev_b32_e32 v140, 16, v211
	v_and_b32_e32 v141, 0xffff0000, v211
	v_add_f32_e32 v84, 1.0, v84
	v_add_f32_e32 v85, 1.0, v85
	v_add_f32_e32 v86, 1.0, v86
	v_add_f32_e32 v87, 1.0, v87
	v_rcp_f32_e32 v84, v84
	v_rcp_f32_e32 v85, v85
	v_rcp_f32_e32 v86, v86
	v_rcp_f32_e32 v87, v87
	s_nop 0
	v_pk_mul_f32 v[84:85], v[84:85], v[134:135]
	v_pk_mul_f32 v[86:87], v[86:87], v[140:141]
	v_cvt_pk_bf16_f32 v134, v84, v85
	v_cvt_pk_bf16_f32 v135, v86, v87
	global_store_dwordx2 v239, v[134:135], s[96:97] offset:256
	s_waitcnt vmcnt(31)
	v_pk_add_f32 v[80:81], v[80:81], v[136:137]
	v_pk_add_f32 v[82:83], v[82:83], v[138:139]
	v_mul_f32_e32 v80, 0xbfb8aa3b, v80
	v_mul_f32_e32 v81, 0xbfb8aa3b, v81
	v_mul_f32_e32 v82, 0xbfb8aa3b, v82
	v_mul_f32_e32 v83, 0xbfb8aa3b, v83
	v_exp_f32_e32 v80, v80
	v_exp_f32_e32 v81, v81
	v_exp_f32_e32 v82, v82
	v_exp_f32_e32 v83, v83
	v_lshlrev_b32_e32 v134, 16, v212
	v_and_b32_e32 v135, 0xffff0000, v212
	v_lshlrev_b32_e32 v140, 16, v213
	v_and_b32_e32 v141, 0xffff0000, v213
	v_add_f32_e32 v80, 1.0, v80
	v_add_f32_e32 v81, 1.0, v81
	v_add_f32_e32 v82, 1.0, v82
	v_add_f32_e32 v83, 1.0, v83
	v_rcp_f32_e32 v80, v80
	v_rcp_f32_e32 v81, v81
	v_rcp_f32_e32 v82, v82
	v_rcp_f32_e32 v83, v83
	s_nop 0
	v_pk_mul_f32 v[80:81], v[80:81], v[134:135]
	v_pk_mul_f32 v[82:83], v[82:83], v[140:141]
	v_cvt_pk_bf16_f32 v134, v80, v81
	v_cvt_pk_bf16_f32 v135, v82, v83
	global_store_dwordx2 v239, v[134:135], s[96:97] offset:288
	v_add_u32_e32 v239, 0x8000, v239
	s_waitcnt vmcnt(31)
	v_pk_add_f32 v[76:77], v[76:77], v[240:241]
	v_pk_add_f32 v[78:79], v[78:79], v[242:243]
	v_mul_f32_e32 v76, 0xbfb8aa3b, v76
	v_mul_f32_e32 v77, 0xbfb8aa3b, v77
	v_mul_f32_e32 v78, 0xbfb8aa3b, v78
	v_mul_f32_e32 v79, 0xbfb8aa3b, v79
	v_exp_f32_e32 v76, v76
	v_exp_f32_e32 v77, v77
	v_exp_f32_e32 v78, v78
	v_exp_f32_e32 v79, v79
	v_lshlrev_b32_e32 v134, 16, v214
	v_and_b32_e32 v135, 0xffff0000, v214
	v_lshlrev_b32_e32 v140, 16, v215
	v_and_b32_e32 v141, 0xffff0000, v215
	v_add_f32_e32 v76, 1.0, v76
	v_add_f32_e32 v77, 1.0, v77
	v_add_f32_e32 v78, 1.0, v78
	v_add_f32_e32 v79, 1.0, v79
	v_rcp_f32_e32 v76, v76
	v_rcp_f32_e32 v77, v77
	v_rcp_f32_e32 v78, v78
	v_rcp_f32_e32 v79, v79
	s_nop 0
	v_pk_mul_f32 v[76:77], v[76:77], v[134:135]
	v_pk_mul_f32 v[78:79], v[78:79], v[140:141]
	v_cvt_pk_bf16_f32 v134, v76, v77
	v_cvt_pk_bf16_f32 v135, v78, v79
	global_store_dwordx2 v239, v[134:135], s[96:97]
	s_waitcnt vmcnt(31)
	v_pk_add_f32 v[72:73], v[72:73], v[244:245]
	v_pk_add_f32 v[74:75], v[74:75], v[246:247]
	v_mul_f32_e32 v72, 0xbfb8aa3b, v72
	v_mul_f32_e32 v73, 0xbfb8aa3b, v73
	v_mul_f32_e32 v74, 0xbfb8aa3b, v74
	v_mul_f32_e32 v75, 0xbfb8aa3b, v75
	v_exp_f32_e32 v72, v72
	v_exp_f32_e32 v73, v73
	v_exp_f32_e32 v74, v74
	v_exp_f32_e32 v75, v75
	v_lshlrev_b32_e32 v134, 16, v216
	v_and_b32_e32 v135, 0xffff0000, v216
	v_lshlrev_b32_e32 v140, 16, v217
	v_and_b32_e32 v141, 0xffff0000, v217
	v_add_f32_e32 v72, 1.0, v72
	v_add_f32_e32 v73, 1.0, v73
	v_add_f32_e32 v74, 1.0, v74
	v_add_f32_e32 v75, 1.0, v75
	v_rcp_f32_e32 v72, v72
	v_rcp_f32_e32 v73, v73
	v_rcp_f32_e32 v74, v74
	v_rcp_f32_e32 v75, v75
	s_nop 0
	v_pk_mul_f32 v[72:73], v[72:73], v[134:135]
	v_pk_mul_f32 v[74:75], v[74:75], v[140:141]
	v_cvt_pk_bf16_f32 v134, v72, v73
	v_cvt_pk_bf16_f32 v135, v74, v75
	global_store_dwordx2 v239, v[134:135], s[96:97] offset:32
	s_waitcnt vmcnt(31)
	v_pk_add_f32 v[68:69], v[68:69], v[252:253]
	v_pk_add_f32 v[70:71], v[70:71], v[254:255]
	v_mul_f32_e32 v68, 0xbfb8aa3b, v68
	v_mul_f32_e32 v69, 0xbfb8aa3b, v69
	v_mul_f32_e32 v70, 0xbfb8aa3b, v70
	v_mul_f32_e32 v71, 0xbfb8aa3b, v71
	v_exp_f32_e32 v68, v68
	v_exp_f32_e32 v69, v69
	v_exp_f32_e32 v70, v70
	v_exp_f32_e32 v71, v71
	v_lshlrev_b32_e32 v134, 16, v218
	v_and_b32_e32 v135, 0xffff0000, v218
	v_lshlrev_b32_e32 v140, 16, v219
	v_and_b32_e32 v141, 0xffff0000, v219
	v_add_f32_e32 v68, 1.0, v68
	v_add_f32_e32 v69, 1.0, v69
	v_add_f32_e32 v70, 1.0, v70
	v_add_f32_e32 v71, 1.0, v71
	v_rcp_f32_e32 v68, v68
	v_rcp_f32_e32 v69, v69
	v_rcp_f32_e32 v70, v70
	v_rcp_f32_e32 v71, v71
	s_nop 0
	v_pk_mul_f32 v[68:69], v[68:69], v[134:135]
	v_pk_mul_f32 v[70:71], v[70:71], v[140:141]
	v_cvt_pk_bf16_f32 v134, v68, v69
	v_cvt_pk_bf16_f32 v135, v70, v71
	global_store_dwordx2 v239, v[134:135], s[96:97] offset:256
	s_waitcnt vmcnt(31)
	v_pk_add_f32 v[64:65], v[64:65], v[136:137]
	v_pk_add_f32 v[66:67], v[66:67], v[138:139]
	v_mul_f32_e32 v64, 0xbfb8aa3b, v64
	v_mul_f32_e32 v65, 0xbfb8aa3b, v65
	v_mul_f32_e32 v66, 0xbfb8aa3b, v66
	v_mul_f32_e32 v67, 0xbfb8aa3b, v67
	v_exp_f32_e32 v64, v64
	v_exp_f32_e32 v65, v65
	v_exp_f32_e32 v66, v66
	v_exp_f32_e32 v67, v67
	v_lshlrev_b32_e32 v134, 16, v220
	v_and_b32_e32 v135, 0xffff0000, v220
	v_lshlrev_b32_e32 v140, 16, v221
	v_and_b32_e32 v141, 0xffff0000, v221
	v_add_f32_e32 v64, 1.0, v64
	v_add_f32_e32 v65, 1.0, v65
	v_add_f32_e32 v66, 1.0, v66
	v_add_f32_e32 v67, 1.0, v67
	v_rcp_f32_e32 v64, v64
	v_rcp_f32_e32 v65, v65
	v_rcp_f32_e32 v66, v66
	v_rcp_f32_e32 v67, v67
	s_nop 0
	v_pk_mul_f32 v[64:65], v[64:65], v[134:135]
	v_pk_mul_f32 v[66:67], v[66:67], v[140:141]
	v_cvt_pk_bf16_f32 v134, v64, v65
	v_cvt_pk_bf16_f32 v135, v66, v67
	global_store_dwordx2 v239, v[134:135], s[96:97] offset:288
	v_add_u32_e32 v239, 0x28000, v239
	s_waitcnt vmcnt(31)
	v_pk_add_f32 v[60:61], v[60:61], v[240:241]
	v_pk_add_f32 v[62:63], v[62:63], v[242:243]
	v_mul_f32_e32 v60, 0xbfb8aa3b, v60
	v_mul_f32_e32 v61, 0xbfb8aa3b, v61
	v_mul_f32_e32 v62, 0xbfb8aa3b, v62
	v_mul_f32_e32 v63, 0xbfb8aa3b, v63
	v_exp_f32_e32 v60, v60
	v_exp_f32_e32 v61, v61
	v_exp_f32_e32 v62, v62
	v_exp_f32_e32 v63, v63
	v_lshlrev_b32_e32 v134, 16, v222
	v_and_b32_e32 v135, 0xffff0000, v222
	v_lshlrev_b32_e32 v140, 16, v223
	v_and_b32_e32 v141, 0xffff0000, v223
	v_add_f32_e32 v60, 1.0, v60
	v_add_f32_e32 v61, 1.0, v61
	v_add_f32_e32 v62, 1.0, v62
	v_add_f32_e32 v63, 1.0, v63
	v_rcp_f32_e32 v60, v60
	v_rcp_f32_e32 v61, v61
	v_rcp_f32_e32 v62, v62
	v_rcp_f32_e32 v63, v63
	s_nop 0
	v_pk_mul_f32 v[60:61], v[60:61], v[134:135]
	v_pk_mul_f32 v[62:63], v[62:63], v[140:141]
	v_cvt_pk_bf16_f32 v134, v60, v61
	v_cvt_pk_bf16_f32 v135, v62, v63
	global_store_dwordx2 v239, v[134:135], s[96:97]
	s_waitcnt vmcnt(31)
	v_pk_add_f32 v[56:57], v[56:57], v[244:245]
	v_pk_add_f32 v[58:59], v[58:59], v[246:247]
	v_mul_f32_e32 v56, 0xbfb8aa3b, v56
	v_mul_f32_e32 v57, 0xbfb8aa3b, v57
	v_mul_f32_e32 v58, 0xbfb8aa3b, v58
	v_mul_f32_e32 v59, 0xbfb8aa3b, v59
	v_exp_f32_e32 v56, v56
	v_exp_f32_e32 v57, v57
	v_exp_f32_e32 v58, v58
	v_exp_f32_e32 v59, v59
	v_lshlrev_b32_e32 v134, 16, v146
	v_and_b32_e32 v135, 0xffff0000, v146
	v_lshlrev_b32_e32 v140, 16, v147
	v_and_b32_e32 v141, 0xffff0000, v147
	v_add_f32_e32 v56, 1.0, v56
	v_add_f32_e32 v57, 1.0, v57
	v_add_f32_e32 v58, 1.0, v58
	v_add_f32_e32 v59, 1.0, v59
	v_rcp_f32_e32 v56, v56
	v_rcp_f32_e32 v57, v57
	v_rcp_f32_e32 v58, v58
	v_rcp_f32_e32 v59, v59
	s_nop 0
	v_pk_mul_f32 v[56:57], v[56:57], v[134:135]
	v_pk_mul_f32 v[58:59], v[58:59], v[140:141]
	v_cvt_pk_bf16_f32 v134, v56, v57
	v_cvt_pk_bf16_f32 v135, v58, v59
	global_store_dwordx2 v239, v[134:135], s[96:97] offset:32
	s_waitcnt vmcnt(31)
	v_pk_add_f32 v[52:53], v[52:53], v[252:253]
	v_pk_add_f32 v[54:55], v[54:55], v[254:255]
	v_mul_f32_e32 v52, 0xbfb8aa3b, v52
	v_mul_f32_e32 v53, 0xbfb8aa3b, v53
	v_mul_f32_e32 v54, 0xbfb8aa3b, v54
	v_mul_f32_e32 v55, 0xbfb8aa3b, v55
	v_exp_f32_e32 v52, v52
	v_exp_f32_e32 v53, v53
	v_exp_f32_e32 v54, v54
	v_exp_f32_e32 v55, v55
	v_lshlrev_b32_e32 v134, 16, v148
	v_and_b32_e32 v135, 0xffff0000, v148
	v_lshlrev_b32_e32 v140, 16, v149
	v_and_b32_e32 v141, 0xffff0000, v149
	v_add_f32_e32 v52, 1.0, v52
	v_add_f32_e32 v53, 1.0, v53
	v_add_f32_e32 v54, 1.0, v54
	v_add_f32_e32 v55, 1.0, v55
	v_rcp_f32_e32 v52, v52
	v_rcp_f32_e32 v53, v53
	v_rcp_f32_e32 v54, v54
	v_rcp_f32_e32 v55, v55
	s_nop 0
	v_pk_mul_f32 v[52:53], v[52:53], v[134:135]
	v_pk_mul_f32 v[54:55], v[54:55], v[140:141]
	v_cvt_pk_bf16_f32 v134, v52, v53
	v_cvt_pk_bf16_f32 v135, v54, v55
	global_store_dwordx2 v239, v[134:135], s[96:97] offset:256
	s_waitcnt vmcnt(31)
	v_pk_add_f32 v[48:49], v[48:49], v[136:137]
	v_pk_add_f32 v[50:51], v[50:51], v[138:139]
	v_mul_f32_e32 v48, 0xbfb8aa3b, v48
	v_mul_f32_e32 v49, 0xbfb8aa3b, v49
	v_mul_f32_e32 v50, 0xbfb8aa3b, v50
	v_mul_f32_e32 v51, 0xbfb8aa3b, v51
	v_exp_f32_e32 v48, v48
	v_exp_f32_e32 v49, v49
	v_exp_f32_e32 v50, v50
	v_exp_f32_e32 v51, v51
	v_lshlrev_b32_e32 v134, 16, v150
	v_and_b32_e32 v135, 0xffff0000, v150
	v_lshlrev_b32_e32 v140, 16, v151
	v_and_b32_e32 v141, 0xffff0000, v151
	v_add_f32_e32 v48, 1.0, v48
	v_add_f32_e32 v49, 1.0, v49
	v_add_f32_e32 v50, 1.0, v50
	v_add_f32_e32 v51, 1.0, v51
	v_rcp_f32_e32 v48, v48
	v_rcp_f32_e32 v49, v49
	v_rcp_f32_e32 v50, v50
	v_rcp_f32_e32 v51, v51
	s_nop 0
	v_pk_mul_f32 v[48:49], v[48:49], v[134:135]
	v_pk_mul_f32 v[50:51], v[50:51], v[140:141]
	v_cvt_pk_bf16_f32 v134, v48, v49
	v_cvt_pk_bf16_f32 v135, v50, v51
	global_store_dwordx2 v239, v[134:135], s[96:97] offset:288
	v_add_u32_e32 v239, 0x8000, v239
	s_waitcnt vmcnt(31)
	v_pk_add_f32 v[44:45], v[44:45], v[240:241]
	v_pk_add_f32 v[46:47], v[46:47], v[242:243]
	v_mul_f32_e32 v44, 0xbfb8aa3b, v44
	v_mul_f32_e32 v45, 0xbfb8aa3b, v45
	v_mul_f32_e32 v46, 0xbfb8aa3b, v46
	v_mul_f32_e32 v47, 0xbfb8aa3b, v47
	v_exp_f32_e32 v44, v44
	v_exp_f32_e32 v45, v45
	v_exp_f32_e32 v46, v46
	v_exp_f32_e32 v47, v47
	v_lshlrev_b32_e32 v134, 16, v152
	v_and_b32_e32 v135, 0xffff0000, v152
	v_lshlrev_b32_e32 v140, 16, v153
	v_and_b32_e32 v141, 0xffff0000, v153
	v_add_f32_e32 v44, 1.0, v44
	v_add_f32_e32 v45, 1.0, v45
	v_add_f32_e32 v46, 1.0, v46
	v_add_f32_e32 v47, 1.0, v47
	v_rcp_f32_e32 v44, v44
	v_rcp_f32_e32 v45, v45
	v_rcp_f32_e32 v46, v46
	v_rcp_f32_e32 v47, v47
	s_nop 0
	v_pk_mul_f32 v[44:45], v[44:45], v[134:135]
	v_pk_mul_f32 v[46:47], v[46:47], v[140:141]
	v_cvt_pk_bf16_f32 v134, v44, v45
	v_cvt_pk_bf16_f32 v135, v46, v47
	global_store_dwordx2 v239, v[134:135], s[96:97]
	s_waitcnt vmcnt(31)
	v_pk_add_f32 v[40:41], v[40:41], v[244:245]
	v_pk_add_f32 v[42:43], v[42:43], v[246:247]
	v_mul_f32_e32 v40, 0xbfb8aa3b, v40
	v_mul_f32_e32 v41, 0xbfb8aa3b, v41
	v_mul_f32_e32 v42, 0xbfb8aa3b, v42
	v_mul_f32_e32 v43, 0xbfb8aa3b, v43
	v_exp_f32_e32 v40, v40
	v_exp_f32_e32 v41, v41
	v_exp_f32_e32 v42, v42
	v_exp_f32_e32 v43, v43
	v_lshlrev_b32_e32 v134, 16, v154
	v_and_b32_e32 v135, 0xffff0000, v154
	v_lshlrev_b32_e32 v140, 16, v155
	v_and_b32_e32 v141, 0xffff0000, v155
	v_add_f32_e32 v40, 1.0, v40
	v_add_f32_e32 v41, 1.0, v41
	v_add_f32_e32 v42, 1.0, v42
	v_add_f32_e32 v43, 1.0, v43
	v_rcp_f32_e32 v40, v40
	v_rcp_f32_e32 v41, v41
	v_rcp_f32_e32 v42, v42
	v_rcp_f32_e32 v43, v43
	s_nop 0
	v_pk_mul_f32 v[40:41], v[40:41], v[134:135]
	v_pk_mul_f32 v[42:43], v[42:43], v[140:141]
	v_cvt_pk_bf16_f32 v134, v40, v41
	v_cvt_pk_bf16_f32 v135, v42, v43
	global_store_dwordx2 v239, v[134:135], s[96:97] offset:32
	s_waitcnt vmcnt(31)
	v_pk_add_f32 v[36:37], v[36:37], v[252:253]
	v_pk_add_f32 v[38:39], v[38:39], v[254:255]
	v_mul_f32_e32 v36, 0xbfb8aa3b, v36
	v_mul_f32_e32 v37, 0xbfb8aa3b, v37
	v_mul_f32_e32 v38, 0xbfb8aa3b, v38
	v_mul_f32_e32 v39, 0xbfb8aa3b, v39
	v_exp_f32_e32 v36, v36
	v_exp_f32_e32 v37, v37
	v_exp_f32_e32 v38, v38
	v_exp_f32_e32 v39, v39
	v_lshlrev_b32_e32 v134, 16, v156
	v_and_b32_e32 v135, 0xffff0000, v156
	v_lshlrev_b32_e32 v140, 16, v157
	v_and_b32_e32 v141, 0xffff0000, v157
	v_add_f32_e32 v36, 1.0, v36
	v_add_f32_e32 v37, 1.0, v37
	v_add_f32_e32 v38, 1.0, v38
	v_add_f32_e32 v39, 1.0, v39
	v_rcp_f32_e32 v36, v36
	v_rcp_f32_e32 v37, v37
	v_rcp_f32_e32 v38, v38
	v_rcp_f32_e32 v39, v39
	s_nop 0
	v_pk_mul_f32 v[36:37], v[36:37], v[134:135]
	v_pk_mul_f32 v[38:39], v[38:39], v[140:141]
	v_cvt_pk_bf16_f32 v134, v36, v37
	v_cvt_pk_bf16_f32 v135, v38, v39
	global_store_dwordx2 v239, v[134:135], s[96:97] offset:256
	s_waitcnt vmcnt(31)
	v_pk_add_f32 v[32:33], v[32:33], v[136:137]
	v_pk_add_f32 v[34:35], v[34:35], v[138:139]
	v_mul_f32_e32 v32, 0xbfb8aa3b, v32
	v_mul_f32_e32 v33, 0xbfb8aa3b, v33
	v_mul_f32_e32 v34, 0xbfb8aa3b, v34
	v_mul_f32_e32 v35, 0xbfb8aa3b, v35
	v_exp_f32_e32 v32, v32
	v_exp_f32_e32 v33, v33
	v_exp_f32_e32 v34, v34
	v_exp_f32_e32 v35, v35
	v_lshlrev_b32_e32 v134, 16, v158
	v_and_b32_e32 v135, 0xffff0000, v158
	v_lshlrev_b32_e32 v140, 16, v159
	v_and_b32_e32 v141, 0xffff0000, v159
	v_add_f32_e32 v32, 1.0, v32
	v_add_f32_e32 v33, 1.0, v33
	v_add_f32_e32 v34, 1.0, v34
	v_add_f32_e32 v35, 1.0, v35
	v_rcp_f32_e32 v32, v32
	v_rcp_f32_e32 v33, v33
	v_rcp_f32_e32 v34, v34
	v_rcp_f32_e32 v35, v35
	s_nop 0
	v_pk_mul_f32 v[32:33], v[32:33], v[134:135]
	v_pk_mul_f32 v[34:35], v[34:35], v[140:141]
	v_cvt_pk_bf16_f32 v134, v32, v33
	v_cvt_pk_bf16_f32 v135, v34, v35
	global_store_dwordx2 v239, v[134:135], s[96:97] offset:288
	v_add_u32_e32 v239, 0x8000, v239
	s_waitcnt vmcnt(31)
	v_pk_add_f32 v[28:29], v[28:29], v[240:241]
	v_pk_add_f32 v[30:31], v[30:31], v[242:243]
	v_mul_f32_e32 v28, 0xbfb8aa3b, v28
	v_mul_f32_e32 v29, 0xbfb8aa3b, v29
	v_mul_f32_e32 v30, 0xbfb8aa3b, v30
	v_mul_f32_e32 v31, 0xbfb8aa3b, v31
	v_exp_f32_e32 v28, v28
	v_exp_f32_e32 v29, v29
	v_exp_f32_e32 v30, v30
	v_exp_f32_e32 v31, v31
	v_lshlrev_b32_e32 v134, 16, v160
	v_and_b32_e32 v135, 0xffff0000, v160
	v_lshlrev_b32_e32 v140, 16, v161
	v_and_b32_e32 v141, 0xffff0000, v161
	v_add_f32_e32 v28, 1.0, v28
	v_add_f32_e32 v29, 1.0, v29
	v_add_f32_e32 v30, 1.0, v30
	v_add_f32_e32 v31, 1.0, v31
	v_rcp_f32_e32 v28, v28
	v_rcp_f32_e32 v29, v29
	v_rcp_f32_e32 v30, v30
	v_rcp_f32_e32 v31, v31
	s_nop 0
	v_pk_mul_f32 v[28:29], v[28:29], v[134:135]
	v_pk_mul_f32 v[30:31], v[30:31], v[140:141]
	v_cvt_pk_bf16_f32 v134, v28, v29
	v_cvt_pk_bf16_f32 v135, v30, v31
	global_store_dwordx2 v239, v[134:135], s[96:97]
	s_waitcnt vmcnt(31)
	v_pk_add_f32 v[24:25], v[24:25], v[244:245]
	v_pk_add_f32 v[26:27], v[26:27], v[246:247]
	v_mul_f32_e32 v24, 0xbfb8aa3b, v24
	v_mul_f32_e32 v25, 0xbfb8aa3b, v25
	v_mul_f32_e32 v26, 0xbfb8aa3b, v26
	v_mul_f32_e32 v27, 0xbfb8aa3b, v27
	v_exp_f32_e32 v24, v24
	v_exp_f32_e32 v25, v25
	v_exp_f32_e32 v26, v26
	v_exp_f32_e32 v27, v27
	v_lshlrev_b32_e32 v134, 16, v162
	v_and_b32_e32 v135, 0xffff0000, v162
	v_lshlrev_b32_e32 v140, 16, v163
	v_and_b32_e32 v141, 0xffff0000, v163
	v_add_f32_e32 v24, 1.0, v24
	v_add_f32_e32 v25, 1.0, v25
	v_add_f32_e32 v26, 1.0, v26
	v_add_f32_e32 v27, 1.0, v27
	v_rcp_f32_e32 v24, v24
	v_rcp_f32_e32 v25, v25
	v_rcp_f32_e32 v26, v26
	v_rcp_f32_e32 v27, v27
	s_nop 0
	v_pk_mul_f32 v[24:25], v[24:25], v[134:135]
	v_pk_mul_f32 v[26:27], v[26:27], v[140:141]
	v_cvt_pk_bf16_f32 v134, v24, v25
	v_cvt_pk_bf16_f32 v135, v26, v27
	global_store_dwordx2 v239, v[134:135], s[96:97] offset:32
	s_waitcnt vmcnt(31)
	v_pk_add_f32 v[20:21], v[20:21], v[252:253]
	v_pk_add_f32 v[22:23], v[22:23], v[254:255]
	v_mul_f32_e32 v20, 0xbfb8aa3b, v20
	v_mul_f32_e32 v21, 0xbfb8aa3b, v21
	v_mul_f32_e32 v22, 0xbfb8aa3b, v22
	v_mul_f32_e32 v23, 0xbfb8aa3b, v23
	v_exp_f32_e32 v20, v20
	v_exp_f32_e32 v21, v21
	v_exp_f32_e32 v22, v22
	v_exp_f32_e32 v23, v23
	v_lshlrev_b32_e32 v134, 16, v164
	v_and_b32_e32 v135, 0xffff0000, v164
	v_lshlrev_b32_e32 v140, 16, v165
	v_and_b32_e32 v141, 0xffff0000, v165
	v_add_f32_e32 v20, 1.0, v20
	v_add_f32_e32 v21, 1.0, v21
	v_add_f32_e32 v22, 1.0, v22
	v_add_f32_e32 v23, 1.0, v23
	v_rcp_f32_e32 v20, v20
	v_rcp_f32_e32 v21, v21
	v_rcp_f32_e32 v22, v22
	v_rcp_f32_e32 v23, v23
	s_nop 0
	v_pk_mul_f32 v[20:21], v[20:21], v[134:135]
	v_pk_mul_f32 v[22:23], v[22:23], v[140:141]
	v_cvt_pk_bf16_f32 v134, v20, v21
	v_cvt_pk_bf16_f32 v135, v22, v23
	global_store_dwordx2 v239, v[134:135], s[96:97] offset:256
	s_waitcnt vmcnt(31)
	v_pk_add_f32 v[16:17], v[16:17], v[136:137]
	v_pk_add_f32 v[18:19], v[18:19], v[138:139]
	v_mul_f32_e32 v16, 0xbfb8aa3b, v16
	v_mul_f32_e32 v17, 0xbfb8aa3b, v17
	v_mul_f32_e32 v18, 0xbfb8aa3b, v18
	v_mul_f32_e32 v19, 0xbfb8aa3b, v19
	v_exp_f32_e32 v16, v16
	v_exp_f32_e32 v17, v17
	v_exp_f32_e32 v18, v18
	v_exp_f32_e32 v19, v19
	v_lshlrev_b32_e32 v134, 16, v166
	v_and_b32_e32 v135, 0xffff0000, v166
	v_lshlrev_b32_e32 v140, 16, v167
	v_and_b32_e32 v141, 0xffff0000, v167
	v_add_f32_e32 v16, 1.0, v16
	v_add_f32_e32 v17, 1.0, v17
	v_add_f32_e32 v18, 1.0, v18
	v_add_f32_e32 v19, 1.0, v19
	v_rcp_f32_e32 v16, v16
	v_rcp_f32_e32 v17, v17
	v_rcp_f32_e32 v18, v18
	v_rcp_f32_e32 v19, v19
	s_nop 0
	v_pk_mul_f32 v[16:17], v[16:17], v[134:135]
	v_pk_mul_f32 v[18:19], v[18:19], v[140:141]
	v_cvt_pk_bf16_f32 v134, v16, v17
	v_cvt_pk_bf16_f32 v135, v18, v19
	global_store_dwordx2 v239, v[134:135], s[96:97] offset:288
	v_add_u32_e32 v239, 0x8000, v239
	s_waitcnt vmcnt(31)
	v_pk_add_f32 v[12:13], v[12:13], v[240:241]
	v_pk_add_f32 v[14:15], v[14:15], v[242:243]
	v_mul_f32_e32 v12, 0xbfb8aa3b, v12
	v_mul_f32_e32 v13, 0xbfb8aa3b, v13
	v_mul_f32_e32 v14, 0xbfb8aa3b, v14
	v_mul_f32_e32 v15, 0xbfb8aa3b, v15
	v_exp_f32_e32 v12, v12
	v_exp_f32_e32 v13, v13
	v_exp_f32_e32 v14, v14
	v_exp_f32_e32 v15, v15
	v_lshlrev_b32_e32 v134, 16, v168
	v_and_b32_e32 v135, 0xffff0000, v168
	v_lshlrev_b32_e32 v140, 16, v169
	v_and_b32_e32 v141, 0xffff0000, v169
	v_add_f32_e32 v12, 1.0, v12
	v_add_f32_e32 v13, 1.0, v13
	v_add_f32_e32 v14, 1.0, v14
	v_add_f32_e32 v15, 1.0, v15
	v_rcp_f32_e32 v12, v12
	v_rcp_f32_e32 v13, v13
	v_rcp_f32_e32 v14, v14
	v_rcp_f32_e32 v15, v15
	s_nop 0
	v_pk_mul_f32 v[12:13], v[12:13], v[134:135]
	v_pk_mul_f32 v[14:15], v[14:15], v[140:141]
	v_cvt_pk_bf16_f32 v134, v12, v13
	v_cvt_pk_bf16_f32 v135, v14, v15
	global_store_dwordx2 v239, v[134:135], s[96:97]
	s_waitcnt vmcnt(31)
	v_pk_add_f32 v[8:9], v[8:9], v[244:245]
	v_pk_add_f32 v[10:11], v[10:11], v[246:247]
	v_mul_f32_e32 v8, 0xbfb8aa3b, v8
	v_mul_f32_e32 v9, 0xbfb8aa3b, v9
	v_mul_f32_e32 v10, 0xbfb8aa3b, v10
	v_mul_f32_e32 v11, 0xbfb8aa3b, v11
	v_exp_f32_e32 v8, v8
	v_exp_f32_e32 v9, v9
	v_exp_f32_e32 v10, v10
	v_exp_f32_e32 v11, v11
	v_lshlrev_b32_e32 v134, 16, v170
	v_and_b32_e32 v135, 0xffff0000, v170
	v_lshlrev_b32_e32 v140, 16, v171
	v_and_b32_e32 v141, 0xffff0000, v171
	v_add_f32_e32 v8, 1.0, v8
	v_add_f32_e32 v9, 1.0, v9
	v_add_f32_e32 v10, 1.0, v10
	v_add_f32_e32 v11, 1.0, v11
	v_rcp_f32_e32 v8, v8
	v_rcp_f32_e32 v9, v9
	v_rcp_f32_e32 v10, v10
	v_rcp_f32_e32 v11, v11
	s_nop 0
	v_pk_mul_f32 v[8:9], v[8:9], v[134:135]
	v_pk_mul_f32 v[10:11], v[10:11], v[140:141]
	v_cvt_pk_bf16_f32 v134, v8, v9
	v_cvt_pk_bf16_f32 v135, v10, v11
	global_store_dwordx2 v239, v[134:135], s[96:97] offset:32
	s_waitcnt vmcnt(31)
	v_pk_add_f32 v[4:5], v[4:5], v[252:253]
	v_pk_add_f32 v[6:7], v[6:7], v[254:255]
	v_mul_f32_e32 v4, 0xbfb8aa3b, v4
	v_mul_f32_e32 v5, 0xbfb8aa3b, v5
	v_mul_f32_e32 v6, 0xbfb8aa3b, v6
	v_mul_f32_e32 v7, 0xbfb8aa3b, v7
	v_exp_f32_e32 v4, v4
	v_exp_f32_e32 v5, v5
	v_exp_f32_e32 v6, v6
	v_exp_f32_e32 v7, v7
	v_lshlrev_b32_e32 v134, 16, v172
	v_and_b32_e32 v135, 0xffff0000, v172
	v_lshlrev_b32_e32 v140, 16, v173
	v_and_b32_e32 v141, 0xffff0000, v173
	v_add_f32_e32 v4, 1.0, v4
	v_add_f32_e32 v5, 1.0, v5
	v_add_f32_e32 v6, 1.0, v6
	v_add_f32_e32 v7, 1.0, v7
	v_rcp_f32_e32 v4, v4
	v_rcp_f32_e32 v5, v5
	v_rcp_f32_e32 v6, v6
	v_rcp_f32_e32 v7, v7
	s_nop 0
	v_pk_mul_f32 v[4:5], v[4:5], v[134:135]
	v_pk_mul_f32 v[6:7], v[6:7], v[140:141]
	v_cvt_pk_bf16_f32 v134, v4, v5
	v_cvt_pk_bf16_f32 v135, v6, v7
	global_store_dwordx2 v239, v[134:135], s[96:97] offset:256
	s_waitcnt vmcnt(31)
	v_pk_add_f32 v[0:1], v[0:1], v[136:137]
	v_pk_add_f32 v[2:3], v[2:3], v[138:139]
	v_mul_f32_e32 v0, 0xbfb8aa3b, v0
	v_mul_f32_e32 v1, 0xbfb8aa3b, v1
	v_mul_f32_e32 v2, 0xbfb8aa3b, v2
	v_mul_f32_e32 v3, 0xbfb8aa3b, v3
	v_exp_f32_e32 v0, v0
	v_exp_f32_e32 v1, v1
	v_exp_f32_e32 v2, v2
	v_exp_f32_e32 v3, v3
	v_lshlrev_b32_e32 v134, 16, v174
	v_and_b32_e32 v135, 0xffff0000, v174
	v_lshlrev_b32_e32 v140, 16, v175
	v_and_b32_e32 v141, 0xffff0000, v175
	v_add_f32_e32 v0, 1.0, v0
	v_add_f32_e32 v1, 1.0, v1
	v_add_f32_e32 v2, 1.0, v2
	v_add_f32_e32 v3, 1.0, v3
	v_rcp_f32_e32 v0, v0
	v_rcp_f32_e32 v1, v1
	v_rcp_f32_e32 v2, v2
	v_rcp_f32_e32 v3, v3
	s_nop 0
	v_pk_mul_f32 v[0:1], v[0:1], v[134:135]
	v_pk_mul_f32 v[2:3], v[2:3], v[140:141]
	v_cvt_pk_bf16_f32 v134, v0, v1
	v_cvt_pk_bf16_f32 v135, v2, v3
	global_store_dwordx2 v239, v[134:135], s[96:97] offset:288
	s_and_b64 vcc, exec, s[40:41]
	s_cbranch_vccz .LBB0_925
	s_waitcnt vmcnt(0)
	s_cmpk_gt_u32 s22, 0xff
	s_cbranch_scc1 .LBB0_936
	s_barrier

.LBB0_1001:
	v_readlane_b32 s6, v249, 32
	v_readlane_b32 s7, v249, 33
	s_lshl_b64 s[6:7], s[6:7], 2
	v_and_b32_e32 v204, 15, v8
	s_waitcnt lgkmcnt(0)
	s_add_u32 s62, s4, s6
	v_bfe_u32 v205, v8, 4, 2
	v_lshlrev_b32_e32 v15, 6, v204
	v_lshlrev_b32_e32 v8, 2, v8
	s_addc_u32 s63, s5, s7
	s_and_b32 s64, s3, 3
	v_lshl_or_b32 v15, v205, 4, v15
	s_lshl_b32 s3, s56, 13
	v_and_b32_e32 v8, 32, v8
	s_add_i32 m0, s58, 0x18000
	v_lshl_add_u64 v[6:7], v[6:7], 0, s[24:25]
	v_bitop3_b32 v16, v15, s3, v8 bitop3:0xde
	s_lshl_b32 s3, s64, 12
	s_waitcnt vmcnt(4)
	s_barrier
	global_load_lds_dwordx4 v[6:7], off
	v_lshl_add_u64 v[4:5], v[4:5], 0, s[24:25]
	s_add_i32 m0, s58, 0x1a000
	s_add_i32 s65, s58, 0x8000
	s_add_i32 s66, s58, 0xa000
	global_load_lds_dwordx4 v[4:5], off
	v_lshl_add_u64 v[2:3], v[2:3], 0, s[24:25]
	s_mov_b32 m0, s65
	s_add_u32 s4, s42, 0x40080
	global_load_lds_dwordx4 v[2:3], off
	v_lshl_add_u64 v[0:1], v[0:1], 0, s[24:25]
	s_mov_b32 m0, s66
	s_addc_u32 s5, s43, 0
	global_load_lds_dwordx4 v[0:1], off
	s_add_i32 m0, s58, 0x1c000
	v_lshl_add_u64 v[0:1], s[4:5], 0, v[176:177]
	global_load_lds_dwordx4 v[0:1], off
	v_lshl_add_u64 v[0:1], s[4:5], 0, v[158:159]
	s_add_i32 m0, s58, 0x1e000
	v_bitop3_b32 v206, v15, s3, v8 bitop3:0xde
	global_load_lds_dwordx4 v[0:1], off
	s_not_b32 s3, s21
	v_readlane_b32 s4, v250, 18
	s_ashr_i32 s67, s21, 31
	s_add_i32 s3, s4, s3
	s_add_u32 s4, s96, 0x1734f800
	s_addc_u32 s5, s97, 0
	s_add_u32 s6, s96, 0x1735f800
	s_addc_u32 s7, s97, 0
	s_add_u32 s10, s96, 0x1736f800
	s_addc_u32 s11, s97, 0
	s_add_u32 s12, s96, 0x1737f800
	s_addc_u32 s13, s97, 0
	s_add_u32 s14, s96, 0x173cf800
	s_addc_u32 s15, s97, 0
	s_add_u32 s16, s96, 0x173df800
	s_addc_u32 s17, s97, 0
	s_add_u32 s18, s96, 0x173ef800
	s_addc_u32 s19, s97, 0
	s_add_u32 s22, s96, 0x173ff800
	s_addc_u32 s23, s97, 0
	s_ashr_i32 s38, s3, 31
	s_abs_i32 s3, s3
	v_readlane_b32 s28, v250, 14
	s_mul_hi_u32 s39, s3, s28
	v_readlane_b32 s28, v250, 13
	s_mul_i32 s44, s39, s28
	s_sub_i32 s3, s3, s44
	s_xor_b32 s38, s38, s81
	s_add_i32 s44, s39, 1
	s_sub_i32 s45, s3, s28
	v_lshlrev_b32_e32 v0, 14, v9
	s_cmp_ge_u32 s3, s28
	v_and_b32_e32 v0, 0xffff8000, v0
	s_cselect_b32 s39, s44, s39
	v_lshl_add_u32 v0, v10, 11, v0
	v_and_b32_e32 v1, 1, v9
	s_cselect_b32 s3, s45, s3
	s_add_i32 s44, s39, 1
	v_lshl_or_b32 v0, v1, 6, v0
	s_cmp_ge_u32 s3, s28
	v_lshl_add_u32 v160, v11, 1, v0
	v_lshlrev_b32_e32 v0, 14, v12
	s_cselect_b32 s3, s44, s39
	v_and_b32_e32 v0, 0xffff8000, v0
	s_waitcnt vmcnt(0)
	s_xor_b32 s3, s3, s38
	v_lshl_add_u32 v0, v13, 11, v0
	v_and_b32_e32 v1, 1, v12
	s_sub_i32 s3, s3, s38
	v_lshl_or_b32 v0, v1, 6, v0
	s_lshl_b32 s68, s3, 3
	v_mov_b32_e32 v161, v177
	v_lshl_add_u32 v162, v14, 1, v0
	v_mov_b32_e32 v163, v177
	s_mov_b32 s73, 0
	s_mov_b32 s3, 8
	v_add_u32_e32 v207, 0, v16
	v_readlane_b32 s28, v249, 18
	s_barrier
	s_branch .LBB0_1003

.LBB0_1021:
	s_add_i32 s77, s42, 2
	s_add_u32 s43, s40, 0xfffc0080
	s_addc_u32 s44, s41, -1
	s_add_i32 s78, 0, 0x10000
	v_add_u32_e32 v140, s78, v206
	ds_read_b128 v[128:131], v140
	ds_read_b128 v[132:135], v140 offset:1024
	ds_read_b128 v[136:139], v140 offset:2048
	ds_read_b128 v[140:143], v140 offset:3072
	s_cmp_eq_u32 s74, s42
	s_cselect_b32 s42, s73, s75
	s_cselect_b32 s45, s47, s44
	s_cselect_b32 s44, s54, s43
	s_cselect_b32 s43, s55, s76
	v_lshl_add_u64 v[156:157], s[40:41], 0, v[160:161]
	s_add_i32 m0, s58, 0xc000
	ds_read_b128 v[144:147], v207
	ds_read_b128 v[148:151], v207 offset:1024
	ds_read_b128 v[152:155], v207 offset:2048
	ds_read_b128 v[164:167], v207 offset:3072
	ds_read_b128 v[168:171], v207 offset:4096
	ds_read_b128 v[172:175], v207 offset:5120
	ds_read_b128 v[190:193], v207 offset:6144
	ds_read_b128 v[194:197], v207 offset:7168
	global_load_lds_dwordx4 v[156:157], off
	v_lshl_add_u64 v[156:157], s[40:41], 0, v[162:163]
	s_add_i32 m0, s58, 0xe000
	s_nop 0
	global_load_lds_dwordx4 v[156:157], off
	s_waitcnt lgkmcnt(8)
	s_waitcnt vmcnt(10)
	s_barrier
	s_waitcnt lgkmcnt(0)
	s_setprio 1
	s_waitcnt lgkmcnt(0)
	v_mfma_f32_16x16x32_bf16 v[124:127], v[128:131], v[144:147], v[124:127]
	v_mfma_f32_16x16x32_bf16 v[120:123], v[136:139], v[144:147], v[120:123]
	v_mfma_f32_16x16x32_bf16 v[116:119], v[128:131], v[152:155], v[116:119]
	v_mfma_f32_16x16x32_bf16 v[112:115], v[136:139], v[152:155], v[112:115]
	v_mfma_f32_16x16x32_bf16 v[108:111], v[128:131], v[168:171], v[108:111]
	v_mfma_f32_16x16x32_bf16 v[104:107], v[136:139], v[168:171], v[104:107]
	v_mfma_f32_16x16x32_bf16 v[100:103], v[128:131], v[190:193], v[100:103]
	v_mfma_f32_16x16x32_bf16 v[96:99], v[136:139], v[190:193], v[96:99]
	v_mfma_f32_16x16x32_bf16 v[124:127], v[132:135], v[148:151], v[124:127]
	v_mfma_f32_16x16x32_bf16 v[120:123], v[140:143], v[148:151], v[120:123]
	v_mfma_f32_16x16x32_bf16 v[116:119], v[132:135], v[164:167], v[116:119]
	v_mfma_f32_16x16x32_bf16 v[112:115], v[140:143], v[164:167], v[112:115]
	v_mfma_f32_16x16x32_bf16 v[108:111], v[132:135], v[172:175], v[108:111]
	v_mfma_f32_16x16x32_bf16 v[104:107], v[140:143], v[172:175], v[104:107]
	v_mfma_f32_16x16x32_bf16 v[100:103], v[132:135], v[194:197], v[100:103]
	v_mfma_f32_16x16x32_bf16 v[96:99], v[140:143], v[194:197], v[96:99]
	s_setprio 0
	s_barrier
	s_add_i32 s80, 0, 0x14000
	v_add_u32_e32 v156, s80, v206
	s_add_i32 s78, s78, s57
	ds_read_b128 v[198:201], v156
	ds_read_b128 v[208:211], v156 offset:1024
	ds_read_b128 v[212:215], v156 offset:2048
	ds_read_b128 v[216:219], v156 offset:3072
	v_lshl_add_u64 v[156:157], s[42:43], 0, v[176:177]
	s_mov_b32 m0, s78
	v_lshl_add_u64 v[202:203], s[42:43], 0, v[158:159]
	global_load_lds_dwordx4 v[156:157], off
	s_add_i32 m0, s78, 0x2000
	s_nop 0
	global_load_lds_dwordx4 v[202:203], off
	s_waitcnt vmcnt(10)
	s_barrier
	s_waitcnt lgkmcnt(0)
	s_setprio 1
	s_waitcnt lgkmcnt(0)
	v_mfma_f32_16x16x32_bf16 v[92:95], v[198:201], v[144:147], v[92:95]
	v_mfma_f32_16x16x32_bf16 v[88:91], v[212:215], v[144:147], v[88:91]
	v_mfma_f32_16x16x32_bf16 v[84:87], v[198:201], v[152:155], v[84:87]
	v_mfma_f32_16x16x32_bf16 v[80:83], v[212:215], v[152:155], v[80:83]
	v_mfma_f32_16x16x32_bf16 v[76:79], v[198:201], v[168:171], v[76:79]
	v_mfma_f32_16x16x32_bf16 v[72:75], v[212:215], v[168:171], v[72:75]
	v_mfma_f32_16x16x32_bf16 v[68:71], v[198:201], v[190:193], v[68:71]
	v_mfma_f32_16x16x32_bf16 v[64:67], v[212:215], v[190:193], v[64:67]
	v_mfma_f32_16x16x32_bf16 v[92:95], v[208:211], v[148:151], v[92:95]
	v_mfma_f32_16x16x32_bf16 v[88:91], v[216:219], v[148:151], v[88:91]
	v_mfma_f32_16x16x32_bf16 v[84:87], v[208:211], v[164:167], v[84:87]
	v_mfma_f32_16x16x32_bf16 v[80:83], v[216:219], v[164:167], v[80:83]
	v_mfma_f32_16x16x32_bf16 v[76:79], v[208:211], v[172:175], v[76:79]
	v_mfma_f32_16x16x32_bf16 v[72:75], v[216:219], v[172:175], v[72:75]
	v_mfma_f32_16x16x32_bf16 v[68:71], v[208:211], v[194:197], v[68:71]
	v_mfma_f32_16x16x32_bf16 v[64:67], v[216:219], v[194:197], v[64:67]
	s_setprio 0
	s_mov_b32 m0, s58
	v_lshl_add_u64 v[220:221], s[44:45], 0, v[176:177]
	s_barrier
	ds_read_b128 v[144:147], v207 offset:16384
	ds_read_b128 v[148:151], v207 offset:17408
	ds_read_b128 v[152:155], v207 offset:18432
	ds_read_b128 v[164:167], v207 offset:19456
	ds_read_b128 v[168:171], v207 offset:20480
	ds_read_b128 v[172:175], v207 offset:21504
	ds_read_b128 v[190:193], v207 offset:22528
	ds_read_b128 v[194:197], v207 offset:23552
	global_load_lds_dwordx4 v[220:221], off
	v_lshl_add_u64 v[222:223], s[44:45], 0, v[158:159]
	s_mov_b32 m0, s59
	s_nop 0
	global_load_lds_dwordx4 v[222:223], off
	s_barrier
	s_waitcnt lgkmcnt(0)
	s_setprio 1
	s_waitcnt lgkmcnt(0)
	v_mfma_f32_16x16x32_bf16 v[60:63], v[128:131], v[144:147], v[60:63]
	v_mfma_f32_16x16x32_bf16 v[56:59], v[136:139], v[144:147], v[56:59]
	v_mfma_f32_16x16x32_bf16 v[52:55], v[128:131], v[152:155], v[52:55]
	v_mfma_f32_16x16x32_bf16 v[48:51], v[136:139], v[152:155], v[48:51]
	v_mfma_f32_16x16x32_bf16 v[44:47], v[128:131], v[168:171], v[44:47]
	v_mfma_f32_16x16x32_bf16 v[40:43], v[136:139], v[168:171], v[40:43]
	v_mfma_f32_16x16x32_bf16 v[36:39], v[128:131], v[190:193], v[36:39]
	v_mfma_f32_16x16x32_bf16 v[32:35], v[136:139], v[190:193], v[32:35]
	v_mfma_f32_16x16x32_bf16 v[60:63], v[132:135], v[148:151], v[60:63]
	v_mfma_f32_16x16x32_bf16 v[56:59], v[140:143], v[148:151], v[56:59]
	v_mfma_f32_16x16x32_bf16 v[52:55], v[132:135], v[164:167], v[52:55]
	v_mfma_f32_16x16x32_bf16 v[48:51], v[140:143], v[164:167], v[48:51]
	v_mfma_f32_16x16x32_bf16 v[44:47], v[132:135], v[172:175], v[44:47]
	v_mfma_f32_16x16x32_bf16 v[40:43], v[140:143], v[172:175], v[40:43]
	v_mfma_f32_16x16x32_bf16 v[36:39], v[132:135], v[194:197], v[36:39]
	v_mfma_f32_16x16x32_bf16 v[32:35], v[140:143], v[194:197], v[32:35]
	s_setprio 0
	s_barrier
	s_add_u32 s78, s42, 0x40000
	s_addc_u32 s79, s43, 0
	s_add_i32 s80, s80, s57
	v_lshl_add_u64 v[128:129], s[78:79], 0, v[176:177]
	s_mov_b32 m0, s80
	s_nop 0
	global_load_lds_dwordx4 v[128:129], off
	v_lshl_add_u64 v[128:129], s[78:79], 0, v[158:159]
	s_add_i32 m0, s80, 0x2000
	s_nop 0
	global_load_lds_dwordx4 v[128:129], off
	s_waitcnt vmcnt(10)
	s_barrier
	s_setprio 1
	v_mfma_f32_16x16x32_bf16 v[28:31], v[198:201], v[144:147], v[28:31]
	v_mfma_f32_16x16x32_bf16 v[24:27], v[212:215], v[144:147], v[24:27]
	v_mfma_f32_16x16x32_bf16 v[20:23], v[198:201], v[152:155], v[20:23]
	v_mfma_f32_16x16x32_bf16 v[16:19], v[212:215], v[152:155], v[16:19]
	v_mfma_f32_16x16x32_bf16 v[12:15], v[198:201], v[168:171], v[12:15]
	v_mfma_f32_16x16x32_bf16 v[8:11], v[212:215], v[168:171], v[8:11]
	v_mfma_f32_16x16x32_bf16 v[4:7], v[198:201], v[190:193], v[4:7]
	v_mfma_f32_16x16x32_bf16 v[0:3], v[212:215], v[190:193], v[0:3]
	v_mfma_f32_16x16x32_bf16 v[28:31], v[208:211], v[148:151], v[28:31]
	v_mfma_f32_16x16x32_bf16 v[24:27], v[216:219], v[148:151], v[24:27]
	v_mfma_f32_16x16x32_bf16 v[20:23], v[208:211], v[164:167], v[20:23]
	v_mfma_f32_16x16x32_bf16 v[16:19], v[216:219], v[164:167], v[16:19]
	v_mfma_f32_16x16x32_bf16 v[12:15], v[208:211], v[172:175], v[12:15]
	v_mfma_f32_16x16x32_bf16 v[8:11], v[216:219], v[172:175], v[8:11]
	v_mfma_f32_16x16x32_bf16 v[4:7], v[208:211], v[194:197], v[4:7]
	v_mfma_f32_16x16x32_bf16 v[0:3], v[216:219], v[194:197], v[0:3]
	s_setprio 0
	s_add_i32 s78, 0, 0x18000
	v_add_u32_e32 v140, s78, v206
	s_barrier
	ds_read_b128 v[128:131], v140
	ds_read_b128 v[132:135], v140 offset:1024
	ds_read_b128 v[136:139], v140 offset:2048
	ds_read_b128 v[140:143], v140 offset:3072
	s_add_u32 s44, s44, 0x40000
	s_addc_u32 s45, s45, 0
	s_mov_b32 m0, s60
	v_lshl_add_u64 v[198:199], s[44:45], 0, v[176:177]
	ds_read_b128 v[144:147], v207 offset:32768
	ds_read_b128 v[148:151], v207 offset:33792
	ds_read_b128 v[152:155], v207 offset:34816
	ds_read_b128 v[164:167], v207 offset:35840
	ds_read_b128 v[168:171], v207 offset:36864
	ds_read_b128 v[172:175], v207 offset:37888
	ds_read_b128 v[190:193], v207 offset:38912
	ds_read_b128 v[194:197], v207 offset:39936
	global_load_lds_dwordx4 v[198:199], off
	v_lshl_add_u64 v[198:199], s[44:45], 0, v[158:159]
	s_mov_b32 m0, s61
	s_nop 0
	global_load_lds_dwordx4 v[198:199], off
	s_waitcnt lgkmcnt(8)
	s_waitcnt vmcnt(10)
	s_barrier
	s_waitcnt lgkmcnt(0)
	s_setprio 1
	s_waitcnt lgkmcnt(0)
	v_mfma_f32_16x16x32_bf16 v[124:127], v[128:131], v[144:147], v[124:127]
	v_mfma_f32_16x16x32_bf16 v[120:123], v[136:139], v[144:147], v[120:123]
	v_mfma_f32_16x16x32_bf16 v[116:119], v[128:131], v[152:155], v[116:119]
	v_mfma_f32_16x16x32_bf16 v[112:115], v[136:139], v[152:155], v[112:115]
	v_mfma_f32_16x16x32_bf16 v[108:111], v[128:131], v[168:171], v[108:111]
	v_mfma_f32_16x16x32_bf16 v[104:107], v[136:139], v[168:171], v[104:107]
	v_mfma_f32_16x16x32_bf16 v[100:103], v[128:131], v[190:193], v[100:103]
	v_mfma_f32_16x16x32_bf16 v[96:99], v[136:139], v[190:193], v[96:99]
	v_mfma_f32_16x16x32_bf16 v[124:127], v[132:135], v[148:151], v[124:127]
	v_mfma_f32_16x16x32_bf16 v[120:123], v[140:143], v[148:151], v[120:123]
	v_mfma_f32_16x16x32_bf16 v[116:119], v[132:135], v[164:167], v[116:119]
	v_mfma_f32_16x16x32_bf16 v[112:115], v[140:143], v[164:167], v[112:115]
	v_mfma_f32_16x16x32_bf16 v[108:111], v[132:135], v[172:175], v[108:111]
	v_mfma_f32_16x16x32_bf16 v[104:107], v[140:143], v[172:175], v[104:107]
	v_mfma_f32_16x16x32_bf16 v[100:103], v[132:135], v[194:197], v[100:103]
	v_mfma_f32_16x16x32_bf16 v[96:99], v[140:143], v[194:197], v[96:99]
	s_setprio 0
	s_barrier
	s_add_i32 s44, 0, 0x1c000
	s_add_i32 s45, s78, s57
	v_add_u32_e32 v216, s44, v206
	v_lshl_add_u64 v[156:157], v[156:157], 0, s[24:25]
	s_mov_b32 m0, s45
	ds_read_b128 v[198:201], v216
	ds_read_b128 v[208:211], v216 offset:1024
	ds_read_b128 v[212:215], v216 offset:2048
	ds_read_b128 v[216:219], v216 offset:3072
	global_load_lds_dwordx4 v[156:157], off
	v_lshl_add_u64 v[156:157], v[202:203], 0, s[24:25]
	s_add_i32 m0, s45, 0x2000
	s_nop 0
	global_load_lds_dwordx4 v[156:157], off
	s_waitcnt vmcnt(10)
	s_barrier
	s_waitcnt lgkmcnt(0)
	s_setprio 1
	s_waitcnt lgkmcnt(0)
	v_mfma_f32_16x16x32_bf16 v[92:95], v[198:201], v[144:147], v[92:95]
	v_mfma_f32_16x16x32_bf16 v[88:91], v[212:215], v[144:147], v[88:91]
	v_mfma_f32_16x16x32_bf16 v[84:87], v[198:201], v[152:155], v[84:87]
	v_mfma_f32_16x16x32_bf16 v[80:83], v[212:215], v[152:155], v[80:83]
	v_mfma_f32_16x16x32_bf16 v[76:79], v[198:201], v[168:171], v[76:79]
	v_mfma_f32_16x16x32_bf16 v[72:75], v[212:215], v[168:171], v[72:75]
	v_mfma_f32_16x16x32_bf16 v[68:71], v[198:201], v[190:193], v[68:71]
	v_mfma_f32_16x16x32_bf16 v[64:67], v[212:215], v[190:193], v[64:67]
	v_mfma_f32_16x16x32_bf16 v[92:95], v[208:211], v[148:151], v[92:95]
	v_mfma_f32_16x16x32_bf16 v[88:91], v[216:219], v[148:151], v[88:91]
	v_mfma_f32_16x16x32_bf16 v[84:87], v[208:211], v[164:167], v[84:87]
	v_mfma_f32_16x16x32_bf16 v[80:83], v[216:219], v[164:167], v[80:83]
	v_mfma_f32_16x16x32_bf16 v[76:79], v[208:211], v[172:175], v[76:79]
	v_mfma_f32_16x16x32_bf16 v[72:75], v[216:219], v[172:175], v[72:75]
	v_mfma_f32_16x16x32_bf16 v[68:71], v[208:211], v[194:197], v[68:71]
	v_mfma_f32_16x16x32_bf16 v[64:67], v[216:219], v[194:197], v[64:67]
	s_setprio 0
	s_mov_b32 m0, s65
	v_lshl_add_u64 v[156:157], v[220:221], 0, s[24:25]
	s_barrier
	ds_read_b128 v[144:147], v207 offset:49152
	ds_read_b128 v[148:151], v207 offset:50176
	ds_read_b128 v[152:155], v207 offset:51200
	ds_read_b128 v[164:167], v207 offset:52224
	ds_read_b128 v[168:171], v207 offset:53248
	ds_read_b128 v[172:175], v207 offset:54272
	ds_read_b128 v[190:193], v207 offset:55296
	ds_read_b128 v[194:197], v207 offset:56320
	global_load_lds_dwordx4 v[156:157], off
	v_lshl_add_u64 v[156:157], v[222:223], 0, s[24:25]
	s_mov_b32 m0, s66
	s_nop 0
	global_load_lds_dwordx4 v[156:157], off
	s_barrier
	s_waitcnt lgkmcnt(0)
	s_setprio 1
	s_waitcnt lgkmcnt(0)
	v_mfma_f32_16x16x32_bf16 v[60:63], v[128:131], v[144:147], v[60:63]
	v_mfma_f32_16x16x32_bf16 v[56:59], v[136:139], v[144:147], v[56:59]
	v_mfma_f32_16x16x32_bf16 v[52:55], v[128:131], v[152:155], v[52:55]
	v_mfma_f32_16x16x32_bf16 v[48:51], v[136:139], v[152:155], v[48:51]
	v_mfma_f32_16x16x32_bf16 v[44:47], v[128:131], v[168:171], v[44:47]
	v_mfma_f32_16x16x32_bf16 v[40:43], v[136:139], v[168:171], v[40:43]
	v_mfma_f32_16x16x32_bf16 v[36:39], v[128:131], v[190:193], v[36:39]
	v_mfma_f32_16x16x32_bf16 v[32:35], v[136:139], v[190:193], v[32:35]
	v_mfma_f32_16x16x32_bf16 v[60:63], v[132:135], v[148:151], v[60:63]
	v_mfma_f32_16x16x32_bf16 v[56:59], v[140:143], v[148:151], v[56:59]
	v_mfma_f32_16x16x32_bf16 v[52:55], v[132:135], v[164:167], v[52:55]
	v_mfma_f32_16x16x32_bf16 v[48:51], v[140:143], v[164:167], v[48:51]
	v_mfma_f32_16x16x32_bf16 v[44:47], v[132:135], v[172:175], v[44:47]
	v_mfma_f32_16x16x32_bf16 v[40:43], v[140:143], v[172:175], v[40:43]
	v_mfma_f32_16x16x32_bf16 v[36:39], v[132:135], v[194:197], v[36:39]
	v_mfma_f32_16x16x32_bf16 v[32:35], v[140:143], v[194:197], v[32:35]
	s_setprio 0
	s_barrier
	s_add_u32 s42, s42, 0x40080
	s_addc_u32 s43, s43, 0
	s_add_i32 s44, s44, s57
	v_lshl_add_u64 v[128:129], s[42:43], 0, v[176:177]
	s_mov_b32 m0, s44
	s_nop 0
	global_load_lds_dwordx4 v[128:129], off
	v_lshl_add_u64 v[128:129], s[42:43], 0, v[158:159]
	s_add_i32 m0, s44, 0x2000
	s_nop 0
	global_load_lds_dwordx4 v[128:129], off
	s_waitcnt vmcnt(10)
	s_barrier
	s_setprio 1
	v_mfma_f32_16x16x32_bf16 v[28:31], v[198:201], v[144:147], v[28:31]
	v_mfma_f32_16x16x32_bf16 v[24:27], v[212:215], v[144:147], v[24:27]
	v_mfma_f32_16x16x32_bf16 v[20:23], v[198:201], v[152:155], v[20:23]
	v_mfma_f32_16x16x32_bf16 v[16:19], v[212:215], v[152:155], v[16:19]
	v_mfma_f32_16x16x32_bf16 v[12:15], v[198:201], v[168:171], v[12:15]
	v_mfma_f32_16x16x32_bf16 v[8:11], v[212:215], v[168:171], v[8:11]
	v_mfma_f32_16x16x32_bf16 v[4:7], v[198:201], v[190:193], v[4:7]
	v_mfma_f32_16x16x32_bf16 v[0:3], v[212:215], v[190:193], v[0:3]
	v_mfma_f32_16x16x32_bf16 v[28:31], v[208:211], v[148:151], v[28:31]
	v_mfma_f32_16x16x32_bf16 v[24:27], v[216:219], v[148:151], v[24:27]
	v_mfma_f32_16x16x32_bf16 v[20:23], v[208:211], v[164:167], v[20:23]
	v_mfma_f32_16x16x32_bf16 v[16:19], v[216:219], v[164:167], v[16:19]
	v_mfma_f32_16x16x32_bf16 v[12:15], v[208:211], v[172:175], v[12:15]
	v_mfma_f32_16x16x32_bf16 v[8:11], v[216:219], v[172:175], v[8:11]
	v_mfma_f32_16x16x32_bf16 v[4:7], v[208:211], v[194:197], v[4:7]
	v_mfma_f32_16x16x32_bf16 v[0:3], v[216:219], v[194:197], v[0:3]
	s_setprio 0
	s_add_u32 s40, s40, 0x100
	s_addc_u32 s41, s41, 0
	s_add_u32 s75, s75, 0x100
	s_addc_u32 s76, s76, 0
	s_cmp_ge_i32 s77, s3
	s_mov_b32 s42, s77
	s_barrier
	s_cbranch_scc0 .LBB0_1021
	v_readlane_b32 s36, v251, 0
	s_mov_b32 s3, s56
	v_mov_b32_e32 v130, v205
	s_mov_b32 s45, s64
	v_mov_b32_e32 v144, v204
	s_mov_b32 s40, s36
	s_ashr_i32 s41, s40, 31
	s_lshl_b64 s[40:41], s[40:41], 17
	s_add_u32 s40, s28, s40
	v_readlane_b32 s37, v249, 19
	s_addc_u32 s41, s37, s41
	v_mov_b32_e32 v128, v224
	s_bitcmp1_b32 s72, 0
	s_cselect_b64 s[54:55], -1, 0
	v_ashrrev_i32_e32 v129, 31, v128
	v_readlane_b32 s76, v250, 37
	v_readlane_b32 s78, v250, 39
	v_lshl_add_u64 v[164:165], v[128:129], 4, s[40:41]
	s_mov_b32 s40, s36
	v_mov_b32_e32 v128, v224
	s_mov_b64 s[42:43], -1
	s_and_b64 vcc, exec, s[54:55]
	v_readlane_b32 s77, v250, 38
	v_readlane_b32 s79, v250, 40
	s_cbranch_vccz .LBB0_1184
	s_ashr_i32 s41, s40, 31
	s_lshl_b64 s[40:41], s[40:41], 17
	v_readlane_b32 s36, v249, 10
	v_readlane_b32 s37, v249, 11
	s_add_u32 s40, s36, s40
	s_addc_u32 s41, s37, s41
	s_cmp_lt_i32 s72, 8
	v_ashrrev_i32_e32 v129, 31, v128
	s_cselect_b64 s[54:55], -1, 0
	s_cmp_gt_i32 s72, 7
	v_lshl_add_u64 v[168:169], v[128:129], 4, s[40:41]
	s_cselect_b64 s[40:41], -1, 0
	s_bfe_u32 s44, s72, 0x20001
	v_lshlrev_b32_e64 v145, 6, s3
	s_lshl_b32 s3, s71, 8
	v_lshlrev_b32_e64 v128, 5, s45
	v_lshlrev_b32_e32 v129, 2, v130
	v_add3_u32 v166, v128, s3, v129
	s_lshl_b32 s3, s44, 12
	s_add_u32 s42, s62, s3
	s_addc_u32 s43, s63, 0
	s_lshl_b32 s2, s2, 8
	v_add3_u32 v172, v144, s2, v145
	v_readlane_b32 s2, v249, 12
	v_ashrrev_i32_e32 v167, 31, v166
	v_ashrrev_i32_e32 v173, 31, v172
	v_readlane_b32 s3, v249, 13
	v_lshl_add_u64 v[128:129], v[166:167], 2, s[42:43]
	s_branch .Lmrg_fast

.LBB0_1310:
	v_and_b32_e32 v168, 15, v8
	v_bfe_u32 v169, v8, 4, 2
	v_lshlrev_b32_e32 v17, 6, v168
	v_lshlrev_b32_e32 v8, 2, v8
	s_and_b32 s55, s2, 3
	v_lshl_or_b32 v17, v169, 4, v17
	s_lshl_b32 s2, s48, 13
	v_and_b32_e32 v8, 32, v8
	s_add_i32 m0, s51, 0x18000
	v_lshl_add_u64 v[6:7], v[6:7], 0, s[24:25]
	v_bitop3_b32 v18, v17, s2, v8 bitop3:0xde
	s_lshl_b32 s2, s55, 12
	s_waitcnt vmcnt(4)
	s_barrier
	global_load_lds_dwordx4 v[6:7], off
	v_lshl_add_u64 v[4:5], v[4:5], 0, s[24:25]
	s_add_i32 m0, s51, 0x1a000
	s_add_i32 s56, s51, 0x8000
	s_add_i32 s57, s51, 0xa000
	v_bitop3_b32 v170, v17, s2, v8 bitop3:0xde
	global_load_lds_dwordx4 v[4:5], off
	v_lshl_add_u64 v[2:3], v[2:3], 0, s[24:25]
	s_mov_b32 m0, s56
	s_add_u32 s2, s40, 0x40080
	global_load_lds_dwordx4 v[2:3], off
	v_lshl_add_u64 v[0:1], v[0:1], 0, s[24:25]
	s_mov_b32 m0, s57
	s_addc_u32 s3, s41, 0
	global_load_lds_dwordx4 v[0:1], off
	s_add_i32 m0, s51, 0x1c000
	v_lshl_add_u64 v[0:1], s[2:3], 0, v[176:177]
	global_load_lds_dwordx4 v[0:1], off
	v_lshl_add_u64 v[0:1], s[2:3], 0, v[132:133]
	s_add_i32 m0, s51, 0x1e000
	s_not_b32 s2, s21
	global_load_lds_dwordx4 v[0:1], off
	v_readlane_b32 s3, v250, 18
	s_ashr_i32 s58, s21, 31
	s_add_i32 s2, s3, s2
	s_waitcnt lgkmcnt(0)
	s_cmp_lg_u64 s[4:5], 0
	s_cselect_b64 s[6:7], -1, 0
	s_ashr_i32 s3, s2, 31
	s_abs_i32 s2, s2
	v_readlane_b32 s12, v250, 14
	s_mul_hi_u32 s12, s2, s12
	v_readlane_b32 s15, v250, 13
	s_mul_i32 s13, s12, s15
	s_sub_i32 s2, s2, s13
	s_xor_b32 s3, s3, s81
	s_add_i32 s13, s12, 1
	s_sub_i32 s14, s2, s15
	s_cmp_ge_u32 s2, s15
	s_cselect_b32 s12, s13, s12
	s_cselect_b32 s2, s14, s2
	s_add_i32 s13, s12, 1
	v_lshlrev_b32_e32 v0, 13, v9
	s_cmp_ge_u32 s2, s15
	v_and_b32_e32 v0, 0x7fffc000, v0
	s_cselect_b32 s2, s13, s12
	v_lshl_add_u32 v0, v10, 10, v0
	s_xor_b32 s2, s2, s3
	v_or_b32_e32 v0, v0, v11
	s_sub_i32 s59, s2, s3
	v_add_lshl_u32 v0, v0, v12, 1
	v_mov_b32_e32 v1, v177
	s_mov_b64 s[2:3], 0x40080
	v_lshl_add_u64 v[134:135], v[0:1], 0, s[2:3]
	v_lshlrev_b32_e32 v0, 13, v13
	v_and_b32_e32 v0, 0x7fffc000, v0
	v_lshl_add_u32 v0, v14, 10, v0
	s_waitcnt vmcnt(0)
	v_or_b32_e32 v0, v0, v15
	v_add_lshl_u32 v0, v0, v16, 1
	v_lshl_add_u64 v[136:137], v[0:1], 0, s[2:3]
	s_mov_b32 s60, 0
	v_add_u32_e32 v171, 0, v18
	s_barrier
	s_branch .LBB0_1312

.LBB0_1322:
	s_add_i32 s69, s42, 2
	s_add_u32 s40, s38, 0x100
	s_addc_u32 s41, s39, 0
	s_add_i32 s70, 0, 0x10000
	v_add_u32_e32 v146, s70, v170
	s_waitcnt lgkmcnt(0)
	ds_read_b128 v[128:131], v146
	ds_read_b128 v[138:141], v146 offset:1024
	ds_read_b128 v[142:145], v146 offset:2048
	ds_read_b128 v[146:149], v146 offset:3072
	s_cmp_eq_u32 s66, s42
	s_cselect_b32 s42, s65, s67
	s_cselect_b32 s45, s13, s41
	s_cselect_b32 s44, s23, s40
	s_cselect_b32 s43, s64, s68
	v_lshl_add_u64 v[166:167], s[38:39], 0, v[134:135]
	s_add_i32 m0, s51, 0xc000
	ds_read_b128 v[150:153], v171
	ds_read_b128 v[154:157], v171 offset:1024
	ds_read_b128 v[158:161], v171 offset:2048
	ds_read_b128 v[162:165], v171 offset:3072
	ds_read_b128 v[172:175], v171 offset:4096
	ds_read_b128 v[190:193], v171 offset:5120
	ds_read_b128 v[194:197], v171 offset:6144
	ds_read_b128 v[198:201], v171 offset:7168
	global_load_lds_dwordx4 v[166:167], off
	v_lshl_add_u64 v[166:167], s[38:39], 0, v[136:137]
	s_add_i32 m0, s51, 0xe000
	s_nop 0
	global_load_lds_dwordx4 v[166:167], off
	s_waitcnt lgkmcnt(8)
	s_waitcnt vmcnt(10)
	s_barrier
	s_waitcnt lgkmcnt(0)
	s_setprio 1
	s_waitcnt lgkmcnt(0)
	v_mfma_f32_16x16x32_bf16 v[124:127], v[128:131], v[150:153], v[124:127]
	v_mfma_f32_16x16x32_bf16 v[120:123], v[142:145], v[150:153], v[120:123]
	v_mfma_f32_16x16x32_bf16 v[116:119], v[128:131], v[158:161], v[116:119]
	v_mfma_f32_16x16x32_bf16 v[112:115], v[142:145], v[158:161], v[112:115]
	v_mfma_f32_16x16x32_bf16 v[104:107], v[128:131], v[172:175], v[104:107]
	v_mfma_f32_16x16x32_bf16 v[96:99], v[142:145], v[172:175], v[96:99]
	v_mfma_f32_16x16x32_bf16 v[88:91], v[128:131], v[194:197], v[88:91]
	v_mfma_f32_16x16x32_bf16 v[80:83], v[142:145], v[194:197], v[80:83]
	v_mfma_f32_16x16x32_bf16 v[124:127], v[138:141], v[154:157], v[124:127]
	v_mfma_f32_16x16x32_bf16 v[120:123], v[146:149], v[154:157], v[120:123]
	v_mfma_f32_16x16x32_bf16 v[116:119], v[138:141], v[162:165], v[116:119]
	v_mfma_f32_16x16x32_bf16 v[112:115], v[146:149], v[162:165], v[112:115]
	v_mfma_f32_16x16x32_bf16 v[104:107], v[138:141], v[190:193], v[104:107]
	v_mfma_f32_16x16x32_bf16 v[96:99], v[146:149], v[190:193], v[96:99]
	v_mfma_f32_16x16x32_bf16 v[88:91], v[138:141], v[198:201], v[88:91]
	v_mfma_f32_16x16x32_bf16 v[80:83], v[146:149], v[198:201], v[80:83]
	s_setprio 0
	s_barrier
	s_add_i32 s71, 0, 0x14000
	v_add_u32_e32 v166, s71, v170
	s_add_i32 s38, s70, s49
	ds_read_b128 v[202:205], v166
	ds_read_b128 v[206:209], v166 offset:1024
	ds_read_b128 v[210:213], v166 offset:2048
	ds_read_b128 v[214:217], v166 offset:3072
	v_lshl_add_u64 v[166:167], s[42:43], 0, v[176:177]
	s_mov_b32 m0, s38
	v_lshl_add_u64 v[218:219], s[42:43], 0, v[132:133]
	global_load_lds_dwordx4 v[166:167], off
	s_add_i32 m0, s38, 0x2000
	s_nop 0
	global_load_lds_dwordx4 v[218:219], off
	s_waitcnt vmcnt(10)
	s_barrier
	s_waitcnt lgkmcnt(0)
	s_setprio 1
	s_waitcnt lgkmcnt(0)
	v_mfma_f32_16x16x32_bf16 v[108:111], v[202:205], v[150:153], v[108:111]
	v_mfma_f32_16x16x32_bf16 v[100:103], v[210:213], v[150:153], v[100:103]
	v_mfma_f32_16x16x32_bf16 v[92:95], v[202:205], v[158:161], v[92:95]
	v_mfma_f32_16x16x32_bf16 v[84:87], v[210:213], v[158:161], v[84:87]
	v_mfma_f32_16x16x32_bf16 v[76:79], v[202:205], v[172:175], v[76:79]
	v_mfma_f32_16x16x32_bf16 v[72:75], v[210:213], v[172:175], v[72:75]
	v_mfma_f32_16x16x32_bf16 v[68:71], v[202:205], v[194:197], v[68:71]
	v_mfma_f32_16x16x32_bf16 v[64:67], v[210:213], v[194:197], v[64:67]
	v_mfma_f32_16x16x32_bf16 v[108:111], v[206:209], v[154:157], v[108:111]
	v_mfma_f32_16x16x32_bf16 v[100:103], v[214:217], v[154:157], v[100:103]
	v_mfma_f32_16x16x32_bf16 v[92:95], v[206:209], v[162:165], v[92:95]
	v_mfma_f32_16x16x32_bf16 v[84:87], v[214:217], v[162:165], v[84:87]
	v_mfma_f32_16x16x32_bf16 v[76:79], v[206:209], v[190:193], v[76:79]
	v_mfma_f32_16x16x32_bf16 v[72:75], v[214:217], v[190:193], v[72:75]
	v_mfma_f32_16x16x32_bf16 v[68:71], v[206:209], v[198:201], v[68:71]
	v_mfma_f32_16x16x32_bf16 v[64:67], v[214:217], v[198:201], v[64:67]
	s_setprio 0
	s_mov_b32 m0, s51
	v_lshl_add_u64 v[220:221], s[44:45], 0, v[176:177]
	s_barrier
	ds_read_b128 v[150:153], v171 offset:16384
	ds_read_b128 v[154:157], v171 offset:17408
	ds_read_b128 v[158:161], v171 offset:18432
	ds_read_b128 v[162:165], v171 offset:19456
	ds_read_b128 v[172:175], v171 offset:20480
	ds_read_b128 v[190:193], v171 offset:21504
	ds_read_b128 v[194:197], v171 offset:22528
	ds_read_b128 v[198:201], v171 offset:23552
	global_load_lds_dwordx4 v[220:221], off
	v_lshl_add_u64 v[222:223], s[44:45], 0, v[132:133]
	s_mov_b32 m0, s52
	s_nop 0
	global_load_lds_dwordx4 v[222:223], off
	s_barrier
	s_waitcnt lgkmcnt(0)
	s_setprio 1
	s_waitcnt lgkmcnt(0)
	v_mfma_f32_16x16x32_bf16 v[60:63], v[128:131], v[150:153], v[60:63]
	v_mfma_f32_16x16x32_bf16 v[56:59], v[142:145], v[150:153], v[56:59]
	v_mfma_f32_16x16x32_bf16 v[52:55], v[128:131], v[158:161], v[52:55]
	v_mfma_f32_16x16x32_bf16 v[48:51], v[142:145], v[158:161], v[48:51]
	v_mfma_f32_16x16x32_bf16 v[40:43], v[128:131], v[172:175], v[40:43]
	v_mfma_f32_16x16x32_bf16 v[32:35], v[142:145], v[172:175], v[32:35]
	v_mfma_f32_16x16x32_bf16 v[24:27], v[128:131], v[194:197], v[24:27]
	v_mfma_f32_16x16x32_bf16 v[16:19], v[142:145], v[194:197], v[16:19]
	v_mfma_f32_16x16x32_bf16 v[60:63], v[138:141], v[154:157], v[60:63]
	v_mfma_f32_16x16x32_bf16 v[56:59], v[146:149], v[154:157], v[56:59]
	v_mfma_f32_16x16x32_bf16 v[52:55], v[138:141], v[162:165], v[52:55]
	v_mfma_f32_16x16x32_bf16 v[48:51], v[146:149], v[162:165], v[48:51]
	v_mfma_f32_16x16x32_bf16 v[40:43], v[138:141], v[190:193], v[40:43]
	v_mfma_f32_16x16x32_bf16 v[32:35], v[146:149], v[190:193], v[32:35]
	v_mfma_f32_16x16x32_bf16 v[24:27], v[138:141], v[198:201], v[24:27]
	v_mfma_f32_16x16x32_bf16 v[16:19], v[146:149], v[198:201], v[16:19]
	s_setprio 0
	s_barrier
	s_add_u32 s38, s42, 0x40000
	s_addc_u32 s39, s43, 0
	s_add_i32 s70, s71, s49
	v_lshl_add_u64 v[128:129], s[38:39], 0, v[176:177]
	s_mov_b32 m0, s70
	s_nop 0
	global_load_lds_dwordx4 v[128:129], off
	v_lshl_add_u64 v[128:129], s[38:39], 0, v[132:133]
	s_add_i32 m0, s70, 0x2000
	s_nop 0
	global_load_lds_dwordx4 v[128:129], off
	s_waitcnt vmcnt(10)
	s_barrier
	s_setprio 1
	v_mfma_f32_16x16x32_bf16 v[44:47], v[202:205], v[150:153], v[44:47]
	v_mfma_f32_16x16x32_bf16 v[36:39], v[210:213], v[150:153], v[36:39]
	v_mfma_f32_16x16x32_bf16 v[28:31], v[202:205], v[158:161], v[28:31]
	v_mfma_f32_16x16x32_bf16 v[20:23], v[210:213], v[158:161], v[20:23]
	v_mfma_f32_16x16x32_bf16 v[12:15], v[202:205], v[172:175], v[12:15]
	v_mfma_f32_16x16x32_bf16 v[8:11], v[210:213], v[172:175], v[8:11]
	v_mfma_f32_16x16x32_bf16 v[4:7], v[202:205], v[194:197], v[4:7]
	v_mfma_f32_16x16x32_bf16 v[0:3], v[210:213], v[194:197], v[0:3]
	v_mfma_f32_16x16x32_bf16 v[44:47], v[206:209], v[154:157], v[44:47]
	v_mfma_f32_16x16x32_bf16 v[36:39], v[214:217], v[154:157], v[36:39]
	v_mfma_f32_16x16x32_bf16 v[28:31], v[206:209], v[162:165], v[28:31]
	v_mfma_f32_16x16x32_bf16 v[20:23], v[214:217], v[162:165], v[20:23]
	v_mfma_f32_16x16x32_bf16 v[12:15], v[206:209], v[190:193], v[12:15]
	v_mfma_f32_16x16x32_bf16 v[8:11], v[214:217], v[190:193], v[8:11]
	v_mfma_f32_16x16x32_bf16 v[4:7], v[206:209], v[198:201], v[4:7]
	v_mfma_f32_16x16x32_bf16 v[0:3], v[214:217], v[198:201], v[0:3]
	s_setprio 0
	s_add_i32 s70, 0, 0x18000
	v_add_u32_e32 v146, s70, v170
	s_barrier
	ds_read_b128 v[128:131], v146
	ds_read_b128 v[138:141], v146 offset:1024
	ds_read_b128 v[142:145], v146 offset:2048
	ds_read_b128 v[146:149], v146 offset:3072
	s_add_u32 s38, s44, 0x40000
	s_addc_u32 s39, s45, 0
	s_mov_b32 m0, s53
	v_lshl_add_u64 v[202:203], s[38:39], 0, v[176:177]
	ds_read_b128 v[150:153], v171 offset:32768
	ds_read_b128 v[154:157], v171 offset:33792
	ds_read_b128 v[158:161], v171 offset:34816
	ds_read_b128 v[162:165], v171 offset:35840
	ds_read_b128 v[172:175], v171 offset:36864
	ds_read_b128 v[190:193], v171 offset:37888
	ds_read_b128 v[194:197], v171 offset:38912
	ds_read_b128 v[198:201], v171 offset:39936
	global_load_lds_dwordx4 v[202:203], off
	v_lshl_add_u64 v[202:203], s[38:39], 0, v[132:133]
	s_mov_b32 m0, s54
	s_nop 0
	global_load_lds_dwordx4 v[202:203], off
	s_waitcnt lgkmcnt(8)
	s_waitcnt vmcnt(10)
	s_barrier
	s_waitcnt lgkmcnt(0)
	s_setprio 1
	s_waitcnt lgkmcnt(0)
	v_mfma_f32_16x16x32_bf16 v[124:127], v[128:131], v[150:153], v[124:127]
	v_mfma_f32_16x16x32_bf16 v[120:123], v[142:145], v[150:153], v[120:123]
	v_mfma_f32_16x16x32_bf16 v[116:119], v[128:131], v[158:161], v[116:119]
	v_mfma_f32_16x16x32_bf16 v[112:115], v[142:145], v[158:161], v[112:115]
	v_mfma_f32_16x16x32_bf16 v[104:107], v[128:131], v[172:175], v[104:107]
	v_mfma_f32_16x16x32_bf16 v[96:99], v[142:145], v[172:175], v[96:99]
	v_mfma_f32_16x16x32_bf16 v[88:91], v[128:131], v[194:197], v[88:91]
	v_mfma_f32_16x16x32_bf16 v[80:83], v[142:145], v[194:197], v[80:83]
	v_mfma_f32_16x16x32_bf16 v[124:127], v[138:141], v[154:157], v[124:127]
	v_mfma_f32_16x16x32_bf16 v[120:123], v[146:149], v[154:157], v[120:123]
	v_mfma_f32_16x16x32_bf16 v[116:119], v[138:141], v[162:165], v[116:119]
	v_mfma_f32_16x16x32_bf16 v[112:115], v[146:149], v[162:165], v[112:115]
	v_mfma_f32_16x16x32_bf16 v[104:107], v[138:141], v[190:193], v[104:107]
	v_mfma_f32_16x16x32_bf16 v[96:99], v[146:149], v[190:193], v[96:99]
	v_mfma_f32_16x16x32_bf16 v[88:91], v[138:141], v[198:201], v[88:91]
	v_mfma_f32_16x16x32_bf16 v[80:83], v[146:149], v[198:201], v[80:83]
	s_setprio 0
	s_barrier
	s_add_i32 s44, 0, 0x1c000
	s_add_i32 s38, s70, s49
	v_add_u32_e32 v214, s44, v170
	v_lshl_add_u64 v[166:167], v[166:167], 0, s[24:25]
	s_mov_b32 m0, s38
	ds_read_b128 v[202:205], v214
	ds_read_b128 v[206:209], v214 offset:1024
	ds_read_b128 v[210:213], v214 offset:2048
	ds_read_b128 v[214:217], v214 offset:3072
	global_load_lds_dwordx4 v[166:167], off
	v_lshl_add_u64 v[166:167], v[218:219], 0, s[24:25]
	s_add_i32 m0, s38, 0x2000
	s_nop 0
	global_load_lds_dwordx4 v[166:167], off
	s_waitcnt vmcnt(10)
	s_barrier
	s_waitcnt lgkmcnt(0)
	s_setprio 1
	s_waitcnt lgkmcnt(0)
	v_mfma_f32_16x16x32_bf16 v[108:111], v[202:205], v[150:153], v[108:111]
	v_mfma_f32_16x16x32_bf16 v[100:103], v[210:213], v[150:153], v[100:103]
	v_mfma_f32_16x16x32_bf16 v[92:95], v[202:205], v[158:161], v[92:95]
	v_mfma_f32_16x16x32_bf16 v[84:87], v[210:213], v[158:161], v[84:87]
	v_mfma_f32_16x16x32_bf16 v[76:79], v[202:205], v[172:175], v[76:79]
	v_mfma_f32_16x16x32_bf16 v[72:75], v[210:213], v[172:175], v[72:75]
	v_mfma_f32_16x16x32_bf16 v[68:71], v[202:205], v[194:197], v[68:71]
	v_mfma_f32_16x16x32_bf16 v[64:67], v[210:213], v[194:197], v[64:67]
	v_mfma_f32_16x16x32_bf16 v[108:111], v[206:209], v[154:157], v[108:111]
	v_mfma_f32_16x16x32_bf16 v[100:103], v[214:217], v[154:157], v[100:103]
	v_mfma_f32_16x16x32_bf16 v[92:95], v[206:209], v[162:165], v[92:95]
	v_mfma_f32_16x16x32_bf16 v[84:87], v[214:217], v[162:165], v[84:87]
	v_mfma_f32_16x16x32_bf16 v[76:79], v[206:209], v[190:193], v[76:79]
	v_mfma_f32_16x16x32_bf16 v[72:75], v[214:217], v[190:193], v[72:75]
	v_mfma_f32_16x16x32_bf16 v[68:71], v[206:209], v[198:201], v[68:71]
	v_mfma_f32_16x16x32_bf16 v[64:67], v[214:217], v[198:201], v[64:67]
	s_setprio 0
	s_mov_b32 m0, s56
	v_lshl_add_u64 v[166:167], v[220:221], 0, s[24:25]
	s_barrier
	ds_read_b128 v[150:153], v171 offset:49152
	ds_read_b128 v[154:157], v171 offset:50176
	ds_read_b128 v[158:161], v171 offset:51200
	ds_read_b128 v[162:165], v171 offset:52224
	ds_read_b128 v[172:175], v171 offset:53248
	ds_read_b128 v[190:193], v171 offset:54272
	ds_read_b128 v[194:197], v171 offset:55296
	ds_read_b128 v[198:201], v171 offset:56320
	global_load_lds_dwordx4 v[166:167], off
	v_lshl_add_u64 v[166:167], v[222:223], 0, s[24:25]
	s_mov_b32 m0, s57
	s_nop 0
	global_load_lds_dwordx4 v[166:167], off
	s_barrier
	s_waitcnt lgkmcnt(0)
	s_setprio 1
	s_waitcnt lgkmcnt(0)
	v_mfma_f32_16x16x32_bf16 v[60:63], v[128:131], v[150:153], v[60:63]
	v_mfma_f32_16x16x32_bf16 v[56:59], v[142:145], v[150:153], v[56:59]
	v_mfma_f32_16x16x32_bf16 v[52:55], v[128:131], v[158:161], v[52:55]
	v_mfma_f32_16x16x32_bf16 v[48:51], v[142:145], v[158:161], v[48:51]
	v_mfma_f32_16x16x32_bf16 v[40:43], v[128:131], v[172:175], v[40:43]
	v_mfma_f32_16x16x32_bf16 v[32:35], v[142:145], v[172:175], v[32:35]
	v_mfma_f32_16x16x32_bf16 v[24:27], v[128:131], v[194:197], v[24:27]
	v_mfma_f32_16x16x32_bf16 v[16:19], v[142:145], v[194:197], v[16:19]
	v_mfma_f32_16x16x32_bf16 v[60:63], v[138:141], v[154:157], v[60:63]
	v_mfma_f32_16x16x32_bf16 v[56:59], v[146:149], v[154:157], v[56:59]
	v_mfma_f32_16x16x32_bf16 v[52:55], v[138:141], v[162:165], v[52:55]
	v_mfma_f32_16x16x32_bf16 v[48:51], v[146:149], v[162:165], v[48:51]
	v_mfma_f32_16x16x32_bf16 v[40:43], v[138:141], v[190:193], v[40:43]
	v_mfma_f32_16x16x32_bf16 v[32:35], v[146:149], v[190:193], v[32:35]
	v_mfma_f32_16x16x32_bf16 v[24:27], v[138:141], v[198:201], v[24:27]
	v_mfma_f32_16x16x32_bf16 v[16:19], v[146:149], v[198:201], v[16:19]
	s_setprio 0
	s_barrier
	s_add_u32 s38, s42, 0x40080
	s_addc_u32 s39, s43, 0
	s_add_i32 s42, s44, s49
	v_lshl_add_u64 v[128:129], s[38:39], 0, v[176:177]
	s_mov_b32 m0, s42
	s_nop 0
	global_load_lds_dwordx4 v[128:129], off
	v_lshl_add_u64 v[128:129], s[38:39], 0, v[132:133]
	s_add_i32 m0, s42, 0x2000
	s_nop 0
	global_load_lds_dwordx4 v[128:129], off
	s_waitcnt vmcnt(10)
	s_barrier
	s_setprio 1
	v_mfma_f32_16x16x32_bf16 v[44:47], v[202:205], v[150:153], v[44:47]
	v_mfma_f32_16x16x32_bf16 v[36:39], v[210:213], v[150:153], v[36:39]
	v_mfma_f32_16x16x32_bf16 v[28:31], v[202:205], v[158:161], v[28:31]
	v_mfma_f32_16x16x32_bf16 v[20:23], v[210:213], v[158:161], v[20:23]
	v_mfma_f32_16x16x32_bf16 v[12:15], v[202:205], v[172:175], v[12:15]
	v_mfma_f32_16x16x32_bf16 v[8:11], v[210:213], v[172:175], v[8:11]
	v_mfma_f32_16x16x32_bf16 v[4:7], v[202:205], v[194:197], v[4:7]
	v_mfma_f32_16x16x32_bf16 v[0:3], v[210:213], v[194:197], v[0:3]
	v_mfma_f32_16x16x32_bf16 v[44:47], v[206:209], v[154:157], v[44:47]
	v_mfma_f32_16x16x32_bf16 v[36:39], v[214:217], v[154:157], v[36:39]
	v_mfma_f32_16x16x32_bf16 v[28:31], v[206:209], v[162:165], v[28:31]
	v_mfma_f32_16x16x32_bf16 v[20:23], v[214:217], v[162:165], v[20:23]
	v_mfma_f32_16x16x32_bf16 v[12:15], v[206:209], v[190:193], v[12:15]
	v_mfma_f32_16x16x32_bf16 v[8:11], v[214:217], v[190:193], v[8:11]
	v_mfma_f32_16x16x32_bf16 v[4:7], v[206:209], v[198:201], v[4:7]
	v_mfma_f32_16x16x32_bf16 v[0:3], v[214:217], v[198:201], v[0:3]
	s_setprio 0
	s_add_u32 s67, s67, 0x100
	s_addc_u32 s68, s68, 0
	s_cmp_ge_i32 s69, s63
	s_mov_b64 s[38:39], s[40:41]
	s_mov_b32 s42, s69
	s_barrier
	s_cbranch_scc0 .LBB0_1322
	v_mov_b32_e32 v166, v169
	s_mov_b32 s13, s55
	v_mov_b32_e32 v128, v168
	s_mov_b32 s23, s48
	s_lshl_b32 s22, s22, 8
	s_lshl_b32 s23, s23, 6
	s_add_i32 s23, s23, s22
	s_lshl_b32 s22, s62, 8
	s_lshl_b32 s13, s13, 5
	s_add_i32 s13, s13, s22
	v_lshl_add_u32 v140, v166, 2, s13
	v_add_u32_e32 v138, s23, v128
	s_mov_b64 s[22:23], -1
	s_cmp_gt_i32 s47, 0
	v_ashrrev_i32_e32 v141, 31, v140
	s_cbranch_scc1 .LBB0_1474
	v_lshlrev_b32_e32 v139, 11, v138
	v_lshl_add_u32 v139, v140, 1, v139
	v_lshlrev_b32_e32 v143, 2, v138
	v_xor_b32_e32 v238, 16, v229
	v_xor_b32_e32 v239, 32, v229
	v_lshlrev_b32_e32 v238, 2, v238
	v_lshlrev_b32_e32 v239, 2, v239
	v_mov_b32_e32 v142, v139
	s_and_b64 vcc, exec, s[6:7]
	s_cbranch_vccnz .LresF_xin
	v_mov_b32_e32 v141, v139
	global_load_dwordx2 v[192:193], v141, s[96:97]
	global_load_dwordx2 v[194:195], v141, s[96:97] offset:32
	global_load_dwordx2 v[196:197], v141, s[96:97] offset:256
	global_load_dwordx2 v[198:199], v141, s[96:97] offset:288
	v_add_u32_e32 v141, 0x8000, v141
	global_load_dwordx2 v[200:201], v141, s[96:97]
	global_load_dwordx2 v[202:203], v141, s[96:97] offset:32
	global_load_dwordx2 v[204:205], v141, s[96:97] offset:256
	global_load_dwordx2 v[206:207], v141, s[96:97] offset:288
	v_add_u32_e32 v141, 0x8000, v141
	global_load_dwordx2 v[208:209], v141, s[96:97]
	global_load_dwordx2 v[210:211], v141, s[96:97] offset:32
	global_load_dwordx2 v[212:213], v141, s[96:97] offset:256
	global_load_dwordx2 v[214:215], v141, s[96:97] offset:288
	v_add_u32_e32 v141, 0x8000, v141
	global_load_dwordx2 v[216:217], v141, s[96:97]
	global_load_dwordx2 v[218:219], v141, s[96:97] offset:32
	global_load_dwordx2 v[220:221], v141, s[96:97] offset:256
	global_load_dwordx2 v[222:223], v141, s[96:97] offset:288
	v_add_u32_e32 v141, 0x28000, v141
	global_load_dwordx2 v[144:145], v141, s[96:97]
	global_load_dwordx2 v[146:147], v141, s[96:97] offset:32
	global_load_dwordx2 v[148:149], v141, s[96:97] offset:256
	global_load_dwordx2 v[150:151], v141, s[96:97] offset:288
	v_add_u32_e32 v141, 0x8000, v141
	global_load_dwordx2 v[152:153], v141, s[96:97]
	global_load_dwordx2 v[154:155], v141, s[96:97] offset:32
	global_load_dwordx2 v[156:157], v141, s[96:97] offset:256
	global_load_dwordx2 v[158:159], v141, s[96:97] offset:288
	v_add_u32_e32 v141, 0x8000, v141
	global_load_dwordx2 v[160:161], v141, s[96:97]
	global_load_dwordx2 v[162:163], v141, s[96:97] offset:32
	global_load_dwordx2 v[164:165], v141, s[96:97] offset:256
	global_load_dwordx2 v[166:167], v141, s[96:97] offset:288
	v_add_u32_e32 v141, 0x8000, v141
	global_load_dwordx2 v[240:241], v141, s[96:97]
	global_load_dwordx2 v[242:243], v141, s[96:97] offset:32
	global_load_dwordx2 v[244:245], v141, s[96:97] offset:256
	global_load_dwordx2 v[246:247], v141, s[96:97] offset:288
	s_waitcnt vmcnt(31)
	v_lshlrev_b32_e32 v252, 16, v192
	v_and_b32_e32 v253, 0xffff0000, v192
	v_lshlrev_b32_e32 v254, 16, v193
	v_and_b32_e32 v255, 0xffff0000, v193
	v_pk_add_f32 v[252:253], v[124:125], v[252:253]
	v_pk_add_f32 v[254:255], v[126:127], v[254:255]
	v_mul_f32_e32 v128, v252, v252
	v_fmac_f32_e32 v128, v253, v253
	v_fmac_f32_e32 v128, v254, v254
	v_fmac_f32_e32 v128, v255, v255
	v_cvt_pk_bf16_f32 v190, v252, v253
	v_cvt_pk_bf16_f32 v191, v254, v255
	global_store_dwordx2 v142, v[190:191], s[96:97]
	s_waitcnt vmcnt(31)
	v_lshlrev_b32_e32 v252, 16, v194
	v_and_b32_e32 v253, 0xffff0000, v194
	v_lshlrev_b32_e32 v254, 16, v195
	v_and_b32_e32 v255, 0xffff0000, v195
	v_pk_add_f32 v[252:253], v[120:121], v[252:253]
	v_pk_add_f32 v[254:255], v[122:123], v[254:255]
	v_fmac_f32_e32 v128, v252, v252
	v_fmac_f32_e32 v128, v253, v253
	v_fmac_f32_e32 v128, v254, v254
	v_fmac_f32_e32 v128, v255, v255
	v_cvt_pk_bf16_f32 v190, v252, v253
	v_cvt_pk_bf16_f32 v191, v254, v255
	global_store_dwordx2 v142, v[190:191], s[96:97] offset:32
	s_waitcnt vmcnt(31)
	v_lshlrev_b32_e32 v252, 16, v196
	v_and_b32_e32 v253, 0xffff0000, v196
	v_lshlrev_b32_e32 v254, 16, v197
	v_and_b32_e32 v255, 0xffff0000, v197
	v_pk_add_f32 v[252:253], v[108:109], v[252:253]
	v_pk_add_f32 v[254:255], v[110:111], v[254:255]
	v_fmac_f32_e32 v128, v252, v252
	v_fmac_f32_e32 v128, v253, v253
	v_fmac_f32_e32 v128, v254, v254
	v_fmac_f32_e32 v128, v255, v255
	v_cvt_pk_bf16_f32 v190, v252, v253
	v_cvt_pk_bf16_f32 v191, v254, v255
	global_store_dwordx2 v142, v[190:191], s[96:97] offset:256
	s_waitcnt vmcnt(31)
	v_lshlrev_b32_e32 v252, 16, v198
	v_and_b32_e32 v253, 0xffff0000, v198
	v_lshlrev_b32_e32 v254, 16, v199
	v_and_b32_e32 v255, 0xffff0000, v199
	v_pk_add_f32 v[252:253], v[100:101], v[252:253]
	v_pk_add_f32 v[254:255], v[102:103], v[254:255]
	v_fmac_f32_e32 v128, v252, v252
	v_fmac_f32_e32 v128, v253, v253
	v_fmac_f32_e32 v128, v254, v254
	v_fmac_f32_e32 v128, v255, v255
	v_cvt_pk_bf16_f32 v190, v252, v253
	v_cvt_pk_bf16_f32 v191, v254, v255
	global_store_dwordx2 v142, v[190:191], s[96:97] offset:288
	v_add_u32_e32 v142, 0x8000, v142
	s_waitcnt vmcnt(31)
	v_lshlrev_b32_e32 v252, 16, v200
	v_and_b32_e32 v253, 0xffff0000, v200
	v_lshlrev_b32_e32 v254, 16, v201
	v_and_b32_e32 v255, 0xffff0000, v201
	v_pk_add_f32 v[252:253], v[116:117], v[252:253]
	v_pk_add_f32 v[254:255], v[118:119], v[254:255]
	v_mul_f32_e32 v129, v252, v252
	v_fmac_f32_e32 v129, v253, v253
	v_fmac_f32_e32 v129, v254, v254
	v_fmac_f32_e32 v129, v255, v255
	v_cvt_pk_bf16_f32 v190, v252, v253
	v_cvt_pk_bf16_f32 v191, v254, v255
	global_store_dwordx2 v142, v[190:191], s[96:97]
	s_waitcnt vmcnt(31)
	v_lshlrev_b32_e32 v252, 16, v202
	v_and_b32_e32 v253, 0xffff0000, v202
	v_lshlrev_b32_e32 v254, 16, v203
	v_and_b32_e32 v255, 0xffff0000, v203
	v_pk_add_f32 v[252:253], v[112:113], v[252:253]
	v_pk_add_f32 v[254:255], v[114:115], v[254:255]
	v_fmac_f32_e32 v129, v252, v252
	v_fmac_f32_e32 v129, v253, v253
	v_fmac_f32_e32 v129, v254, v254
	v_fmac_f32_e32 v129, v255, v255
	v_cvt_pk_bf16_f32 v190, v252, v253
	v_cvt_pk_bf16_f32 v191, v254, v255
	global_store_dwordx2 v142, v[190:191], s[96:97] offset:32
	s_waitcnt vmcnt(31)
	v_lshlrev_b32_e32 v252, 16, v204
	v_and_b32_e32 v253, 0xffff0000, v204
	v_lshlrev_b32_e32 v254, 16, v205
	v_and_b32_e32 v255, 0xffff0000, v205
	v_pk_add_f32 v[252:253], v[92:93], v[252:253]
	v_pk_add_f32 v[254:255], v[94:95], v[254:255]
	v_fmac_f32_e32 v129, v252, v252
	v_fmac_f32_e32 v129, v253, v253
	v_fmac_f32_e32 v129, v254, v254
	v_fmac_f32_e32 v129, v255, v255
	v_cvt_pk_bf16_f32 v190, v252, v253
	v_cvt_pk_bf16_f32 v191, v254, v255
	global_store_dwordx2 v142, v[190:191], s[96:97] offset:256
	s_waitcnt vmcnt(31)
	v_lshlrev_b32_e32 v252, 16, v206
	v_and_b32_e32 v253, 0xffff0000, v206
	v_lshlrev_b32_e32 v254, 16, v207
	v_and_b32_e32 v255, 0xffff0000, v207
	v_pk_add_f32 v[252:253], v[84:85], v[252:253]
	v_pk_add_f32 v[254:255], v[86:87], v[254:255]
	v_fmac_f32_e32 v129, v252, v252
	v_fmac_f32_e32 v129, v253, v253
	v_fmac_f32_e32 v129, v254, v254
	v_fmac_f32_e32 v129, v255, v255
	v_cvt_pk_bf16_f32 v190, v252, v253
	v_cvt_pk_bf16_f32 v191, v254, v255
	global_store_dwordx2 v142, v[190:191], s[96:97] offset:288
	v_add_u32_e32 v142, 0x8000, v142
	s_waitcnt vmcnt(31)
	v_lshlrev_b32_e32 v252, 16, v208
	v_and_b32_e32 v253, 0xffff0000, v208
	v_lshlrev_b32_e32 v254, 16, v209
	v_and_b32_e32 v255, 0xffff0000, v209
	v_pk_add_f32 v[252:253], v[104:105], v[252:253]
	v_pk_add_f32 v[254:255], v[106:107], v[254:255]
	v_mul_f32_e32 v130, v252, v252
	v_fmac_f32_e32 v130, v253, v253
	v_fmac_f32_e32 v130, v254, v254
	v_fmac_f32_e32 v130, v255, v255
	v_cvt_pk_bf16_f32 v190, v252, v253
	v_cvt_pk_bf16_f32 v191, v254, v255
	global_store_dwordx2 v142, v[190:191], s[96:97]
	s_waitcnt vmcnt(31)
	v_lshlrev_b32_e32 v252, 16, v210
	v_and_b32_e32 v253, 0xffff0000, v210
	v_lshlrev_b32_e32 v254, 16, v211
	v_and_b32_e32 v255, 0xffff0000, v211
	v_pk_add_f32 v[252:253], v[96:97], v[252:253]
	v_pk_add_f32 v[254:255], v[98:99], v[254:255]
	v_fmac_f32_e32 v130, v252, v252
	v_fmac_f32_e32 v130, v253, v253
	v_fmac_f32_e32 v130, v254, v254
	v_fmac_f32_e32 v130, v255, v255
	v_cvt_pk_bf16_f32 v190, v252, v253
	v_cvt_pk_bf16_f32 v191, v254, v255
	global_store_dwordx2 v142, v[190:191], s[96:97] offset:32
	s_waitcnt vmcnt(31)
	v_lshlrev_b32_e32 v252, 16, v212
	v_and_b32_e32 v253, 0xffff0000, v212
	v_lshlrev_b32_e32 v254, 16, v213
	v_and_b32_e32 v255, 0xffff0000, v213
	v_pk_add_f32 v[252:253], v[76:77], v[252:253]
	v_pk_add_f32 v[254:255], v[78:79], v[254:255]
	v_fmac_f32_e32 v130, v252, v252
	v_fmac_f32_e32 v130, v253, v253
	v_fmac_f32_e32 v130, v254, v254
	v_fmac_f32_e32 v130, v255, v255
	v_cvt_pk_bf16_f32 v190, v252, v253
	v_cvt_pk_bf16_f32 v191, v254, v255
	global_store_dwordx2 v142, v[190:191], s[96:97] offset:256
	s_waitcnt vmcnt(31)
	v_lshlrev_b32_e32 v252, 16, v214
	v_and_b32_e32 v253, 0xffff0000, v214
	v_lshlrev_b32_e32 v254, 16, v215
	v_and_b32_e32 v255, 0xffff0000, v215
	v_pk_add_f32 v[252:253], v[72:73], v[252:253]
	v_pk_add_f32 v[254:255], v[74:75], v[254:255]
	v_fmac_f32_e32 v130, v252, v252
	v_fmac_f32_e32 v130, v253, v253
	v_fmac_f32_e32 v130, v254, v254
	v_fmac_f32_e32 v130, v255, v255
	v_cvt_pk_bf16_f32 v190, v252, v253
	v_cvt_pk_bf16_f32 v191, v254, v255
	global_store_dwordx2 v142, v[190:191], s[96:97] offset:288
	v_add_u32_e32 v142, 0x8000, v142
	s_waitcnt vmcnt(31)
	v_lshlrev_b32_e32 v252, 16, v216
	v_and_b32_e32 v253, 0xffff0000, v216
	v_lshlrev_b32_e32 v254, 16, v217
	v_and_b32_e32 v255, 0xffff0000, v217
	v_pk_add_f32 v[252:253], v[88:89], v[252:253]
	v_pk_add_f32 v[254:255], v[90:91], v[254:255]
	v_mul_f32_e32 v131, v252, v252
	v_fmac_f32_e32 v131, v253, v253
	v_fmac_f32_e32 v131, v254, v254
	v_fmac_f32_e32 v131, v255, v255
	v_cvt_pk_bf16_f32 v190, v252, v253
	v_cvt_pk_bf16_f32 v191, v254, v255
	global_store_dwordx2 v142, v[190:191], s[96:97]
	s_waitcnt vmcnt(31)
	v_lshlrev_b32_e32 v252, 16, v218
	v_and_b32_e32 v253, 0xffff0000, v218
	v_lshlrev_b32_e32 v254, 16, v219
	v_and_b32_e32 v255, 0xffff0000, v219
	v_pk_add_f32 v[252:253], v[80:81], v[252:253]
	v_pk_add_f32 v[254:255], v[82:83], v[254:255]
	v_fmac_f32_e32 v131, v252, v252
	v_fmac_f32_e32 v131, v253, v253
	v_fmac_f32_e32 v131, v254, v254
	v_fmac_f32_e32 v131, v255, v255
	v_cvt_pk_bf16_f32 v190, v252, v253
	v_cvt_pk_bf16_f32 v191, v254, v255
	global_store_dwordx2 v142, v[190:191], s[96:97] offset:32
	s_waitcnt vmcnt(31)
	v_lshlrev_b32_e32 v252, 16, v220
	v_and_b32_e32 v253, 0xffff0000, v220
	v_lshlrev_b32_e32 v254, 16, v221
	v_and_b32_e32 v255, 0xffff0000, v221
	v_pk_add_f32 v[252:253], v[68:69], v[252:253]
	v_pk_add_f32 v[254:255], v[70:71], v[254:255]
	v_fmac_f32_e32 v131, v252, v252
	v_fmac_f32_e32 v131, v253, v253
	v_fmac_f32_e32 v131, v254, v254
	v_fmac_f32_e32 v131, v255, v255
	v_cvt_pk_bf16_f32 v190, v252, v253
	v_cvt_pk_bf16_f32 v191, v254, v255
	global_store_dwordx2 v142, v[190:191], s[96:97] offset:256
	s_waitcnt vmcnt(31)
	v_lshlrev_b32_e32 v252, 16, v222
	v_and_b32_e32 v253, 0xffff0000, v222
	v_lshlrev_b32_e32 v254, 16, v223
	v_and_b32_e32 v255, 0xffff0000, v223
	v_pk_add_f32 v[252:253], v[64:65], v[252:253]
	v_pk_add_f32 v[254:255], v[66:67], v[254:255]
	v_fmac_f32_e32 v131, v252, v252
	v_fmac_f32_e32 v131, v253, v253
	v_fmac_f32_e32 v131, v254, v254
	v_fmac_f32_e32 v131, v255, v255
	v_cvt_pk_bf16_f32 v190, v252, v253
	v_cvt_pk_bf16_f32 v191, v254, v255
	global_store_dwordx2 v142, v[190:191], s[96:97] offset:288
	v_add_u32_e32 v142, 0x28000, v142
	s_waitcnt vmcnt(31)
	v_lshlrev_b32_e32 v252, 16, v144
	v_and_b32_e32 v253, 0xffff0000, v144
	v_lshlrev_b32_e32 v254, 16, v145
	v_and_b32_e32 v255, 0xffff0000, v145
	v_pk_add_f32 v[252:253], v[60:61], v[252:253]
	v_pk_add_f32 v[254:255], v[62:63], v[254:255]
	v_mul_f32_e32 v172, v252, v252
	v_fmac_f32_e32 v172, v253, v253
	v_fmac_f32_e32 v172, v254, v254
	v_fmac_f32_e32 v172, v255, v255
	v_cvt_pk_bf16_f32 v190, v252, v253
	v_cvt_pk_bf16_f32 v191, v254, v255
	global_store_dwordx2 v142, v[190:191], s[96:97]
	s_waitcnt vmcnt(31)
	v_lshlrev_b32_e32 v252, 16, v146
	v_and_b32_e32 v253, 0xffff0000, v146
	v_lshlrev_b32_e32 v254, 16, v147
	v_and_b32_e32 v255, 0xffff0000, v147
	v_pk_add_f32 v[252:253], v[56:57], v[252:253]
	v_pk_add_f32 v[254:255], v[58:59], v[254:255]
	v_fmac_f32_e32 v172, v252, v252
	v_fmac_f32_e32 v172, v253, v253
	v_fmac_f32_e32 v172, v254, v254
	v_fmac_f32_e32 v172, v255, v255
	v_cvt_pk_bf16_f32 v190, v252, v253
	v_cvt_pk_bf16_f32 v191, v254, v255
	global_store_dwordx2 v142, v[190:191], s[96:97] offset:32
	s_waitcnt vmcnt(31)
	v_lshlrev_b32_e32 v252, 16, v148
	v_and_b32_e32 v253, 0xffff0000, v148
	v_lshlrev_b32_e32 v254, 16, v149
	v_and_b32_e32 v255, 0xffff0000, v149
	v_pk_add_f32 v[252:253], v[44:45], v[252:253]
	v_pk_add_f32 v[254:255], v[46:47], v[254:255]
	v_fmac_f32_e32 v172, v252, v252
	v_fmac_f32_e32 v172, v253, v253
	v_fmac_f32_e32 v172, v254, v254
	v_fmac_f32_e32 v172, v255, v255
	v_cvt_pk_bf16_f32 v190, v252, v253
	v_cvt_pk_bf16_f32 v191, v254, v255
	global_store_dwordx2 v142, v[190:191], s[96:97] offset:256
	s_waitcnt vmcnt(31)
	v_lshlrev_b32_e32 v252, 16, v150
	v_and_b32_e32 v253, 0xffff0000, v150
	v_lshlrev_b32_e32 v254, 16, v151
	v_and_b32_e32 v255, 0xffff0000, v151
	v_pk_add_f32 v[252:253], v[36:37], v[252:253]
	v_pk_add_f32 v[254:255], v[38:39], v[254:255]
	v_fmac_f32_e32 v172, v252, v252
	v_fmac_f32_e32 v172, v253, v253
	v_fmac_f32_e32 v172, v254, v254
	v_fmac_f32_e32 v172, v255, v255
	v_cvt_pk_bf16_f32 v190, v252, v253
	v_cvt_pk_bf16_f32 v191, v254, v255
	global_store_dwordx2 v142, v[190:191], s[96:97] offset:288
	v_add_u32_e32 v142, 0x8000, v142
	s_waitcnt vmcnt(31)
	v_lshlrev_b32_e32 v252, 16, v152
	v_and_b32_e32 v253, 0xffff0000, v152
	v_lshlrev_b32_e32 v254, 16, v153
	v_and_b32_e32 v255, 0xffff0000, v153
	v_pk_add_f32 v[252:253], v[52:53], v[252:253]
	v_pk_add_f32 v[254:255], v[54:55], v[254:255]
	v_mul_f32_e32 v173, v252, v252
	v_fmac_f32_e32 v173, v253, v253
	v_fmac_f32_e32 v173, v254, v254
	v_fmac_f32_e32 v173, v255, v255
	v_cvt_pk_bf16_f32 v190, v252, v253
	v_cvt_pk_bf16_f32 v191, v254, v255
	global_store_dwordx2 v142, v[190:191], s[96:97]
	s_waitcnt vmcnt(31)
	v_lshlrev_b32_e32 v252, 16, v154
	v_and_b32_e32 v253, 0xffff0000, v154
	v_lshlrev_b32_e32 v254, 16, v155
	v_and_b32_e32 v255, 0xffff0000, v155
	v_pk_add_f32 v[252:253], v[48:49], v[252:253]
	v_pk_add_f32 v[254:255], v[50:51], v[254:255]
	v_fmac_f32_e32 v173, v252, v252
	v_fmac_f32_e32 v173, v253, v253
	v_fmac_f32_e32 v173, v254, v254
	v_fmac_f32_e32 v173, v255, v255
	v_cvt_pk_bf16_f32 v190, v252, v253
	v_cvt_pk_bf16_f32 v191, v254, v255
	global_store_dwordx2 v142, v[190:191], s[96:97] offset:32
	s_waitcnt vmcnt(31)
	v_lshlrev_b32_e32 v252, 16, v156
	v_and_b32_e32 v253, 0xffff0000, v156
	v_lshlrev_b32_e32 v254, 16, v157
	v_and_b32_e32 v255, 0xffff0000, v157
	v_pk_add_f32 v[252:253], v[28:29], v[252:253]
	v_pk_add_f32 v[254:255], v[30:31], v[254:255]
	v_fmac_f32_e32 v173, v252, v252
	v_fmac_f32_e32 v173, v253, v253
	v_fmac_f32_e32 v173, v254, v254
	v_fmac_f32_e32 v173, v255, v255
	v_cvt_pk_bf16_f32 v190, v252, v253
	v_cvt_pk_bf16_f32 v191, v254, v255
	global_store_dwordx2 v142, v[190:191], s[96:97] offset:256
	s_waitcnt vmcnt(31)
	v_lshlrev_b32_e32 v252, 16, v158
	v_and_b32_e32 v253, 0xffff0000, v158
	v_lshlrev_b32_e32 v254, 16, v159
	v_and_b32_e32 v255, 0xffff0000, v159
	v_pk_add_f32 v[252:253], v[20:21], v[252:253]
	v_pk_add_f32 v[254:255], v[22:23], v[254:255]
	v_fmac_f32_e32 v173, v252, v252
	v_fmac_f32_e32 v173, v253, v253
	v_fmac_f32_e32 v173, v254, v254
	v_fmac_f32_e32 v173, v255, v255
	v_cvt_pk_bf16_f32 v190, v252, v253
	v_cvt_pk_bf16_f32 v191, v254, v255
	global_store_dwordx2 v142, v[190:191], s[96:97] offset:288
	v_add_u32_e32 v142, 0x8000, v142
	s_waitcnt vmcnt(31)
	v_lshlrev_b32_e32 v252, 16, v160
	v_and_b32_e32 v253, 0xffff0000, v160
	v_lshlrev_b32_e32 v254, 16, v161
	v_and_b32_e32 v255, 0xffff0000, v161
	v_pk_add_f32 v[252:253], v[40:41], v[252:253]
	v_pk_add_f32 v[254:255], v[42:43], v[254:255]
	v_mul_f32_e32 v174, v252, v252
	v_fmac_f32_e32 v174, v253, v253
	v_fmac_f32_e32 v174, v254, v254
	v_fmac_f32_e32 v174, v255, v255
	v_cvt_pk_bf16_f32 v190, v252, v253
	v_cvt_pk_bf16_f32 v191, v254, v255
	global_store_dwordx2 v142, v[190:191], s[96:97]
	s_waitcnt vmcnt(31)
	v_lshlrev_b32_e32 v252, 16, v162
	v_and_b32_e32 v253, 0xffff0000, v162
	v_lshlrev_b32_e32 v254, 16, v163
	v_and_b32_e32 v255, 0xffff0000, v163
	v_pk_add_f32 v[252:253], v[32:33], v[252:253]
	v_pk_add_f32 v[254:255], v[34:35], v[254:255]
	v_fmac_f32_e32 v174, v252, v252
	v_fmac_f32_e32 v174, v253, v253
	v_fmac_f32_e32 v174, v254, v254
	v_fmac_f32_e32 v174, v255, v255
	v_cvt_pk_bf16_f32 v190, v252, v253
	v_cvt_pk_bf16_f32 v191, v254, v255
	global_store_dwordx2 v142, v[190:191], s[96:97] offset:32
	s_waitcnt vmcnt(31)
	v_lshlrev_b32_e32 v252, 16, v164
	v_and_b32_e32 v253, 0xffff0000, v164
	v_lshlrev_b32_e32 v254, 16, v165
	v_and_b32_e32 v255, 0xffff0000, v165
	v_pk_add_f32 v[252:253], v[12:13], v[252:253]
	v_pk_add_f32 v[254:255], v[14:15], v[254:255]
	v_fmac_f32_e32 v174, v252, v252
	v_fmac_f32_e32 v174, v253, v253
	v_fmac_f32_e32 v174, v254, v254
	v_fmac_f32_e32 v174, v255, v255
	v_cvt_pk_bf16_f32 v190, v252, v253
	v_cvt_pk_bf16_f32 v191, v254, v255
	global_store_dwordx2 v142, v[190:191], s[96:97] offset:256
	s_waitcnt vmcnt(31)
	v_lshlrev_b32_e32 v252, 16, v166
	v_and_b32_e32 v253, 0xffff0000, v166
	v_lshlrev_b32_e32 v254, 16, v167
	v_and_b32_e32 v255, 0xffff0000, v167
	v_pk_add_f32 v[252:253], v[8:9], v[252:253]
	v_pk_add_f32 v[254:255], v[10:11], v[254:255]
	v_fmac_f32_e32 v174, v252, v252
	v_fmac_f32_e32 v174, v253, v253
	v_fmac_f32_e32 v174, v254, v254
	v_fmac_f32_e32 v174, v255, v255
	v_cvt_pk_bf16_f32 v190, v252, v253
	v_cvt_pk_bf16_f32 v191, v254, v255
	global_store_dwordx2 v142, v[190:191], s[96:97] offset:288
	v_add_u32_e32 v142, 0x8000, v142
	s_waitcnt vmcnt(31)
	v_lshlrev_b32_e32 v252, 16, v240
	v_and_b32_e32 v253, 0xffff0000, v240
	v_lshlrev_b32_e32 v254, 16, v241
	v_and_b32_e32 v255, 0xffff0000, v241
	v_pk_add_f32 v[252:253], v[24:25], v[252:253]
	v_pk_add_f32 v[254:255], v[26:27], v[254:255]
	v_mul_f32_e32 v175, v252, v252
	v_fmac_f32_e32 v175, v253, v253
	v_fmac_f32_e32 v175, v254, v254
	v_fmac_f32_e32 v175, v255, v255
	v_cvt_pk_bf16_f32 v190, v252, v253
	v_cvt_pk_bf16_f32 v191, v254, v255
	global_store_dwordx2 v142, v[190:191], s[96:97]
	s_waitcnt vmcnt(31)
	v_lshlrev_b32_e32 v252, 16, v242
	v_and_b32_e32 v253, 0xffff0000, v242
	v_lshlrev_b32_e32 v254, 16, v243
	v_and_b32_e32 v255, 0xffff0000, v243
	v_pk_add_f32 v[252:253], v[16:17], v[252:253]
	v_pk_add_f32 v[254:255], v[18:19], v[254:255]
	v_fmac_f32_e32 v175, v252, v252
	v_fmac_f32_e32 v175, v253, v253
	v_fmac_f32_e32 v175, v254, v254
	v_fmac_f32_e32 v175, v255, v255
	v_cvt_pk_bf16_f32 v190, v252, v253
	v_cvt_pk_bf16_f32 v191, v254, v255
	global_store_dwordx2 v142, v[190:191], s[96:97] offset:32
	s_waitcnt vmcnt(31)
	v_lshlrev_b32_e32 v252, 16, v244
	v_and_b32_e32 v253, 0xffff0000, v244
	v_lshlrev_b32_e32 v254, 16, v245
	v_and_b32_e32 v255, 0xffff0000, v245
	v_pk_add_f32 v[252:253], v[4:5], v[252:253]
	v_pk_add_f32 v[254:255], v[6:7], v[254:255]
	v_fmac_f32_e32 v175, v252, v252
	v_fmac_f32_e32 v175, v253, v253
	v_fmac_f32_e32 v175, v254, v254
	v_fmac_f32_e32 v175, v255, v255
	v_cvt_pk_bf16_f32 v190, v252, v253
	v_cvt_pk_bf16_f32 v191, v254, v255
	global_store_dwordx2 v142, v[190:191], s[96:97] offset:256
	s_waitcnt vmcnt(31)
	v_lshlrev_b32_e32 v252, 16, v246
	v_and_b32_e32 v253, 0xffff0000, v246
	v_lshlrev_b32_e32 v254, 16, v247
	v_and_b32_e32 v255, 0xffff0000, v247
	v_pk_add_f32 v[252:253], v[0:1], v[252:253]
	v_pk_add_f32 v[254:255], v[2:3], v[254:255]
	v_fmac_f32_e32 v175, v252, v252
	v_fmac_f32_e32 v175, v253, v253
	v_fmac_f32_e32 v175, v254, v254
	v_fmac_f32_e32 v175, v255, v255
	v_cvt_pk_bf16_f32 v190, v252, v253
	v_cvt_pk_bf16_f32 v191, v254, v255
	global_store_dwordx2 v142, v[190:191], s[96:97] offset:288
	s_branch .LresF_red

.LBB0_1600:
	v_and_b32_e32 v222, 15, v8
	v_bfe_u32 v223, v8, 4, 2
	v_lshlrev_b32_e32 v15, 6, v222
	v_lshlrev_b32_e32 v8, 2, v8
	s_and_b32 s58, s3, 3
	v_lshl_or_b32 v15, v223, 4, v15
	s_lshl_b32 s3, s52, 13
	v_and_b32_e32 v8, 32, v8
	s_add_i32 m0, s54, 0x18000
	v_lshl_add_u64 v[6:7], v[6:7], 0, s[24:25]
	v_bitop3_b32 v16, v15, s3, v8 bitop3:0xde
	s_lshl_b32 s3, s58, 12
	s_waitcnt vmcnt(4)
	s_barrier
	global_load_lds_dwordx4 v[6:7], off
	v_lshl_add_u64 v[4:5], v[4:5], 0, s[24:25]
	s_add_i32 m0, s54, 0x1a000
	s_add_i32 s59, s54, 0x8000
	s_add_i32 s60, s54, 0xa000
	global_load_lds_dwordx4 v[4:5], off
	v_lshl_add_u64 v[2:3], v[2:3], 0, s[24:25]
	s_mov_b32 m0, s59
	s_add_u32 s12, s44, 0x40080
	global_load_lds_dwordx4 v[2:3], off
	v_lshl_add_u64 v[0:1], v[0:1], 0, s[24:25]
	s_mov_b32 m0, s60
	s_addc_u32 s13, s45, 0
	global_load_lds_dwordx4 v[0:1], off
	s_add_i32 m0, s54, 0x1c000
	v_lshl_add_u64 v[0:1], s[12:13], 0, v[160:161]
	global_load_lds_dwordx4 v[0:1], off
	v_lshl_add_u64 v[0:1], s[12:13], 0, v[162:163]
	s_add_i32 m0, s54, 0x1e000
	s_ashr_i32 s61, s21, 31
	global_load_lds_dwordx4 v[0:1], off
	v_lshlrev_b32_e32 v0, 14, v9
	v_and_b32_e32 v0, 0xffff8000, v0
	v_lshl_add_u32 v0, v10, 11, v0
	v_and_b32_e32 v1, 1, v9
	s_add_u32 s12, s96, 0x19d93000
	v_lshl_or_b32 v0, v1, 6, v0
	s_addc_u32 s13, s97, 0
	v_lshl_add_u32 v164, v11, 1, v0
	v_lshlrev_b32_e32 v0, 14, v12
	s_add_u32 s14, s4, 0x5800
	v_and_b32_e32 v0, 0xffff8000, v0
	s_waitcnt vmcnt(0)
	s_addc_u32 s15, s5, 0
	v_lshl_add_u32 v0, v13, 11, v0
	v_and_b32_e32 v1, 1, v12
	s_add_u32 s16, s4, 0xb000
	v_lshl_or_b32 v0, v1, 6, v0
	v_bitop3_b32 v238, v15, s3, v8 bitop3:0xde
	s_addc_u32 s17, s5, 0
	v_mov_b32_e32 v165, v177
	v_lshl_add_u32 v166, v14, 1, v0
	v_mov_b32_e32 v167, v177
	s_mov_b32 s62, 0
	v_add_u32_e32 v239, 0, v16
	s_mov_b64 s[36:37], s[42:43]
	s_mov_b64 s[38:39], s[44:45]
	s_barrier
	s_branch .LBB0_1602

.LBB0_1609:
	s_add_u32 s44, s42, 0xfffc0080
	s_addc_u32 s45, s43, -1
	s_add_i32 s49, 0, 0x10000
	v_add_u32_e32 v116, s49, v238
	ds_read_b128 v[104:107], v116
	ds_read_b128 v[108:111], v116 offset:1024
	ds_read_b128 v[112:115], v116 offset:2048
	ds_read_b128 v[116:119], v116 offset:3072
	s_cmp_eq_u32 s23, 12
	s_cselect_b32 s47, s37, s45
	s_cselect_b32 s46, s36, s44
	s_cselect_b32 s45, s39, s19
	s_cselect_b32 s44, s38, s3
	v_lshl_add_u64 v[198:199], s[42:43], 0, v[164:165]
	s_add_i32 m0, s54, 0xc000
	ds_read_b128 v[120:123], v239
	ds_read_b128 v[124:127], v239 offset:1024
	ds_read_b128 v[128:131], v239 offset:2048
	ds_read_b128 v[132:135], v239 offset:3072
	ds_read_b128 v[168:171], v239 offset:4096
	ds_read_b128 v[172:175], v239 offset:5120
	ds_read_b128 v[190:193], v239 offset:6144
	ds_read_b128 v[194:197], v239 offset:7168
	global_load_lds_dwordx4 v[198:199], off
	v_lshl_add_u64 v[198:199], s[42:43], 0, v[166:167]
	s_add_i32 m0, s54, 0xe000
	s_nop 0
	global_load_lds_dwordx4 v[198:199], off
	s_waitcnt lgkmcnt(8)
	s_waitcnt vmcnt(10)
	s_barrier
	s_waitcnt lgkmcnt(0)
	s_setprio 1
	s_waitcnt lgkmcnt(0)
	v_mfma_f32_16x16x32_bf16 v[156:159], v[104:107], v[120:123], v[156:159]
	v_mfma_f32_16x16x32_bf16 v[60:63], v[112:115], v[120:123], v[60:63]
	v_mfma_f32_16x16x32_bf16 v[148:151], v[104:107], v[128:131], v[148:151]
	v_mfma_f32_16x16x32_bf16 v[52:55], v[112:115], v[128:131], v[52:55]
	v_mfma_f32_16x16x32_bf16 v[140:143], v[104:107], v[168:171], v[140:143]
	v_mfma_f32_16x16x32_bf16 v[44:47], v[112:115], v[168:171], v[44:47]
	v_mfma_f32_16x16x32_bf16 v[100:103], v[104:107], v[190:193], v[100:103]
	v_mfma_f32_16x16x32_bf16 v[36:39], v[112:115], v[190:193], v[36:39]
	v_mfma_f32_16x16x32_bf16 v[156:159], v[108:111], v[124:127], v[156:159]
	v_mfma_f32_16x16x32_bf16 v[60:63], v[116:119], v[124:127], v[60:63]
	v_mfma_f32_16x16x32_bf16 v[148:151], v[108:111], v[132:135], v[148:151]
	v_mfma_f32_16x16x32_bf16 v[52:55], v[116:119], v[132:135], v[52:55]
	v_mfma_f32_16x16x32_bf16 v[140:143], v[108:111], v[172:175], v[140:143]
	v_mfma_f32_16x16x32_bf16 v[44:47], v[116:119], v[172:175], v[44:47]
	v_mfma_f32_16x16x32_bf16 v[100:103], v[108:111], v[194:197], v[100:103]
	v_mfma_f32_16x16x32_bf16 v[36:39], v[116:119], v[194:197], v[36:39]
	s_setprio 0
	s_barrier
	s_add_i32 s63, 0, 0x14000
	s_add_i32 s49, s49, s53
	v_add_u32_e32 v176, s63, v238
	v_lshl_add_u64 v[218:219], s[44:45], 0, v[160:161]
	s_mov_b32 m0, s49
	ds_read_b128 v[198:201], v176
	ds_read_b128 v[202:205], v176 offset:1024
	ds_read_b128 v[206:209], v176 offset:2048
	ds_read_b128 v[210:213], v176 offset:3072
	global_load_lds_dwordx4 v[218:219], off
	v_lshl_add_u64 v[220:221], s[44:45], 0, v[162:163]
	s_add_i32 m0, s49, 0x2000
	s_nop 0
	global_load_lds_dwordx4 v[220:221], off
	s_waitcnt vmcnt(10)
	s_barrier
	s_waitcnt lgkmcnt(0)
	s_setprio 1
	s_waitcnt lgkmcnt(0)
	v_mfma_f32_16x16x32_bf16 v[152:155], v[198:201], v[120:123], v[152:155]
	v_mfma_f32_16x16x32_bf16 v[56:59], v[206:209], v[120:123], v[56:59]
	v_mfma_f32_16x16x32_bf16 v[48:51], v[206:209], v[128:131], v[48:51]
	v_mfma_f32_16x16x32_bf16 v[40:43], v[206:209], v[168:171], v[40:43]
	v_mfma_f32_16x16x32_bf16 v[96:99], v[198:201], v[190:193], v[96:99]
	v_mfma_f32_16x16x32_bf16 v[32:35], v[206:209], v[190:193], v[32:35]
	v_mfma_f32_16x16x32_bf16 v[152:155], v[202:205], v[124:127], v[152:155]
	v_mfma_f32_16x16x32_bf16 v[56:59], v[210:213], v[124:127], v[56:59]
	v_mfma_f32_16x16x32_bf16 v[120:123], v[198:201], v[128:131], v[144:147]
	v_mfma_f32_16x16x32_bf16 v[48:51], v[210:213], v[132:135], v[48:51]
	v_mfma_f32_16x16x32_bf16 v[124:127], v[198:201], v[168:171], v[136:139]
	v_mfma_f32_16x16x32_bf16 v[40:43], v[210:213], v[172:175], v[40:43]
	v_mfma_f32_16x16x32_bf16 v[96:99], v[202:205], v[194:197], v[96:99]
	v_mfma_f32_16x16x32_bf16 v[32:35], v[210:213], v[194:197], v[32:35]
	v_mfma_f32_16x16x32_bf16 v[120:123], v[202:205], v[132:135], v[120:123]
	v_mfma_f32_16x16x32_bf16 v[124:127], v[202:205], v[172:175], v[124:127]
	s_setprio 0
	s_mov_b32 m0, s54
	v_lshl_add_u64 v[240:241], s[46:47], 0, v[160:161]
	s_barrier
	ds_read_b128 v[128:131], v239 offset:16384
	ds_read_b128 v[132:135], v239 offset:17408
	ds_read_b128 v[136:139], v239 offset:18432
	ds_read_b128 v[144:147], v239 offset:19456
	ds_read_b128 v[168:171], v239 offset:20480
	ds_read_b128 v[172:175], v239 offset:21504
	ds_read_b128 v[190:193], v239 offset:22528
	ds_read_b128 v[194:197], v239 offset:23552
	global_load_lds_dwordx4 v[240:241], off
	v_lshl_add_u64 v[242:243], s[46:47], 0, v[162:163]
	s_mov_b32 m0, s55
	s_nop 0
	global_load_lds_dwordx4 v[242:243], off
	s_barrier
	s_waitcnt lgkmcnt(0)
	s_setprio 1
	s_waitcnt lgkmcnt(0)
	v_mfma_f32_16x16x32_bf16 v[92:95], v[104:107], v[128:131], v[92:95]
	v_mfma_f32_16x16x32_bf16 v[28:31], v[112:115], v[128:131], v[28:31]
	v_mfma_f32_16x16x32_bf16 v[84:87], v[104:107], v[136:139], v[84:87]
	v_mfma_f32_16x16x32_bf16 v[20:23], v[112:115], v[136:139], v[20:23]
	v_mfma_f32_16x16x32_bf16 v[76:79], v[104:107], v[168:171], v[76:79]
	v_mfma_f32_16x16x32_bf16 v[12:15], v[112:115], v[168:171], v[12:15]
	v_mfma_f32_16x16x32_bf16 v[68:71], v[104:107], v[190:193], v[68:71]
	v_mfma_f32_16x16x32_bf16 v[4:7], v[112:115], v[190:193], v[4:7]
	v_mfma_f32_16x16x32_bf16 v[92:95], v[108:111], v[132:135], v[92:95]
	v_mfma_f32_16x16x32_bf16 v[28:31], v[116:119], v[132:135], v[28:31]
	v_mfma_f32_16x16x32_bf16 v[84:87], v[108:111], v[144:147], v[84:87]
	v_mfma_f32_16x16x32_bf16 v[20:23], v[116:119], v[144:147], v[20:23]
	v_mfma_f32_16x16x32_bf16 v[76:79], v[108:111], v[172:175], v[76:79]
	v_mfma_f32_16x16x32_bf16 v[12:15], v[116:119], v[172:175], v[12:15]
	v_mfma_f32_16x16x32_bf16 v[68:71], v[108:111], v[194:197], v[68:71]
	v_mfma_f32_16x16x32_bf16 v[4:7], v[116:119], v[194:197], v[4:7]
	s_setprio 0
	s_barrier
	s_add_u32 s64, s44, 0x40000
	s_addc_u32 s65, s45, 0
	s_add_i32 s49, s63, s53
	v_lshl_add_u64 v[104:105], s[64:65], 0, v[160:161]
	s_mov_b32 m0, s49
	s_nop 0
	global_load_lds_dwordx4 v[104:105], off
	v_lshl_add_u64 v[104:105], s[64:65], 0, v[162:163]
	s_add_i32 m0, s49, 0x2000
	s_nop 0
	global_load_lds_dwordx4 v[104:105], off
	s_waitcnt vmcnt(10)
	s_barrier
	s_setprio 1
	v_mfma_f32_16x16x32_bf16 v[88:91], v[198:201], v[128:131], v[88:91]
	v_mfma_f32_16x16x32_bf16 v[24:27], v[206:209], v[128:131], v[24:27]
	v_mfma_f32_16x16x32_bf16 v[80:83], v[198:201], v[136:139], v[80:83]
	v_mfma_f32_16x16x32_bf16 v[16:19], v[206:209], v[136:139], v[16:19]
	v_mfma_f32_16x16x32_bf16 v[72:75], v[198:201], v[168:171], v[72:75]
	v_mfma_f32_16x16x32_bf16 v[8:11], v[206:209], v[168:171], v[8:11]
	v_mfma_f32_16x16x32_bf16 v[64:67], v[198:201], v[190:193], v[64:67]
	v_mfma_f32_16x16x32_bf16 v[0:3], v[206:209], v[190:193], v[0:3]
	v_mfma_f32_16x16x32_bf16 v[88:91], v[202:205], v[132:135], v[88:91]
	v_mfma_f32_16x16x32_bf16 v[24:27], v[210:213], v[132:135], v[24:27]
	v_mfma_f32_16x16x32_bf16 v[80:83], v[202:205], v[144:147], v[80:83]
	v_mfma_f32_16x16x32_bf16 v[16:19], v[210:213], v[144:147], v[16:19]
	v_mfma_f32_16x16x32_bf16 v[72:75], v[202:205], v[172:175], v[72:75]
	v_mfma_f32_16x16x32_bf16 v[8:11], v[210:213], v[172:175], v[8:11]
	v_mfma_f32_16x16x32_bf16 v[64:67], v[202:205], v[194:197], v[64:67]
	v_mfma_f32_16x16x32_bf16 v[0:3], v[210:213], v[194:197], v[0:3]
	s_setprio 0
	s_add_i32 s49, 0, 0x18000
	v_add_u32_e32 v116, s49, v238
	s_barrier
	ds_read_b128 v[104:107], v116
	ds_read_b128 v[108:111], v116 offset:1024
	ds_read_b128 v[112:115], v116 offset:2048
	ds_read_b128 v[116:119], v116 offset:3072
	s_add_u32 s46, s46, 0x40000
	s_addc_u32 s47, s47, 0
	s_mov_b32 m0, s56
	v_lshl_add_u64 v[144:145], s[46:47], 0, v[160:161]
	ds_read_b128 v[128:131], v239 offset:32768
	ds_read_b128 v[132:135], v239 offset:33792
	ds_read_b128 v[136:139], v239 offset:34816
	ds_read_b128 v[168:171], v239 offset:35840
	ds_read_b128 v[172:175], v239 offset:36864
	ds_read_b128 v[190:193], v239 offset:37888
	ds_read_b128 v[194:197], v239 offset:38912
	ds_read_b128 v[198:201], v239 offset:39936
	global_load_lds_dwordx4 v[144:145], off
	v_lshl_add_u64 v[144:145], s[46:47], 0, v[162:163]
	s_mov_b32 m0, s57
	s_nop 0
	global_load_lds_dwordx4 v[144:145], off
	s_waitcnt lgkmcnt(8)
	s_waitcnt vmcnt(10)
	s_barrier
	s_waitcnt lgkmcnt(0)
	s_setprio 1
	s_waitcnt lgkmcnt(0)
	v_mfma_f32_16x16x32_bf16 v[144:147], v[104:107], v[128:131], v[156:159]
	v_mfma_f32_16x16x32_bf16 v[156:159], v[108:111], v[132:135], v[144:147]
	v_mfma_f32_16x16x32_bf16 v[60:63], v[112:115], v[128:131], v[60:63]
	v_mfma_f32_16x16x32_bf16 v[144:147], v[104:107], v[136:139], v[148:151]
	v_mfma_f32_16x16x32_bf16 v[52:55], v[112:115], v[136:139], v[52:55]
	v_mfma_f32_16x16x32_bf16 v[140:143], v[104:107], v[172:175], v[140:143]
	v_mfma_f32_16x16x32_bf16 v[44:47], v[112:115], v[172:175], v[44:47]
	v_mfma_f32_16x16x32_bf16 v[100:103], v[104:107], v[194:197], v[100:103]
	v_mfma_f32_16x16x32_bf16 v[36:39], v[112:115], v[194:197], v[36:39]
	v_mfma_f32_16x16x32_bf16 v[60:63], v[116:119], v[132:135], v[60:63]
	v_mfma_f32_16x16x32_bf16 v[148:151], v[108:111], v[168:171], v[144:147]
	v_mfma_f32_16x16x32_bf16 v[52:55], v[116:119], v[168:171], v[52:55]
	v_mfma_f32_16x16x32_bf16 v[140:143], v[108:111], v[190:193], v[140:143]
	v_mfma_f32_16x16x32_bf16 v[44:47], v[116:119], v[190:193], v[44:47]
	v_mfma_f32_16x16x32_bf16 v[100:103], v[108:111], v[198:201], v[100:103]
	v_mfma_f32_16x16x32_bf16 v[36:39], v[116:119], v[198:201], v[36:39]
	s_setprio 0
	s_barrier
	s_add_i32 s46, 0, 0x1c000
	v_add_u32_e32 v144, s46, v238
	s_add_i32 s47, s49, s53
	ds_read_b128 v[202:205], v144
	ds_read_b128 v[206:209], v144 offset:1024
	ds_read_b128 v[210:213], v144 offset:2048
	ds_read_b128 v[214:217], v144 offset:3072
	v_lshl_add_u64 v[144:145], v[218:219], 0, s[24:25]
	s_mov_b32 m0, s47
	s_nop 0
	global_load_lds_dwordx4 v[144:145], off
	v_lshl_add_u64 v[144:145], v[220:221], 0, s[24:25]
	s_add_i32 m0, s47, 0x2000
	s_nop 0
	global_load_lds_dwordx4 v[144:145], off
	s_waitcnt vmcnt(10)
	s_barrier
	s_waitcnt lgkmcnt(0)
	s_setprio 1
	s_waitcnt lgkmcnt(0)
	v_mfma_f32_16x16x32_bf16 v[144:147], v[202:205], v[128:131], v[152:155]
	v_mfma_f32_16x16x32_bf16 v[120:123], v[202:205], v[136:139], v[120:123]
	v_mfma_f32_16x16x32_bf16 v[152:155], v[206:209], v[132:135], v[144:147]
	v_mfma_f32_16x16x32_bf16 v[56:59], v[210:213], v[128:131], v[56:59]
	v_mfma_f32_16x16x32_bf16 v[144:147], v[206:209], v[168:171], v[120:123]
	v_mfma_f32_16x16x32_bf16 v[48:51], v[210:213], v[136:139], v[48:51]
	v_mfma_f32_16x16x32_bf16 v[120:123], v[202:205], v[172:175], v[124:127]
	v_mfma_f32_16x16x32_bf16 v[40:43], v[210:213], v[172:175], v[40:43]
	v_mfma_f32_16x16x32_bf16 v[96:99], v[202:205], v[194:197], v[96:99]
	v_mfma_f32_16x16x32_bf16 v[32:35], v[210:213], v[194:197], v[32:35]
	v_mfma_f32_16x16x32_bf16 v[56:59], v[214:217], v[132:135], v[56:59]
	v_mfma_f32_16x16x32_bf16 v[48:51], v[214:217], v[168:171], v[48:51]
	v_mfma_f32_16x16x32_bf16 v[136:139], v[206:209], v[190:193], v[120:123]
	v_mfma_f32_16x16x32_bf16 v[40:43], v[214:217], v[190:193], v[40:43]
	v_mfma_f32_16x16x32_bf16 v[96:99], v[206:209], v[198:201], v[96:99]
	v_mfma_f32_16x16x32_bf16 v[32:35], v[214:217], v[198:201], v[32:35]
	s_setprio 0
	s_mov_b32 m0, s59
	v_lshl_add_u64 v[198:199], v[240:241], 0, s[24:25]
	s_barrier
	ds_read_b128 v[120:123], v239 offset:49152
	ds_read_b128 v[124:127], v239 offset:50176
	ds_read_b128 v[128:131], v239 offset:51200
	ds_read_b128 v[132:135], v239 offset:52224
	ds_read_b128 v[168:171], v239 offset:53248
	ds_read_b128 v[172:175], v239 offset:54272
	ds_read_b128 v[190:193], v239 offset:55296
	ds_read_b128 v[194:197], v239 offset:56320
	global_load_lds_dwordx4 v[198:199], off
	v_lshl_add_u64 v[198:199], v[242:243], 0, s[24:25]
	s_mov_b32 m0, s60
	s_nop 0
	global_load_lds_dwordx4 v[198:199], off
	s_barrier
	s_waitcnt lgkmcnt(0)
	s_setprio 1
	s_waitcnt lgkmcnt(0)
	v_mfma_f32_16x16x32_bf16 v[92:95], v[104:107], v[120:123], v[92:95]
	v_mfma_f32_16x16x32_bf16 v[28:31], v[112:115], v[120:123], v[28:31]
	v_mfma_f32_16x16x32_bf16 v[84:87], v[104:107], v[128:131], v[84:87]
	v_mfma_f32_16x16x32_bf16 v[20:23], v[112:115], v[128:131], v[20:23]
	v_mfma_f32_16x16x32_bf16 v[76:79], v[104:107], v[168:171], v[76:79]
	v_mfma_f32_16x16x32_bf16 v[12:15], v[112:115], v[168:171], v[12:15]
	v_mfma_f32_16x16x32_bf16 v[68:71], v[104:107], v[190:193], v[68:71]
	v_mfma_f32_16x16x32_bf16 v[4:7], v[112:115], v[190:193], v[4:7]
	v_mfma_f32_16x16x32_bf16 v[92:95], v[108:111], v[124:127], v[92:95]
	v_mfma_f32_16x16x32_bf16 v[28:31], v[116:119], v[124:127], v[28:31]
	v_mfma_f32_16x16x32_bf16 v[84:87], v[108:111], v[132:135], v[84:87]
	v_mfma_f32_16x16x32_bf16 v[20:23], v[116:119], v[132:135], v[20:23]
	v_mfma_f32_16x16x32_bf16 v[76:79], v[108:111], v[172:175], v[76:79]
	v_mfma_f32_16x16x32_bf16 v[12:15], v[116:119], v[172:175], v[12:15]
	v_mfma_f32_16x16x32_bf16 v[68:71], v[108:111], v[194:197], v[68:71]
	v_mfma_f32_16x16x32_bf16 v[4:7], v[116:119], v[194:197], v[4:7]
	s_setprio 0
	s_barrier
	s_add_u32 s44, s44, 0x40080
	s_addc_u32 s45, s45, 0
	s_add_i32 s46, s46, s53
	v_lshl_add_u64 v[104:105], s[44:45], 0, v[160:161]
	s_mov_b32 m0, s46
	s_nop 0
	global_load_lds_dwordx4 v[104:105], off
	v_lshl_add_u64 v[104:105], s[44:45], 0, v[162:163]
	s_add_i32 m0, s46, 0x2000
	s_nop 0
	global_load_lds_dwordx4 v[104:105], off
	s_waitcnt vmcnt(10)
	s_barrier
	s_setprio 1
	v_mfma_f32_16x16x32_bf16 v[88:91], v[202:205], v[120:123], v[88:91]
	v_mfma_f32_16x16x32_bf16 v[24:27], v[210:213], v[120:123], v[24:27]
	v_mfma_f32_16x16x32_bf16 v[80:83], v[202:205], v[128:131], v[80:83]
	v_mfma_f32_16x16x32_bf16 v[16:19], v[210:213], v[128:131], v[16:19]
	v_mfma_f32_16x16x32_bf16 v[72:75], v[202:205], v[168:171], v[72:75]
	v_mfma_f32_16x16x32_bf16 v[8:11], v[210:213], v[168:171], v[8:11]
	v_mfma_f32_16x16x32_bf16 v[64:67], v[202:205], v[190:193], v[64:67]
	v_mfma_f32_16x16x32_bf16 v[0:3], v[210:213], v[190:193], v[0:3]
	v_mfma_f32_16x16x32_bf16 v[88:91], v[206:209], v[124:127], v[88:91]
	v_mfma_f32_16x16x32_bf16 v[24:27], v[214:217], v[124:127], v[24:27]
	v_mfma_f32_16x16x32_bf16 v[80:83], v[206:209], v[132:135], v[80:83]
	v_mfma_f32_16x16x32_bf16 v[16:19], v[214:217], v[132:135], v[16:19]
	v_mfma_f32_16x16x32_bf16 v[72:75], v[206:209], v[172:175], v[72:75]
	v_mfma_f32_16x16x32_bf16 v[8:11], v[214:217], v[172:175], v[8:11]
	v_mfma_f32_16x16x32_bf16 v[64:67], v[206:209], v[194:197], v[64:67]
	v_mfma_f32_16x16x32_bf16 v[0:3], v[214:217], v[194:197], v[0:3]
	s_setprio 0
	s_add_i32 s23, s23, 2
	s_add_u32 s42, s42, 0x100
	s_addc_u32 s43, s43, 0
	s_add_u32 s3, s3, 0x100
	s_addc_u32 s19, s19, 0
	s_cmp_gt_u32 s23, 13
	s_barrier
	s_cbranch_scc0 .LBB0_1609
	v_mov_b32_e32 v106, v223
	s_mov_b32 s3, s58
	v_mov_b32_e32 v200, v222
	s_mov_b32 s19, s52
	s_lshl_b32 s23, s2, 8
	s_lshl_b32 s42, s19, 6
	s_add_i32 s42, s42, s23
	s_lshl_b32 s23, s48, 7
	s_lshl_b32 s3, s3, 5
	s_add_i32 s3, s3, s23
	v_lshl_add_u32 v170, v106, 2, s3
	v_ashrrev_i32_e32 v171, 31, v170
	v_lshlrev_b64 v[106:107], 2, v[170:171]
	v_add_u32_e32 v104, s42, v200
	v_lshl_add_u64 v[192:193], s[4:5], 0, v[106:107]
	s_movk_i32 s3, 0x2000
	v_ashrrev_i32_e32 v105, 31, v104
	v_add_co_u32_e32 v120, vcc, s3, v192
	v_lshl_add_u64 v[104:105], v[104:105], 2, s[10:11]
	v_lshl_add_u64 v[190:191], s[14:15], 0, v[106:107]
	v_addc_co_u32_e32 v121, vcc, 0, v193, vcc
	global_load_dword v168, v[104:105], off
	v_add_co_u32_e32 v124, vcc, s3, v190
	v_lshl_add_u64 v[174:175], s[16:17], 0, v[106:107]
	s_nop 0
	v_addc_co_u32_e32 v125, vcc, 0, v191, vcc
	v_add_co_u32_e32 v128, vcc, s3, v174
	v_lshl_add_u64 v[172:173], s[6:7], 0, v[106:107]
	s_nop 0
	v_addc_co_u32_e32 v129, vcc, 0, v175, vcc
	v_add_co_u32_e32 v132, vcc, s3, v172
	global_load_dword v245, v[104:105], off offset:64
	global_load_dword v244, v[104:105], off offset:128
	global_load_dword v176, v[104:105], off offset:192
	global_load_dword v243, v[104:105], off offset:512
	global_load_dword v242, v[104:105], off offset:576
	global_load_dword v241, v[104:105], off offset:640
	global_load_dword v169, v[104:105], off offset:704
	v_addc_co_u32_e32 v133, vcc, 0, v173, vcc
	global_load_dwordx4 v[104:107], v[192:193], off
	global_load_dwordx4 v[108:111], v[190:191], off
	global_load_dwordx4 v[112:115], v[174:175], off
	global_load_dwordx4 v[116:119], v[172:173], off
	s_nop 0
	global_load_dwordx4 v[120:123], v[120:121], off offset:3072
	s_nop 0
	global_load_dwordx4 v[124:127], v[124:125], off offset:3072
	s_nop 0
	global_load_dwordx4 v[128:131], v[128:129], off offset:3072
	s_nop 0
	global_load_dwordx4 v[132:135], v[132:133], off offset:3072
	s_lshl_b32 s2, s2, 2
	v_readlane_b32 s42, v249, 58
	s_add_i32 s2, s19, s2
	v_readlane_b32 s43, v249, 59
	v_cmp_lt_i32_e64 s[44:45], 1, v200
	v_lshl_add_u32 v240, s2, 6, v200
	v_lshl_add_u64 v[196:197], v[170:171], 1, s[42:43]
	s_waitcnt vmcnt(0)
	v_fmamk_f32 v168, v168, 0x3a800000, v228
	v_rsq_f32_e32 v168, v168
	s_nop 0
	v_pk_mul_f32 v[208:209], v[156:157], v[168:169] op_sel_hi:[1,0]
	v_pk_mul_f32 v[204:205], v[152:153], v[168:169] op_sel_hi:[1,0]
	v_pk_mul_f32 v[206:207], v[158:159], v[168:169] op_sel_hi:[1,0]
	v_pk_mul_f32 v[210:211], v[154:155], v[168:169] op_sel_hi:[1,0]
	v_mov_b32_dpp v194, v208 row_ror:1 row_mask:0xf bank_mask:0xf
	v_mov_b32_dpp v202, v208 row_ror:2 row_mask:0xf bank_mask:0xf
	v_mov_b32_dpp v195, v209 row_ror:1 row_mask:0xf bank_mask:0xf
	v_mov_b32_dpp v203, v209 row_ror:2 row_mask:0xf bank_mask:0xf
	v_mov_b32_dpp v214, v204 row_ror:1 row_mask:0xf bank_mask:0xf
	v_mov_b32_dpp v216, v204 row_ror:2 row_mask:0xf bank_mask:0xf
	v_mov_b32_dpp v215, v205 row_ror:1 row_mask:0xf bank_mask:0xf
	v_mov_b32_dpp v217, v205 row_ror:2 row_mask:0xf bank_mask:0xf
	v_mov_b32_dpp v198, v206 row_ror:1 row_mask:0xf bank_mask:0xf
	v_mov_b32_dpp v212, v206 row_ror:2 row_mask:0xf bank_mask:0xf
	v_mov_b32_dpp v199, v207 row_ror:1 row_mask:0xf bank_mask:0xf
	v_mov_b32_dpp v213, v207 row_ror:2 row_mask:0xf bank_mask:0xf
	v_mov_b32_dpp v218, v210 row_ror:1 row_mask:0xf bank_mask:0xf
	v_mov_b32_dpp v220, v210 row_ror:2 row_mask:0xf bank_mask:0xf
	v_mov_b32_dpp v219, v211 row_ror:1 row_mask:0xf bank_mask:0xf
	v_mov_b32_dpp v221, v211 row_ror:2 row_mask:0xf bank_mask:0xf
	v_mov_b32_dpp v194, v208 row_shr:1 row_mask:0xf bank_mask:0xf
	v_mov_b32_dpp v202, v208 row_shr:2 row_mask:0xf bank_mask:0xf
	v_mov_b32_dpp v195, v209 row_shr:1 row_mask:0xf bank_mask:0xf
	v_mov_b32_dpp v203, v209 row_shr:2 row_mask:0xf bank_mask:0xf
	v_mov_b32_dpp v214, v204 row_shr:1 row_mask:0xf bank_mask:0xf
	v_mov_b32_dpp v216, v204 row_shr:2 row_mask:0xf bank_mask:0xf
	v_mov_b32_dpp v215, v205 row_shr:1 row_mask:0xf bank_mask:0xf
	v_mov_b32_dpp v217, v205 row_shr:2 row_mask:0xf bank_mask:0xf
	v_mov_b32_dpp v198, v206 row_shr:1 row_mask:0xf bank_mask:0xf
	v_mov_b32_dpp v212, v206 row_shr:2 row_mask:0xf bank_mask:0xf
	v_mov_b32_dpp v199, v207 row_shr:1 row_mask:0xf bank_mask:0xf
	v_mov_b32_dpp v213, v207 row_shr:2 row_mask:0xf bank_mask:0xf
	v_mov_b32_dpp v218, v210 row_shr:1 row_mask:0xf bank_mask:0xf
	v_mov_b32_dpp v220, v210 row_shr:2 row_mask:0xf bank_mask:0xf
	v_mov_b32_dpp v219, v211 row_shr:1 row_mask:0xf bank_mask:0xf
	v_mov_b32_dpp v221, v211 row_shr:2 row_mask:0xf bank_mask:0xf
	s_and_saveexec_b64 s[42:43], s[44:45]
	s_cbranch_execz .LBB0_1612
	v_pk_fma_f32 v[246:247], v[208:209], v[112:113], v[116:117]
	s_movk_i32 s3, 0x1600
	v_pk_fma_f32 v[194:195], v[108:109], v[194:195], v[246:247]
	v_pk_fma_f32 v[246:247], v[204:205], v[128:129], v[132:133]
	v_pk_fma_f32 v[194:195], v[104:105], v[202:203], v[194:195]
	v_pk_fma_f32 v[214:215], v[124:125], v[214:215], v[246:247]
	v_mul_f32_e32 v201, 0xbfb8aa3b, v194
	v_mul_f32_e32 v202, 0xbfb8aa3b, v195
	v_exp_f32_e32 v201, v201
	v_exp_f32_e32 v202, v202
	v_pk_fma_f32 v[214:215], v[120:121], v[216:217], v[214:215]
	v_add_f32_e32 v201, 1.0, v201
	v_add_f32_e32 v203, 1.0, v202
	v_rcp_f32_e32 v202, v201
	v_rcp_f32_e32 v203, v203
	s_nop 0
	v_pk_mul_f32 v[194:195], v[194:195], v[202:203]
	v_pk_fma_f32 v[202:203], v[206:207], v[114:115], v[118:119]
	v_pk_mul_f32 v[194:195], v[194:195], v[214:215]
	v_pk_fma_f32 v[198:199], v[110:111], v[198:199], v[202:203]
	v_cvt_pk_bf16_f32 v194, v194, v195
	v_pk_fma_f32 v[198:199], v[106:107], v[212:213], v[198:199]
	v_pk_fma_f32 v[212:213], v[210:211], v[130:131], v[134:135]
	v_mul_f32_e32 v201, 0xbfb8aa3b, v198
	v_exp_f32_e32 v201, v201
	v_mul_f32_e32 v202, 0xbfb8aa3b, v199
	v_exp_f32_e32 v203, v202
	v_pk_fma_f32 v[212:213], v[126:127], v[218:219], v[212:213]
	v_add_f32_e32 v201, 1.0, v201
	v_rcp_f32_e32 v202, v201
	v_add_f32_e32 v201, 1.0, v203
	v_rcp_f32_e32 v203, v201
	v_pk_fma_f32 v[212:213], v[122:123], v[220:221], v[212:213]
	v_pk_mul_f32 v[198:199], v[198:199], v[202:203]
	s_nop 0
	v_pk_mul_f32 v[198:199], v[198:199], v[212:213]
	s_nop 0
	v_cvt_pk_bf16_f32 v195, v198, v199
	v_mad_i64_i32 v[198:199], s[46:47], v240, s3, v[196:197]
	global_store_dwordx2 v[198:199], v[194:195], off

.LBB0_1775:
	v_and_b32_e32 v160, 15, v8
	s_add_u32 s4, s96, 0x1f30e800
	v_bfe_u32 v161, v8, 4, 2
	v_lshlrev_b32_e32 v17, 6, v160
	v_lshlrev_b32_e32 v8, 2, v8
	s_addc_u32 s5, s97, 0
	s_and_b32 s39, s2, 3
	v_lshl_or_b32 v17, v161, 4, v17
	s_lshl_b32 s2, s28, 13
	v_and_b32_e32 v8, 32, v8
	s_add_i32 m0, s35, 0x18000
	v_lshl_add_u64 v[6:7], v[6:7], 0, s[24:25]
	v_bitop3_b32 v18, v17, s2, v8 bitop3:0xde
	s_lshl_b32 s2, s39, 12
	s_waitcnt vmcnt(4)
	s_barrier
	global_load_lds_dwordx4 v[6:7], off
	v_lshl_add_u64 v[4:5], v[4:5], 0, s[24:25]
	s_add_i32 m0, s35, 0x1a000
	s_add_i32 s46, s35, 0x8000
	s_add_i32 s47, s35, 0xa000
	v_bitop3_b32 v162, v17, s2, v8 bitop3:0xde
	global_load_lds_dwordx4 v[4:5], off
	v_lshl_add_u64 v[2:3], v[2:3], 0, s[24:25]
	s_mov_b32 m0, s46
	s_add_u32 s2, s14, 0xb0080
	global_load_lds_dwordx4 v[2:3], off
	v_lshl_add_u64 v[0:1], v[0:1], 0, s[24:25]
	s_mov_b32 m0, s47
	s_addc_u32 s3, s15, 0
	global_load_lds_dwordx4 v[0:1], off
	s_add_i32 m0, s35, 0x1c000
	v_lshl_add_u64 v[0:1], s[2:3], 0, v[176:177]
	global_load_lds_dwordx4 v[0:1], off
	v_lshl_add_u64 v[0:1], s[2:3], 0, v[144:145]
	s_add_i32 m0, s35, 0x1e000
	s_not_b32 s2, s21
	global_load_lds_dwordx4 v[0:1], off
	v_readlane_b32 s3, v250, 18
	s_ashr_i32 s48, s21, 31
	s_add_i32 s8, s3, s2
	s_cmp_lg_u64 s[26:27], 0
	v_readlane_b32 s6, v250, 54
	s_cselect_b64 s[2:3], -1, 0
	v_readlane_b32 s7, v250, 55
	s_and_b64 s[6:7], s[6:7], s[2:3]
	s_ashr_i32 s2, s8, 31
	s_abs_i32 s3, s8
	v_readlane_b32 s8, v250, 14
	s_mul_hi_u32 s8, s3, s8
	v_readlane_b32 s11, v250, 13
	s_mul_i32 s9, s8, s11
	s_sub_i32 s3, s3, s9
	s_xor_b32 s2, s2, s81
	s_add_i32 s9, s8, 1
	s_sub_i32 s10, s3, s11
	s_cmp_ge_u32 s3, s11
	s_cselect_b32 s8, s9, s8
	s_cselect_b32 s3, s10, s3
	s_add_i32 s9, s8, 1
	s_cmp_ge_u32 s3, s11
	s_cselect_b32 s3, s9, s8
	s_movk_i32 s8, 0xb00
	s_xor_b32 s3, s3, s2
	v_lshrrev_b32_e32 v1, 1, v9
	v_mul_lo_u32 v0, v11, s8
	s_mov_b32 s9, 0xb000
	s_sub_i32 s49, s3, s2
	v_mad_u64_u32 v[0:1], s[2:3], v1, s9, v[0:1]
	v_or_b32_e32 v0, v0, v10
	v_add_lshl_u32 v0, v0, v12, 1
	v_mov_b32_e32 v1, v177
	s_mov_b64 s[10:11], 0xb0080
	v_lshl_add_u64 v[146:147], v[0:1], 0, s[10:11]
	v_lshrrev_b32_e32 v1, 1, v13
	v_mul_lo_u32 v0, v15, s8
	v_mad_u64_u32 v[0:1], s[2:3], v1, s9, v[0:1]
	s_waitcnt vmcnt(0)
	v_or_b32_e32 v0, v0, v14
	v_add_lshl_u32 v0, v0, v16, 1
	v_mov_b32_e32 v1, v177
	v_lshl_add_u64 v[148:149], v[0:1], 0, s[10:11]
	s_mov_b32 s51, 0
	v_add_u32_e32 v163, 0, v18
	s_barrier
	s_branch .LBB0_1777

.LBB0_1787:
	s_add_i32 s60, s16, 2
	s_add_u32 s14, s12, 0x100
	s_addc_u32 s15, s13, 0
	s_add_i32 s61, 0, 0x10000
	v_add_u32_e32 v140, s61, v162
	s_waitcnt lgkmcnt(0)
	ds_read_b128 v[128:131], v140
	ds_read_b128 v[132:135], v140 offset:1024
	ds_read_b128 v[136:139], v140 offset:2048
	ds_read_b128 v[140:143], v140 offset:3072
	s_cmp_eq_u32 s57, s16
	s_cselect_b32 s16, s56, s58
	s_cselect_b32 s19, s43, s15
	s_cselect_b32 s18, s44, s14
	s_cselect_b32 s17, s45, s59
	v_lshl_add_u64 v[158:159], s[12:13], 0, v[146:147]
	s_add_i32 m0, s35, 0xc000
	ds_read_b128 v[150:153], v163
	ds_read_b128 v[154:157], v163 offset:1024
	ds_read_b128 v[164:167], v163 offset:2048
	ds_read_b128 v[168:171], v163 offset:3072
	ds_read_b128 v[172:175], v163 offset:4096
	ds_read_b128 v[190:193], v163 offset:5120
	ds_read_b128 v[194:197], v163 offset:6144
	ds_read_b128 v[198:201], v163 offset:7168
	global_load_lds_dwordx4 v[158:159], off
	v_lshl_add_u64 v[158:159], s[12:13], 0, v[148:149]
	s_add_i32 m0, s35, 0xe000
	s_nop 0
	global_load_lds_dwordx4 v[158:159], off
	s_waitcnt lgkmcnt(8)
	s_waitcnt vmcnt(10)
	s_barrier
	s_waitcnt lgkmcnt(0)
	s_setprio 1
	s_waitcnt lgkmcnt(0)
	v_mfma_f32_16x16x32_bf16 v[124:127], v[128:131], v[150:153], v[124:127]
	v_mfma_f32_16x16x32_bf16 v[120:123], v[136:139], v[150:153], v[120:123]
	v_mfma_f32_16x16x32_bf16 v[116:119], v[128:131], v[164:167], v[116:119]
	v_mfma_f32_16x16x32_bf16 v[112:115], v[136:139], v[164:167], v[112:115]
	v_mfma_f32_16x16x32_bf16 v[104:107], v[128:131], v[172:175], v[104:107]
	v_mfma_f32_16x16x32_bf16 v[96:99], v[136:139], v[172:175], v[96:99]
	v_mfma_f32_16x16x32_bf16 v[88:91], v[128:131], v[194:197], v[88:91]
	v_mfma_f32_16x16x32_bf16 v[80:83], v[136:139], v[194:197], v[80:83]
	v_mfma_f32_16x16x32_bf16 v[124:127], v[132:135], v[154:157], v[124:127]
	v_mfma_f32_16x16x32_bf16 v[120:123], v[140:143], v[154:157], v[120:123]
	v_mfma_f32_16x16x32_bf16 v[116:119], v[132:135], v[168:171], v[116:119]
	v_mfma_f32_16x16x32_bf16 v[112:115], v[140:143], v[168:171], v[112:115]
	v_mfma_f32_16x16x32_bf16 v[104:107], v[132:135], v[190:193], v[104:107]
	v_mfma_f32_16x16x32_bf16 v[96:99], v[140:143], v[190:193], v[96:99]
	v_mfma_f32_16x16x32_bf16 v[88:91], v[132:135], v[198:201], v[88:91]
	v_mfma_f32_16x16x32_bf16 v[80:83], v[140:143], v[198:201], v[80:83]
	s_setprio 0
	s_barrier
	s_add_i32 s62, 0, 0x14000
	v_add_u32_e32 v158, s62, v162
	s_add_i32 s12, s61, s34
	ds_read_b128 v[202:205], v158
	ds_read_b128 v[206:209], v158 offset:1024
	ds_read_b128 v[210:213], v158 offset:2048
	ds_read_b128 v[214:217], v158 offset:3072
	v_lshl_add_u64 v[158:159], s[16:17], 0, v[176:177]
	s_mov_b32 m0, s12
	v_lshl_add_u64 v[218:219], s[16:17], 0, v[144:145]
	global_load_lds_dwordx4 v[158:159], off
	s_add_i32 m0, s12, 0x2000
	s_nop 0
	global_load_lds_dwordx4 v[218:219], off
	s_waitcnt vmcnt(10)
	s_barrier
	s_waitcnt lgkmcnt(0)
	s_setprio 1
	s_waitcnt lgkmcnt(0)
	v_mfma_f32_16x16x32_bf16 v[108:111], v[202:205], v[150:153], v[108:111]
	v_mfma_f32_16x16x32_bf16 v[100:103], v[210:213], v[150:153], v[100:103]
	v_mfma_f32_16x16x32_bf16 v[92:95], v[202:205], v[164:167], v[92:95]
	v_mfma_f32_16x16x32_bf16 v[84:87], v[210:213], v[164:167], v[84:87]
	v_mfma_f32_16x16x32_bf16 v[76:79], v[202:205], v[172:175], v[76:79]
	v_mfma_f32_16x16x32_bf16 v[72:75], v[210:213], v[172:175], v[72:75]
	v_mfma_f32_16x16x32_bf16 v[68:71], v[202:205], v[194:197], v[68:71]
	v_mfma_f32_16x16x32_bf16 v[64:67], v[210:213], v[194:197], v[64:67]
	v_mfma_f32_16x16x32_bf16 v[108:111], v[206:209], v[154:157], v[108:111]
	v_mfma_f32_16x16x32_bf16 v[100:103], v[214:217], v[154:157], v[100:103]
	v_mfma_f32_16x16x32_bf16 v[92:95], v[206:209], v[168:171], v[92:95]
	v_mfma_f32_16x16x32_bf16 v[84:87], v[214:217], v[168:171], v[84:87]
	v_mfma_f32_16x16x32_bf16 v[76:79], v[206:209], v[190:193], v[76:79]
	v_mfma_f32_16x16x32_bf16 v[72:75], v[214:217], v[190:193], v[72:75]
	v_mfma_f32_16x16x32_bf16 v[68:71], v[206:209], v[198:201], v[68:71]
	v_mfma_f32_16x16x32_bf16 v[64:67], v[214:217], v[198:201], v[64:67]
	s_setprio 0
	s_mov_b32 m0, s35
	v_lshl_add_u64 v[220:221], s[18:19], 0, v[176:177]
	s_barrier
	ds_read_b128 v[150:153], v163 offset:16384
	ds_read_b128 v[154:157], v163 offset:17408
	ds_read_b128 v[164:167], v163 offset:18432
	ds_read_b128 v[168:171], v163 offset:19456
	ds_read_b128 v[172:175], v163 offset:20480
	ds_read_b128 v[190:193], v163 offset:21504
	ds_read_b128 v[194:197], v163 offset:22528
	ds_read_b128 v[198:201], v163 offset:23552
	global_load_lds_dwordx4 v[220:221], off
	v_lshl_add_u64 v[222:223], s[18:19], 0, v[144:145]
	s_mov_b32 m0, s36
	s_nop 0
	global_load_lds_dwordx4 v[222:223], off
	s_barrier
	s_waitcnt lgkmcnt(0)
	s_setprio 1
	s_waitcnt lgkmcnt(0)
	v_mfma_f32_16x16x32_bf16 v[60:63], v[128:131], v[150:153], v[60:63]
	v_mfma_f32_16x16x32_bf16 v[56:59], v[136:139], v[150:153], v[56:59]
	v_mfma_f32_16x16x32_bf16 v[52:55], v[128:131], v[164:167], v[52:55]
	v_mfma_f32_16x16x32_bf16 v[48:51], v[136:139], v[164:167], v[48:51]
	v_mfma_f32_16x16x32_bf16 v[40:43], v[128:131], v[172:175], v[40:43]
	v_mfma_f32_16x16x32_bf16 v[32:35], v[136:139], v[172:175], v[32:35]
	v_mfma_f32_16x16x32_bf16 v[24:27], v[128:131], v[194:197], v[24:27]
	v_mfma_f32_16x16x32_bf16 v[16:19], v[136:139], v[194:197], v[16:19]
	v_mfma_f32_16x16x32_bf16 v[60:63], v[132:135], v[154:157], v[60:63]
	v_mfma_f32_16x16x32_bf16 v[56:59], v[140:143], v[154:157], v[56:59]
	v_mfma_f32_16x16x32_bf16 v[52:55], v[132:135], v[168:171], v[52:55]
	v_mfma_f32_16x16x32_bf16 v[48:51], v[140:143], v[168:171], v[48:51]
	v_mfma_f32_16x16x32_bf16 v[40:43], v[132:135], v[190:193], v[40:43]
	v_mfma_f32_16x16x32_bf16 v[32:35], v[140:143], v[190:193], v[32:35]
	v_mfma_f32_16x16x32_bf16 v[24:27], v[132:135], v[198:201], v[24:27]
	v_mfma_f32_16x16x32_bf16 v[16:19], v[140:143], v[198:201], v[16:19]
	s_setprio 0
	s_barrier
	s_add_u32 s12, s16, 0xb0000
	s_addc_u32 s13, s17, 0
	s_add_i32 s61, s62, s34
	v_lshl_add_u64 v[128:129], s[12:13], 0, v[176:177]
	s_mov_b32 m0, s61
	s_nop 0
	global_load_lds_dwordx4 v[128:129], off
	v_lshl_add_u64 v[128:129], s[12:13], 0, v[144:145]
	s_add_i32 m0, s61, 0x2000
	s_nop 0
	global_load_lds_dwordx4 v[128:129], off
	s_waitcnt vmcnt(10)
	s_barrier
	s_setprio 1
	v_mfma_f32_16x16x32_bf16 v[44:47], v[202:205], v[150:153], v[44:47]
	v_mfma_f32_16x16x32_bf16 v[36:39], v[210:213], v[150:153], v[36:39]
	v_mfma_f32_16x16x32_bf16 v[28:31], v[202:205], v[164:167], v[28:31]
	v_mfma_f32_16x16x32_bf16 v[20:23], v[210:213], v[164:167], v[20:23]
	v_mfma_f32_16x16x32_bf16 v[12:15], v[202:205], v[172:175], v[12:15]
	v_mfma_f32_16x16x32_bf16 v[8:11], v[210:213], v[172:175], v[8:11]
	v_mfma_f32_16x16x32_bf16 v[4:7], v[202:205], v[194:197], v[4:7]
	v_mfma_f32_16x16x32_bf16 v[0:3], v[210:213], v[194:197], v[0:3]
	v_mfma_f32_16x16x32_bf16 v[44:47], v[206:209], v[154:157], v[44:47]
	v_mfma_f32_16x16x32_bf16 v[36:39], v[214:217], v[154:157], v[36:39]
	v_mfma_f32_16x16x32_bf16 v[28:31], v[206:209], v[168:171], v[28:31]
	v_mfma_f32_16x16x32_bf16 v[20:23], v[214:217], v[168:171], v[20:23]
	v_mfma_f32_16x16x32_bf16 v[12:15], v[206:209], v[190:193], v[12:15]
	v_mfma_f32_16x16x32_bf16 v[8:11], v[214:217], v[190:193], v[8:11]
	v_mfma_f32_16x16x32_bf16 v[4:7], v[206:209], v[198:201], v[4:7]
	v_mfma_f32_16x16x32_bf16 v[0:3], v[214:217], v[198:201], v[0:3]
	s_setprio 0
	s_add_i32 s61, 0, 0x18000
	v_add_u32_e32 v140, s61, v162
	s_barrier
	ds_read_b128 v[128:131], v140
	ds_read_b128 v[132:135], v140 offset:1024
	ds_read_b128 v[136:139], v140 offset:2048
	ds_read_b128 v[140:143], v140 offset:3072
	s_add_u32 s12, s18, 0xb0000
	s_addc_u32 s13, s19, 0
	s_mov_b32 m0, s37
	v_lshl_add_u64 v[202:203], s[12:13], 0, v[176:177]
	ds_read_b128 v[150:153], v163 offset:32768
	ds_read_b128 v[154:157], v163 offset:33792
	ds_read_b128 v[164:167], v163 offset:34816
	ds_read_b128 v[168:171], v163 offset:35840
	ds_read_b128 v[172:175], v163 offset:36864
	ds_read_b128 v[190:193], v163 offset:37888
	ds_read_b128 v[194:197], v163 offset:38912
	ds_read_b128 v[198:201], v163 offset:39936
	global_load_lds_dwordx4 v[202:203], off
	v_lshl_add_u64 v[202:203], s[12:13], 0, v[144:145]
	s_mov_b32 m0, s38
	s_nop 0
	global_load_lds_dwordx4 v[202:203], off
	s_waitcnt lgkmcnt(8)
	s_waitcnt vmcnt(10)
	s_barrier
	s_waitcnt lgkmcnt(0)
	s_setprio 1
	s_waitcnt lgkmcnt(0)
	v_mfma_f32_16x16x32_bf16 v[124:127], v[128:131], v[150:153], v[124:127]
	v_mfma_f32_16x16x32_bf16 v[120:123], v[136:139], v[150:153], v[120:123]
	v_mfma_f32_16x16x32_bf16 v[116:119], v[128:131], v[164:167], v[116:119]
	v_mfma_f32_16x16x32_bf16 v[112:115], v[136:139], v[164:167], v[112:115]
	v_mfma_f32_16x16x32_bf16 v[104:107], v[128:131], v[172:175], v[104:107]
	v_mfma_f32_16x16x32_bf16 v[96:99], v[136:139], v[172:175], v[96:99]
	v_mfma_f32_16x16x32_bf16 v[88:91], v[128:131], v[194:197], v[88:91]
	v_mfma_f32_16x16x32_bf16 v[80:83], v[136:139], v[194:197], v[80:83]
	v_mfma_f32_16x16x32_bf16 v[124:127], v[132:135], v[154:157], v[124:127]
	v_mfma_f32_16x16x32_bf16 v[120:123], v[140:143], v[154:157], v[120:123]
	v_mfma_f32_16x16x32_bf16 v[116:119], v[132:135], v[168:171], v[116:119]
	v_mfma_f32_16x16x32_bf16 v[112:115], v[140:143], v[168:171], v[112:115]
	v_mfma_f32_16x16x32_bf16 v[104:107], v[132:135], v[190:193], v[104:107]
	v_mfma_f32_16x16x32_bf16 v[96:99], v[140:143], v[190:193], v[96:99]
	v_mfma_f32_16x16x32_bf16 v[88:91], v[132:135], v[198:201], v[88:91]
	v_mfma_f32_16x16x32_bf16 v[80:83], v[140:143], v[198:201], v[80:83]
	s_setprio 0
	s_barrier
	s_add_i32 s18, 0, 0x1c000
	s_add_i32 s12, s61, s34
	v_add_u32_e32 v214, s18, v162
	v_lshl_add_u64 v[158:159], v[158:159], 0, s[24:25]
	s_mov_b32 m0, s12
	ds_read_b128 v[202:205], v214
	ds_read_b128 v[206:209], v214 offset:1024
	ds_read_b128 v[210:213], v214 offset:2048
	ds_read_b128 v[214:217], v214 offset:3072
	global_load_lds_dwordx4 v[158:159], off
	v_lshl_add_u64 v[158:159], v[218:219], 0, s[24:25]
	s_add_i32 m0, s12, 0x2000
	s_nop 0
	global_load_lds_dwordx4 v[158:159], off
	s_waitcnt vmcnt(10)
	s_barrier
	s_waitcnt lgkmcnt(0)
	s_setprio 1
	s_waitcnt lgkmcnt(0)
	v_mfma_f32_16x16x32_bf16 v[108:111], v[202:205], v[150:153], v[108:111]
	v_mfma_f32_16x16x32_bf16 v[100:103], v[210:213], v[150:153], v[100:103]
	v_mfma_f32_16x16x32_bf16 v[92:95], v[202:205], v[164:167], v[92:95]
	v_mfma_f32_16x16x32_bf16 v[84:87], v[210:213], v[164:167], v[84:87]
	v_mfma_f32_16x16x32_bf16 v[76:79], v[202:205], v[172:175], v[76:79]
	v_mfma_f32_16x16x32_bf16 v[72:75], v[210:213], v[172:175], v[72:75]
	v_mfma_f32_16x16x32_bf16 v[68:71], v[202:205], v[194:197], v[68:71]
	v_mfma_f32_16x16x32_bf16 v[64:67], v[210:213], v[194:197], v[64:67]
	v_mfma_f32_16x16x32_bf16 v[108:111], v[206:209], v[154:157], v[108:111]
	v_mfma_f32_16x16x32_bf16 v[100:103], v[214:217], v[154:157], v[100:103]
	v_mfma_f32_16x16x32_bf16 v[92:95], v[206:209], v[168:171], v[92:95]
	v_mfma_f32_16x16x32_bf16 v[84:87], v[214:217], v[168:171], v[84:87]
	v_mfma_f32_16x16x32_bf16 v[76:79], v[206:209], v[190:193], v[76:79]
	v_mfma_f32_16x16x32_bf16 v[72:75], v[214:217], v[190:193], v[72:75]
	v_mfma_f32_16x16x32_bf16 v[68:71], v[206:209], v[198:201], v[68:71]
	v_mfma_f32_16x16x32_bf16 v[64:67], v[214:217], v[198:201], v[64:67]
	s_setprio 0
	s_mov_b32 m0, s46
	v_lshl_add_u64 v[158:159], v[220:221], 0, s[24:25]
	s_barrier
	ds_read_b128 v[150:153], v163 offset:49152
	ds_read_b128 v[154:157], v163 offset:50176
	ds_read_b128 v[164:167], v163 offset:51200
	ds_read_b128 v[168:171], v163 offset:52224
	ds_read_b128 v[172:175], v163 offset:53248
	ds_read_b128 v[190:193], v163 offset:54272
	ds_read_b128 v[194:197], v163 offset:55296
	ds_read_b128 v[198:201], v163 offset:56320
	global_load_lds_dwordx4 v[158:159], off
	v_lshl_add_u64 v[158:159], v[222:223], 0, s[24:25]
	s_mov_b32 m0, s47
	s_nop 0
	global_load_lds_dwordx4 v[158:159], off
	s_barrier
	s_waitcnt lgkmcnt(0)
	s_setprio 1
	s_waitcnt lgkmcnt(0)
	v_mfma_f32_16x16x32_bf16 v[60:63], v[128:131], v[150:153], v[60:63]
	v_mfma_f32_16x16x32_bf16 v[56:59], v[136:139], v[150:153], v[56:59]
	v_mfma_f32_16x16x32_bf16 v[52:55], v[128:131], v[164:167], v[52:55]
	v_mfma_f32_16x16x32_bf16 v[48:51], v[136:139], v[164:167], v[48:51]
	v_mfma_f32_16x16x32_bf16 v[40:43], v[128:131], v[172:175], v[40:43]
	v_mfma_f32_16x16x32_bf16 v[32:35], v[136:139], v[172:175], v[32:35]
	v_mfma_f32_16x16x32_bf16 v[24:27], v[128:131], v[194:197], v[24:27]
	v_mfma_f32_16x16x32_bf16 v[16:19], v[136:139], v[194:197], v[16:19]
	v_mfma_f32_16x16x32_bf16 v[60:63], v[132:135], v[154:157], v[60:63]
	v_mfma_f32_16x16x32_bf16 v[56:59], v[140:143], v[154:157], v[56:59]
	v_mfma_f32_16x16x32_bf16 v[52:55], v[132:135], v[168:171], v[52:55]
	v_mfma_f32_16x16x32_bf16 v[48:51], v[140:143], v[168:171], v[48:51]
	v_mfma_f32_16x16x32_bf16 v[40:43], v[132:135], v[190:193], v[40:43]
	v_mfma_f32_16x16x32_bf16 v[32:35], v[140:143], v[190:193], v[32:35]
	v_mfma_f32_16x16x32_bf16 v[24:27], v[132:135], v[198:201], v[24:27]
	v_mfma_f32_16x16x32_bf16 v[16:19], v[140:143], v[198:201], v[16:19]
	s_setprio 0
	s_barrier
	s_add_u32 s12, s16, 0xb0080
	s_addc_u32 s13, s17, 0
	s_add_i32 s16, s18, s34
	v_lshl_add_u64 v[128:129], s[12:13], 0, v[176:177]
	s_mov_b32 m0, s16
	s_nop 0
	global_load_lds_dwordx4 v[128:129], off
	v_lshl_add_u64 v[128:129], s[12:13], 0, v[144:145]
	s_add_i32 m0, s16, 0x2000
	s_nop 0
	global_load_lds_dwordx4 v[128:129], off
	s_waitcnt vmcnt(10)
	s_barrier
	s_setprio 1
	v_mfma_f32_16x16x32_bf16 v[44:47], v[202:205], v[150:153], v[44:47]
	v_mfma_f32_16x16x32_bf16 v[36:39], v[210:213], v[150:153], v[36:39]
	v_mfma_f32_16x16x32_bf16 v[28:31], v[202:205], v[164:167], v[28:31]
	v_mfma_f32_16x16x32_bf16 v[20:23], v[210:213], v[164:167], v[20:23]
	v_mfma_f32_16x16x32_bf16 v[12:15], v[202:205], v[172:175], v[12:15]
	v_mfma_f32_16x16x32_bf16 v[8:11], v[210:213], v[172:175], v[8:11]
	v_mfma_f32_16x16x32_bf16 v[4:7], v[202:205], v[194:197], v[4:7]
	v_mfma_f32_16x16x32_bf16 v[0:3], v[210:213], v[194:197], v[0:3]
	v_mfma_f32_16x16x32_bf16 v[44:47], v[206:209], v[154:157], v[44:47]
	v_mfma_f32_16x16x32_bf16 v[36:39], v[214:217], v[154:157], v[36:39]
	v_mfma_f32_16x16x32_bf16 v[28:31], v[206:209], v[168:171], v[28:31]
	v_mfma_f32_16x16x32_bf16 v[20:23], v[214:217], v[168:171], v[20:23]
	v_mfma_f32_16x16x32_bf16 v[12:15], v[206:209], v[190:193], v[12:15]
	v_mfma_f32_16x16x32_bf16 v[8:11], v[214:217], v[190:193], v[8:11]
	v_mfma_f32_16x16x32_bf16 v[4:7], v[206:209], v[198:201], v[4:7]
	v_mfma_f32_16x16x32_bf16 v[0:3], v[214:217], v[198:201], v[0:3]
	s_setprio 0
	s_add_u32 s58, s58, 0x100
	s_addc_u32 s59, s59, 0
	s_cmp_ge_i32 s60, s42
	s_mov_b64 s[12:13], s[14:15]
	s_mov_b32 s16, s60
	s_barrier
	s_cbranch_scc0 .LBB0_1787
	v_mov_b32_e32 v158, v161
	s_mov_b32 s12, s39
	v_mov_b32_e32 v128, v160
	s_mov_b32 s13, s28
	s_lshl_b32 s14, s41, 8
	s_lshl_b32 s13, s13, 6
	s_add_i32 s13, s13, s14
	v_add_u32_e32 v150, s13, v128
	s_lshl_b32 s13, s40, 8
	s_lshl_b32 s12, s12, 5
	s_add_i32 s12, s12, s13
	v_lshl_add_u32 v152, v158, 2, s12
	s_cmp_gt_i32 s23, 0
	v_ashrrev_i32_e32 v153, 31, v152
	s_mov_b64 s[12:13], -1
	s_cbranch_scc1 .LBB0_1950
	v_lshlrev_b32_e32 v151, 11, v150
	v_lshl_add_u32 v151, v152, 1, v151
	v_lshlrev_b32_e32 v190, 2, v150
	v_xor_b32_e32 v191, 16, v229
	v_xor_b32_e32 v153, 32, v229
	v_lshlrev_b32_e32 v191, 2, v191
	v_lshlrev_b32_e32 v153, 2, v153
	v_mov_b32_e32 v239, v151
	v_lshlrev_b32_e32 v150, 12, v150
	v_lshl_add_u32 v150, v152, 2, v150
	s_and_b64 vcc, exec, s[6:7]
	s_cbranch_vccnz .LresJ_yout
	v_mov_b32_e32 v238, v151
	global_load_dwordx2 v[192:193], v238, s[96:97]
	global_load_dwordx2 v[194:195], v238, s[96:97] offset:32
	global_load_dwordx2 v[196:197], v238, s[96:97] offset:256
	global_load_dwordx2 v[198:199], v238, s[96:97] offset:288
	v_add_u32_e32 v238, 0x8000, v238
	global_load_dwordx2 v[200:201], v238, s[96:97]
	global_load_dwordx2 v[202:203], v238, s[96:97] offset:32
	global_load_dwordx2 v[204:205], v238, s[96:97] offset:256
	global_load_dwordx2 v[206:207], v238, s[96:97] offset:288
	v_add_u32_e32 v238, 0x8000, v238
	global_load_dwordx2 v[208:209], v238, s[96:97]
	global_load_dwordx2 v[210:211], v238, s[96:97] offset:32
	global_load_dwordx2 v[212:213], v238, s[96:97] offset:256
	global_load_dwordx2 v[214:215], v238, s[96:97] offset:288
	v_add_u32_e32 v238, 0x8000, v238
	global_load_dwordx2 v[216:217], v238, s[96:97]
	global_load_dwordx2 v[218:219], v238, s[96:97] offset:32
	global_load_dwordx2 v[220:221], v238, s[96:97] offset:256
	global_load_dwordx2 v[222:223], v238, s[96:97] offset:288
	v_add_u32_e32 v238, 0x28000, v238
	global_load_dwordx2 v[128:129], v238, s[96:97]
	global_load_dwordx2 v[130:131], v238, s[96:97] offset:32
	global_load_dwordx2 v[132:133], v238, s[96:97] offset:256
	global_load_dwordx2 v[134:135], v238, s[96:97] offset:288
	v_add_u32_e32 v238, 0x8000, v238
	global_load_dwordx2 v[136:137], v238, s[96:97]
	global_load_dwordx2 v[138:139], v238, s[96:97] offset:32
	global_load_dwordx2 v[140:141], v238, s[96:97] offset:256
	global_load_dwordx2 v[142:143], v238, s[96:97] offset:288
	v_add_u32_e32 v238, 0x8000, v238
	global_load_dwordx2 v[164:165], v238, s[96:97]
	global_load_dwordx2 v[166:167], v238, s[96:97] offset:32
	global_load_dwordx2 v[168:169], v238, s[96:97] offset:256
	global_load_dwordx2 v[170:171], v238, s[96:97] offset:288
	v_add_u32_e32 v238, 0x8000, v238
	global_load_dwordx2 v[172:173], v238, s[96:97]
	global_load_dwordx2 v[174:175], v238, s[96:97] offset:32
	global_load_dwordx2 v[240:241], v238, s[96:97] offset:256
	global_load_dwordx2 v[242:243], v238, s[96:97] offset:288
	s_waitcnt vmcnt(31)
	v_lshlrev_b32_e32 v252, 16, v192
	v_and_b32_e32 v253, 0xffff0000, v192
	v_lshlrev_b32_e32 v254, 16, v193
	v_and_b32_e32 v255, 0xffff0000, v193
	v_pk_add_f32 v[252:253], v[124:125], v[252:253]
	v_pk_add_f32 v[254:255], v[126:127], v[254:255]
	v_mul_f32_e32 v154, v252, v252
	v_fmac_f32_e32 v154, v253, v253
	v_fmac_f32_e32 v154, v254, v254
	v_fmac_f32_e32 v154, v255, v255
	v_cvt_pk_bf16_f32 v158, v252, v253
	v_cvt_pk_bf16_f32 v159, v254, v255
	global_store_dwordx2 v239, v[158:159], s[96:97]
	s_waitcnt vmcnt(31)
	v_lshlrev_b32_e32 v252, 16, v194
	v_and_b32_e32 v253, 0xffff0000, v194
	v_lshlrev_b32_e32 v254, 16, v195
	v_and_b32_e32 v255, 0xffff0000, v195
	v_pk_add_f32 v[252:253], v[120:121], v[252:253]
	v_pk_add_f32 v[254:255], v[122:123], v[254:255]
	v_fmac_f32_e32 v154, v252, v252
	v_fmac_f32_e32 v154, v253, v253
	v_fmac_f32_e32 v154, v254, v254
	v_fmac_f32_e32 v154, v255, v255
	v_cvt_pk_bf16_f32 v158, v252, v253
	v_cvt_pk_bf16_f32 v159, v254, v255
	global_store_dwordx2 v239, v[158:159], s[96:97] offset:32
	s_waitcnt vmcnt(31)
	v_lshlrev_b32_e32 v252, 16, v196
	v_and_b32_e32 v253, 0xffff0000, v196
	v_lshlrev_b32_e32 v254, 16, v197
	v_and_b32_e32 v255, 0xffff0000, v197
	v_pk_add_f32 v[252:253], v[108:109], v[252:253]
	v_pk_add_f32 v[254:255], v[110:111], v[254:255]
	v_fmac_f32_e32 v154, v252, v252
	v_fmac_f32_e32 v154, v253, v253
	v_fmac_f32_e32 v154, v254, v254
	v_fmac_f32_e32 v154, v255, v255
	v_cvt_pk_bf16_f32 v158, v252, v253
	v_cvt_pk_bf16_f32 v159, v254, v255
	global_store_dwordx2 v239, v[158:159], s[96:97] offset:256
	s_waitcnt vmcnt(31)
	v_lshlrev_b32_e32 v252, 16, v198
	v_and_b32_e32 v253, 0xffff0000, v198
	v_lshlrev_b32_e32 v254, 16, v199
	v_and_b32_e32 v255, 0xffff0000, v199
	v_pk_add_f32 v[252:253], v[100:101], v[252:253]
	v_pk_add_f32 v[254:255], v[102:103], v[254:255]
	v_fmac_f32_e32 v154, v252, v252
	v_fmac_f32_e32 v154, v253, v253
	v_fmac_f32_e32 v154, v254, v254
	v_fmac_f32_e32 v154, v255, v255
	v_cvt_pk_bf16_f32 v158, v252, v253
	v_cvt_pk_bf16_f32 v159, v254, v255
	global_store_dwordx2 v239, v[158:159], s[96:97] offset:288
	v_add_u32_e32 v239, 0x8000, v239
	s_waitcnt vmcnt(31)
	v_lshlrev_b32_e32 v252, 16, v200
	v_and_b32_e32 v253, 0xffff0000, v200
	v_lshlrev_b32_e32 v254, 16, v201
	v_and_b32_e32 v255, 0xffff0000, v201
	v_pk_add_f32 v[252:253], v[116:117], v[252:253]
	v_pk_add_f32 v[254:255], v[118:119], v[254:255]
	v_mul_f32_e32 v155, v252, v252
	v_fmac_f32_e32 v155, v253, v253
	v_fmac_f32_e32 v155, v254, v254
	v_fmac_f32_e32 v155, v255, v255
	v_cvt_pk_bf16_f32 v158, v252, v253
	v_cvt_pk_bf16_f32 v159, v254, v255
	global_store_dwordx2 v239, v[158:159], s[96:97]
	s_waitcnt vmcnt(31)
	v_lshlrev_b32_e32 v252, 16, v202
	v_and_b32_e32 v253, 0xffff0000, v202
	v_lshlrev_b32_e32 v254, 16, v203
	v_and_b32_e32 v255, 0xffff0000, v203
	v_pk_add_f32 v[252:253], v[112:113], v[252:253]
	v_pk_add_f32 v[254:255], v[114:115], v[254:255]
	v_fmac_f32_e32 v155, v252, v252
	v_fmac_f32_e32 v155, v253, v253
	v_fmac_f32_e32 v155, v254, v254
	v_fmac_f32_e32 v155, v255, v255
	v_cvt_pk_bf16_f32 v158, v252, v253
	v_cvt_pk_bf16_f32 v159, v254, v255
	global_store_dwordx2 v239, v[158:159], s[96:97] offset:32
	s_waitcnt vmcnt(31)
	v_lshlrev_b32_e32 v252, 16, v204
	v_and_b32_e32 v253, 0xffff0000, v204
	v_lshlrev_b32_e32 v254, 16, v205
	v_and_b32_e32 v255, 0xffff0000, v205
	v_pk_add_f32 v[252:253], v[92:93], v[252:253]
	v_pk_add_f32 v[254:255], v[94:95], v[254:255]
	v_fmac_f32_e32 v155, v252, v252
	v_fmac_f32_e32 v155, v253, v253
	v_fmac_f32_e32 v155, v254, v254
	v_fmac_f32_e32 v155, v255, v255
	v_cvt_pk_bf16_f32 v158, v252, v253
	v_cvt_pk_bf16_f32 v159, v254, v255
	global_store_dwordx2 v239, v[158:159], s[96:97] offset:256
	s_waitcnt vmcnt(31)
	v_lshlrev_b32_e32 v252, 16, v206
	v_and_b32_e32 v253, 0xffff0000, v206
	v_lshlrev_b32_e32 v254, 16, v207
	v_and_b32_e32 v255, 0xffff0000, v207
	v_pk_add_f32 v[252:253], v[84:85], v[252:253]
	v_pk_add_f32 v[254:255], v[86:87], v[254:255]
	v_fmac_f32_e32 v155, v252, v252
	v_fmac_f32_e32 v155, v253, v253
	v_fmac_f32_e32 v155, v254, v254
	v_fmac_f32_e32 v155, v255, v255
	v_cvt_pk_bf16_f32 v158, v252, v253
	v_cvt_pk_bf16_f32 v159, v254, v255
	global_store_dwordx2 v239, v[158:159], s[96:97] offset:288
	v_add_u32_e32 v239, 0x8000, v239
	s_waitcnt vmcnt(31)
	v_lshlrev_b32_e32 v252, 16, v208
	v_and_b32_e32 v253, 0xffff0000, v208
	v_lshlrev_b32_e32 v254, 16, v209
	v_and_b32_e32 v255, 0xffff0000, v209
	v_pk_add_f32 v[252:253], v[104:105], v[252:253]
	v_pk_add_f32 v[254:255], v[106:107], v[254:255]
	v_mul_f32_e32 v156, v252, v252
	v_fmac_f32_e32 v156, v253, v253
	v_fmac_f32_e32 v156, v254, v254
	v_fmac_f32_e32 v156, v255, v255
	v_cvt_pk_bf16_f32 v158, v252, v253
	v_cvt_pk_bf16_f32 v159, v254, v255
	global_store_dwordx2 v239, v[158:159], s[96:97]
	s_waitcnt vmcnt(31)
	v_lshlrev_b32_e32 v252, 16, v210
	v_and_b32_e32 v253, 0xffff0000, v210
	v_lshlrev_b32_e32 v254, 16, v211
	v_and_b32_e32 v255, 0xffff0000, v211
	v_pk_add_f32 v[252:253], v[96:97], v[252:253]
	v_pk_add_f32 v[254:255], v[98:99], v[254:255]
	v_fmac_f32_e32 v156, v252, v252
	v_fmac_f32_e32 v156, v253, v253
	v_fmac_f32_e32 v156, v254, v254
	v_fmac_f32_e32 v156, v255, v255
	v_cvt_pk_bf16_f32 v158, v252, v253
	v_cvt_pk_bf16_f32 v159, v254, v255
	global_store_dwordx2 v239, v[158:159], s[96:97] offset:32
	s_waitcnt vmcnt(31)
	v_lshlrev_b32_e32 v252, 16, v212
	v_and_b32_e32 v253, 0xffff0000, v212
	v_lshlrev_b32_e32 v254, 16, v213
	v_and_b32_e32 v255, 0xffff0000, v213
	v_pk_add_f32 v[252:253], v[76:77], v[252:253]
	v_pk_add_f32 v[254:255], v[78:79], v[254:255]
	v_fmac_f32_e32 v156, v252, v252
	v_fmac_f32_e32 v156, v253, v253
	v_fmac_f32_e32 v156, v254, v254
	v_fmac_f32_e32 v156, v255, v255
	v_cvt_pk_bf16_f32 v158, v252, v253
	v_cvt_pk_bf16_f32 v159, v254, v255
	global_store_dwordx2 v239, v[158:159], s[96:97] offset:256
	s_waitcnt vmcnt(31)
	v_lshlrev_b32_e32 v252, 16, v214
	v_and_b32_e32 v253, 0xffff0000, v214
	v_lshlrev_b32_e32 v254, 16, v215
	v_and_b32_e32 v255, 0xffff0000, v215
	v_pk_add_f32 v[252:253], v[72:73], v[252:253]
	v_pk_add_f32 v[254:255], v[74:75], v[254:255]
	v_fmac_f32_e32 v156, v252, v252
	v_fmac_f32_e32 v156, v253, v253
	v_fmac_f32_e32 v156, v254, v254
	v_fmac_f32_e32 v156, v255, v255
	v_cvt_pk_bf16_f32 v158, v252, v253
	v_cvt_pk_bf16_f32 v159, v254, v255
	global_store_dwordx2 v239, v[158:159], s[96:97] offset:288
	v_add_u32_e32 v239, 0x8000, v239
	s_waitcnt vmcnt(31)
	v_lshlrev_b32_e32 v252, 16, v216
	v_and_b32_e32 v253, 0xffff0000, v216
	v_lshlrev_b32_e32 v254, 16, v217
	v_and_b32_e32 v255, 0xffff0000, v217
	v_pk_add_f32 v[252:253], v[88:89], v[252:253]
	v_pk_add_f32 v[254:255], v[90:91], v[254:255]
	v_mul_f32_e32 v157, v252, v252
	v_fmac_f32_e32 v157, v253, v253
	v_fmac_f32_e32 v157, v254, v254
	v_fmac_f32_e32 v157, v255, v255
	v_cvt_pk_bf16_f32 v158, v252, v253
	v_cvt_pk_bf16_f32 v159, v254, v255
	global_store_dwordx2 v239, v[158:159], s[96:97]
	s_waitcnt vmcnt(31)
	v_lshlrev_b32_e32 v252, 16, v218
	v_and_b32_e32 v253, 0xffff0000, v218
	v_lshlrev_b32_e32 v254, 16, v219
	v_and_b32_e32 v255, 0xffff0000, v219
	v_pk_add_f32 v[252:253], v[80:81], v[252:253]
	v_pk_add_f32 v[254:255], v[82:83], v[254:255]
	v_fmac_f32_e32 v157, v252, v252
	v_fmac_f32_e32 v157, v253, v253
	v_fmac_f32_e32 v157, v254, v254
	v_fmac_f32_e32 v157, v255, v255
	v_cvt_pk_bf16_f32 v158, v252, v253
	v_cvt_pk_bf16_f32 v159, v254, v255
	global_store_dwordx2 v239, v[158:159], s[96:97] offset:32
	s_waitcnt vmcnt(31)
	v_lshlrev_b32_e32 v252, 16, v220
	v_and_b32_e32 v253, 0xffff0000, v220
	v_lshlrev_b32_e32 v254, 16, v221
	v_and_b32_e32 v255, 0xffff0000, v221
	v_pk_add_f32 v[252:253], v[68:69], v[252:253]
	v_pk_add_f32 v[254:255], v[70:71], v[254:255]
	v_fmac_f32_e32 v157, v252, v252
	v_fmac_f32_e32 v157, v253, v253
	v_fmac_f32_e32 v157, v254, v254
	v_fmac_f32_e32 v157, v255, v255
	v_cvt_pk_bf16_f32 v158, v252, v253
	v_cvt_pk_bf16_f32 v159, v254, v255
	global_store_dwordx2 v239, v[158:159], s[96:97] offset:256
	s_waitcnt vmcnt(31)
	v_lshlrev_b32_e32 v252, 16, v222
	v_and_b32_e32 v253, 0xffff0000, v222
	v_lshlrev_b32_e32 v254, 16, v223
	v_and_b32_e32 v255, 0xffff0000, v223
	v_pk_add_f32 v[252:253], v[64:65], v[252:253]
	v_pk_add_f32 v[254:255], v[66:67], v[254:255]
	v_fmac_f32_e32 v157, v252, v252
	v_fmac_f32_e32 v157, v253, v253
	v_fmac_f32_e32 v157, v254, v254
	v_fmac_f32_e32 v157, v255, v255
	v_cvt_pk_bf16_f32 v158, v252, v253
	v_cvt_pk_bf16_f32 v159, v254, v255
	global_store_dwordx2 v239, v[158:159], s[96:97] offset:288
	v_add_u32_e32 v239, 0x28000, v239
	s_waitcnt vmcnt(31)
	v_lshlrev_b32_e32 v252, 16, v128
	v_and_b32_e32 v253, 0xffff0000, v128
	v_lshlrev_b32_e32 v254, 16, v129
	v_and_b32_e32 v255, 0xffff0000, v129
	v_pk_add_f32 v[252:253], v[60:61], v[252:253]
	v_pk_add_f32 v[254:255], v[62:63], v[254:255]
	v_mul_f32_e32 v244, v252, v252
	v_fmac_f32_e32 v244, v253, v253
	v_fmac_f32_e32 v244, v254, v254
	v_fmac_f32_e32 v244, v255, v255
	v_cvt_pk_bf16_f32 v158, v252, v253
	v_cvt_pk_bf16_f32 v159, v254, v255
	global_store_dwordx2 v239, v[158:159], s[96:97]
	s_waitcnt vmcnt(31)
	v_lshlrev_b32_e32 v252, 16, v130
	v_and_b32_e32 v253, 0xffff0000, v130
	v_lshlrev_b32_e32 v254, 16, v131
	v_and_b32_e32 v255, 0xffff0000, v131
	v_pk_add_f32 v[252:253], v[56:57], v[252:253]
	v_pk_add_f32 v[254:255], v[58:59], v[254:255]
	v_fmac_f32_e32 v244, v252, v252
	v_fmac_f32_e32 v244, v253, v253
	v_fmac_f32_e32 v244, v254, v254
	v_fmac_f32_e32 v244, v255, v255
	v_cvt_pk_bf16_f32 v158, v252, v253
	v_cvt_pk_bf16_f32 v159, v254, v255
	global_store_dwordx2 v239, v[158:159], s[96:97] offset:32
	s_waitcnt vmcnt(31)
	v_lshlrev_b32_e32 v252, 16, v132
	v_and_b32_e32 v253, 0xffff0000, v132
	v_lshlrev_b32_e32 v254, 16, v133
	v_and_b32_e32 v255, 0xffff0000, v133
	v_pk_add_f32 v[252:253], v[44:45], v[252:253]
	v_pk_add_f32 v[254:255], v[46:47], v[254:255]
	v_fmac_f32_e32 v244, v252, v252
	v_fmac_f32_e32 v244, v253, v253
	v_fmac_f32_e32 v244, v254, v254
	v_fmac_f32_e32 v244, v255, v255
	v_cvt_pk_bf16_f32 v158, v252, v253
	v_cvt_pk_bf16_f32 v159, v254, v255
	global_store_dwordx2 v239, v[158:159], s[96:97] offset:256
	s_waitcnt vmcnt(31)
	v_lshlrev_b32_e32 v252, 16, v134
	v_and_b32_e32 v253, 0xffff0000, v134
	v_lshlrev_b32_e32 v254, 16, v135
	v_and_b32_e32 v255, 0xffff0000, v135
	v_pk_add_f32 v[252:253], v[36:37], v[252:253]
	v_pk_add_f32 v[254:255], v[38:39], v[254:255]
	v_fmac_f32_e32 v244, v252, v252
	v_fmac_f32_e32 v244, v253, v253
	v_fmac_f32_e32 v244, v254, v254
	v_fmac_f32_e32 v244, v255, v255
	v_cvt_pk_bf16_f32 v158, v252, v253
	v_cvt_pk_bf16_f32 v159, v254, v255
	global_store_dwordx2 v239, v[158:159], s[96:97] offset:288
	v_add_u32_e32 v239, 0x8000, v239
	s_waitcnt vmcnt(31)
	v_lshlrev_b32_e32 v252, 16, v136
	v_and_b32_e32 v253, 0xffff0000, v136
	v_lshlrev_b32_e32 v254, 16, v137
	v_and_b32_e32 v255, 0xffff0000, v137
	v_pk_add_f32 v[252:253], v[52:53], v[252:253]
	v_pk_add_f32 v[254:255], v[54:55], v[254:255]
	v_mul_f32_e32 v245, v252, v252
	v_fmac_f32_e32 v245, v253, v253
	v_fmac_f32_e32 v245, v254, v254
	v_fmac_f32_e32 v245, v255, v255
	v_cvt_pk_bf16_f32 v158, v252, v253
	v_cvt_pk_bf16_f32 v159, v254, v255
	global_store_dwordx2 v239, v[158:159], s[96:97]
	s_waitcnt vmcnt(31)
	v_lshlrev_b32_e32 v252, 16, v138
	v_and_b32_e32 v253, 0xffff0000, v138
	v_lshlrev_b32_e32 v254, 16, v139
	v_and_b32_e32 v255, 0xffff0000, v139
	v_pk_add_f32 v[252:253], v[48:49], v[252:253]
	v_pk_add_f32 v[254:255], v[50:51], v[254:255]
	v_fmac_f32_e32 v245, v252, v252
	v_fmac_f32_e32 v245, v253, v253
	v_fmac_f32_e32 v245, v254, v254
	v_fmac_f32_e32 v245, v255, v255
	v_cvt_pk_bf16_f32 v158, v252, v253
	v_cvt_pk_bf16_f32 v159, v254, v255
	global_store_dwordx2 v239, v[158:159], s[96:97] offset:32
	s_waitcnt vmcnt(31)
	v_lshlrev_b32_e32 v252, 16, v140
	v_and_b32_e32 v253, 0xffff0000, v140
	v_lshlrev_b32_e32 v254, 16, v141
	v_and_b32_e32 v255, 0xffff0000, v141
	v_pk_add_f32 v[252:253], v[28:29], v[252:253]
	v_pk_add_f32 v[254:255], v[30:31], v[254:255]
	v_fmac_f32_e32 v245, v252, v252
	v_fmac_f32_e32 v245, v253, v253
	v_fmac_f32_e32 v245, v254, v254
	v_fmac_f32_e32 v245, v255, v255
	v_cvt_pk_bf16_f32 v158, v252, v253
	v_cvt_pk_bf16_f32 v159, v254, v255
	global_store_dwordx2 v239, v[158:159], s[96:97] offset:256
	s_waitcnt vmcnt(31)
	v_lshlrev_b32_e32 v252, 16, v142
	v_and_b32_e32 v253, 0xffff0000, v142
	v_lshlrev_b32_e32 v254, 16, v143
	v_and_b32_e32 v255, 0xffff0000, v143
	v_pk_add_f32 v[252:253], v[20:21], v[252:253]
	v_pk_add_f32 v[254:255], v[22:23], v[254:255]
	v_fmac_f32_e32 v245, v252, v252
	v_fmac_f32_e32 v245, v253, v253
	v_fmac_f32_e32 v245, v254, v254
	v_fmac_f32_e32 v245, v255, v255
	v_cvt_pk_bf16_f32 v158, v252, v253
	v_cvt_pk_bf16_f32 v159, v254, v255
	global_store_dwordx2 v239, v[158:159], s[96:97] offset:288
	v_add_u32_e32 v239, 0x8000, v239
	s_waitcnt vmcnt(31)
	v_lshlrev_b32_e32 v252, 16, v164
	v_and_b32_e32 v253, 0xffff0000, v164
	v_lshlrev_b32_e32 v254, 16, v165
	v_and_b32_e32 v255, 0xffff0000, v165
	v_pk_add_f32 v[252:253], v[40:41], v[252:253]
	v_pk_add_f32 v[254:255], v[42:43], v[254:255]
	v_mul_f32_e32 v246, v252, v252
	v_fmac_f32_e32 v246, v253, v253
	v_fmac_f32_e32 v246, v254, v254
	v_fmac_f32_e32 v246, v255, v255
	v_cvt_pk_bf16_f32 v158, v252, v253
	v_cvt_pk_bf16_f32 v159, v254, v255
	global_store_dwordx2 v239, v[158:159], s[96:97]
	s_waitcnt vmcnt(31)
	v_lshlrev_b32_e32 v252, 16, v166
	v_and_b32_e32 v253, 0xffff0000, v166
	v_lshlrev_b32_e32 v254, 16, v167
	v_and_b32_e32 v255, 0xffff0000, v167
	v_pk_add_f32 v[252:253], v[32:33], v[252:253]
	v_pk_add_f32 v[254:255], v[34:35], v[254:255]
	v_fmac_f32_e32 v246, v252, v252
	v_fmac_f32_e32 v246, v253, v253
	v_fmac_f32_e32 v246, v254, v254
	v_fmac_f32_e32 v246, v255, v255
	v_cvt_pk_bf16_f32 v158, v252, v253
	v_cvt_pk_bf16_f32 v159, v254, v255
	global_store_dwordx2 v239, v[158:159], s[96:97] offset:32
	s_waitcnt vmcnt(31)
	v_lshlrev_b32_e32 v252, 16, v168
	v_and_b32_e32 v253, 0xffff0000, v168
	v_lshlrev_b32_e32 v254, 16, v169
	v_and_b32_e32 v255, 0xffff0000, v169
	v_pk_add_f32 v[252:253], v[12:13], v[252:253]
	v_pk_add_f32 v[254:255], v[14:15], v[254:255]
	v_fmac_f32_e32 v246, v252, v252
	v_fmac_f32_e32 v246, v253, v253
	v_fmac_f32_e32 v246, v254, v254
	v_fmac_f32_e32 v246, v255, v255
	v_cvt_pk_bf16_f32 v158, v252, v253
	v_cvt_pk_bf16_f32 v159, v254, v255
	global_store_dwordx2 v239, v[158:159], s[96:97] offset:256
	s_waitcnt vmcnt(31)
	v_lshlrev_b32_e32 v252, 16, v170
	v_and_b32_e32 v253, 0xffff0000, v170
	v_lshlrev_b32_e32 v254, 16, v171
	v_and_b32_e32 v255, 0xffff0000, v171
	v_pk_add_f32 v[252:253], v[8:9], v[252:253]
	v_pk_add_f32 v[254:255], v[10:11], v[254:255]
	v_fmac_f32_e32 v246, v252, v252
	v_fmac_f32_e32 v246, v253, v253
	v_fmac_f32_e32 v246, v254, v254
	v_fmac_f32_e32 v246, v255, v255
	v_cvt_pk_bf16_f32 v158, v252, v253
	v_cvt_pk_bf16_f32 v159, v254, v255
	global_store_dwordx2 v239, v[158:159], s[96:97] offset:288
	v_add_u32_e32 v239, 0x8000, v239
	s_waitcnt vmcnt(31)
	v_lshlrev_b32_e32 v252, 16, v172
	v_and_b32_e32 v253, 0xffff0000, v172
	v_lshlrev_b32_e32 v254, 16, v173
	v_and_b32_e32 v255, 0xffff0000, v173
	v_pk_add_f32 v[252:253], v[24:25], v[252:253]
	v_pk_add_f32 v[254:255], v[26:27], v[254:255]
	v_mul_f32_e32 v247, v252, v252
	v_fmac_f32_e32 v247, v253, v253
	v_fmac_f32_e32 v247, v254, v254
	v_fmac_f32_e32 v247, v255, v255
	v_cvt_pk_bf16_f32 v158, v252, v253
	v_cvt_pk_bf16_f32 v159, v254, v255
	global_store_dwordx2 v239, v[158:159], s[96:97]
	s_waitcnt vmcnt(31)
	v_lshlrev_b32_e32 v252, 16, v174
	v_and_b32_e32 v253, 0xffff0000, v174
	v_lshlrev_b32_e32 v254, 16, v175
	v_and_b32_e32 v255, 0xffff0000, v175
	v_pk_add_f32 v[252:253], v[16:17], v[252:253]
	v_pk_add_f32 v[254:255], v[18:19], v[254:255]
	v_fmac_f32_e32 v247, v252, v252
	v_fmac_f32_e32 v247, v253, v253
	v_fmac_f32_e32 v247, v254, v254
	v_fmac_f32_e32 v247, v255, v255
	v_cvt_pk_bf16_f32 v158, v252, v253
	v_cvt_pk_bf16_f32 v159, v254, v255
	global_store_dwordx2 v239, v[158:159], s[96:97] offset:32
	s_waitcnt vmcnt(31)
	v_lshlrev_b32_e32 v252, 16, v240
	v_and_b32_e32 v253, 0xffff0000, v240
	v_lshlrev_b32_e32 v254, 16, v241
	v_and_b32_e32 v255, 0xffff0000, v241
	v_pk_add_f32 v[252:253], v[4:5], v[252:253]
	v_pk_add_f32 v[254:255], v[6:7], v[254:255]
	v_fmac_f32_e32 v247, v252, v252
	v_fmac_f32_e32 v247, v253, v253
	v_fmac_f32_e32 v247, v254, v254
	v_fmac_f32_e32 v247, v255, v255
	v_cvt_pk_bf16_f32 v158, v252, v253
	v_cvt_pk_bf16_f32 v159, v254, v255
	global_store_dwordx2 v239, v[158:159], s[96:97] offset:256
	s_waitcnt vmcnt(31)
	v_lshlrev_b32_e32 v252, 16, v242
	v_and_b32_e32 v253, 0xffff0000, v242
	v_lshlrev_b32_e32 v254, 16, v243
	v_and_b32_e32 v255, 0xffff0000, v243
	v_pk_add_f32 v[252:253], v[0:1], v[252:253]
	v_pk_add_f32 v[254:255], v[2:3], v[254:255]
	v_fmac_f32_e32 v247, v252, v252
	v_fmac_f32_e32 v247, v253, v253
	v_fmac_f32_e32 v247, v254, v254
	v_fmac_f32_e32 v247, v255, v255
	v_cvt_pk_bf16_f32 v158, v252, v253
	v_cvt_pk_bf16_f32 v159, v254, v255
	global_store_dwordx2 v239, v[158:159], s[96:97] offset:288
	s_branch .LresJ_red
